# speedup vs baseline: 1.0080x; 1.0080x over previous
.LBB0_348:
	s_cmpk_gt_i32 s16, 0xff
	s_mov_b64 s[4:5], -1
	s_cbranch_scc1 .LBB0_342
	s_ashr_i32 s4, s16, 31
	s_lshr_b32 s4, s4, 26
	s_add_i32 s4, s16, s4
	s_andn2_b32 s4, s4, 63
	s_sub_i32 s16, s16, s4
	s_ashr_i32 s5, s16, 3
	s_lshl_b32 s16, s16, 3
	s_and_b32 s16, s16, 56
	s_or_b32 s4, s4, s16
	s_mul_i32 s16, s5, 0x56000
	v_mov_b32_e32 v1, v170
	s_barrier
	s_or_b32 s4, s4, s18
	s_ashr_i32 s17, s16, 31
	s_lshl_b32 s4, s4, 8
	v_lshlrev_b32_e32 v145, 4, v1
	s_lshl_b64 s[16:17], s[16:17], 1
	v_add_u32_e32 v29, 0x1000, v145
	v_add_u32_e32 v30, 0x2000, v145
	v_add_u32_e32 v32, 0x3000, v145
	s_add_u32 s18, s20, s16
	v_and_b32_e32 v26, 32, v1
	v_bfe_u32 v27, v1, 2, 4
	v_ashrrev_i32_e32 v13, 2, v1
	v_ashrrev_i32_e32 v15, 6, v29
	v_ashrrev_i32_e32 v10, 6, v30
	v_ashrrev_i32_e32 v16, 6, v32
	s_addc_u32 s19, s21, s17
	v_lshrrev_b32_e32 v14, 2, v1
	v_bitop3_b32 v2, v145, v26, 48 bitop3:0x6c
	v_or_b32_e32 v12, s4, v27
	v_mov_b32_e32 v3, v0
	v_and_b32_e32 v6, -16, v13
	v_and_b32_e32 v8, -16, v15
	v_and_b32_e32 v31, -16, v10
	v_and_b32_e32 v33, -16, v16
	v_lshl_add_u64 v[4:5], s[38:39], 0, v[2:3]
	v_add_u32_e32 v6, v12, v6
	v_add_u32_e32 v8, v8, v12
	v_add_u32_e32 v10, v31, v12
	v_add_u32_e32 v12, v33, v12
	v_lshl_add_u64 v[2:3], s[18:19], 0, v[2:3]
	v_bfi_b32 v34, 15, v14, v13
	v_bfi_b32 v35, -16, v15, v14
	v_mad_i64_i32 v[6:7], s[26:27], v6, s3, v[4:5]
	v_mad_i64_i32 v[8:9], s[26:27], v8, s3, v[4:5]
	v_mad_i64_i32 v[10:11], s[26:27], v10, s3, v[4:5]
	v_mad_i64_i32 v[4:5], s[26:27], v12, s3, v[4:5]
	v_mad_i64_i32 v[12:13], s[18:19], v34, s3, v[2:3]
	v_mad_i64_i32 v[2:3], s[18:19], v35, s3, v[2:3]
	v_readfirstlane_b32 s18, v145
	s_waitcnt vmcnt(0)
	s_mov_b32 m0, s18
	v_readfirstlane_b32 s18, v29
	s_mov_b32 m0, s18
	v_readfirstlane_b32 s18, v30
	v_add_u32_e32 v36, 0x4000, v145
	s_mov_b32 m0, s18
	v_readfirstlane_b32 s18, v32
	v_add_u32_e32 v37, 0x5000, v145
	s_mov_b32 m0, s18
	v_readfirstlane_b32 s18, v36
	v_add_u32_e32 v38, 0x6000, v145
	s_mov_b32 m0, s18
	v_readfirstlane_b32 s18, v37
	v_and_b32_e32 v142, 15, v1
	v_bfe_u32 v143, v1, 4, 2
	v_lshlrev_b32_e32 v17, 6, v1
	v_lshlrev_b32_e32 v14, 2, v1
	v_add_u32_e32 v39, 0x7000, v145
	s_mov_b32 m0, s18
	v_readfirstlane_b32 s18, v38
	v_lshlrev_b32_e32 v16, 4, v143
	v_and_b32_e32 v18, 0x3c0, v17
	v_lshlrev_b32_e32 v19, 6, v142
	v_and_b32_e32 v20, 32, v14
	v_lshl_add_u64 v[14:15], v[6:7], 0, 64
	v_add_u32_e32 v40, 0x8000, v145
	s_mov_b32 m0, s18
	v_readfirstlane_b32 s18, v39
	v_add_u32_e32 v41, 0x9000, v145
	v_and_b32_e32 v147, 0xfffff000, v17
	v_bitop3_b32 v149, v16, v20, v18 bitop3:0x36
	v_bitop3_b32 v144, v16, v20, v19 bitop3:0x36
	v_lshl_add_u64 v[16:17], v[8:9], 0, 64
	s_mov_b32 m0, s18
	v_readfirstlane_b32 s18, v40
	v_add_u32_e32 v42, 0xa000, v145
	v_lshl_add_u64 v[18:19], v[10:11], 0, 64
	s_mov_b32 m0, s18
	v_readfirstlane_b32 s18, v41
	v_add_u32_e32 v43, 0xb000, v145
	v_lshl_add_u64 v[20:21], v[4:5], 0, 64
	s_mov_b32 m0, s18
	v_readfirstlane_b32 s18, v42
	v_lshl_add_u64 v[22:23], v[12:13], 0, 64
	s_mov_b32 m0, s18
	v_readfirstlane_b32 s18, v43
	v_lshl_add_u64 v[24:25], v[2:3], 0, 64
	s_mov_b32 m0, s18
	v_mov_b64_e32 v[2:3], s[16:17]
	v_and_b32_e32 v28, 48, v145
	v_mad_i64_i32 v[4:5], s[16:17], v35, s3, v[2:3]
	v_mad_i64_i32 v[2:3], s[16:17], v34, s3, v[2:3]
	v_bitop3_b32 v2, v2, v28, v26 bitop3:0xf6
	v_lshl_add_u64 v[132:133], s[12:13], 0, v[2:3]
	v_add_u32_e32 v2, s4, v33
	v_or_b32_e32 v2, v2, v27
	v_mad_i64_i32 v[2:3], s[16:17], v2, s3, 0
	v_bitop3_b32 v2, v2, v28, v26 bitop3:0xf6
	v_lshl_add_u64 v[134:135], s[14:15], 0, v[2:3]
	v_add_u32_e32 v2, s4, v31
	v_or_b32_e32 v2, v2, v27
	v_mad_i64_i32 v[2:3], s[16:17], v2, s3, 0
	v_bitop3_b32 v2, v2, v28, v26 bitop3:0xf6
	v_lshl_add_u64 v[136:137], s[14:15], 0, v[2:3]
	v_add_u32_e32 v2, s4, v35
	v_mad_i64_i32 v[2:3], s[16:17], v2, s3, 0
	v_bitop3_b32 v2, v2, v28, v26 bitop3:0xf6
	v_lshl_add_u64 v[138:139], s[14:15], 0, v[2:3]
	v_add_u32_e32 v2, s4, v34
	v_mad_i64_i32 v[2:3], s[16:17], v2, s3, 0
	v_bitop3_b32 v2, v2, v28, v26 bitop3:0xf6
	v_bitop3_b32 v4, v4, v28, v26 bitop3:0xf6
	v_lshl_add_u64 v[140:141], s[14:15], 0, v[2:3]
	v_mov_b32_e32 v2, 0
	v_lshl_add_u64 v[130:131], s[12:13], 0, v[4:5]
	s_mov_b32 s18, 0
	s_mov_b64 s[16:17], 0
	v_mov_b32_e32 v3, v2
	v_mov_b32_e32 v4, v2
	v_mov_b32_e32 v5, v2
	v_mov_b32_e32 v6, v2
	v_mov_b32_e32 v7, v2
	v_mov_b32_e32 v8, v2
	v_mov_b32_e32 v9, v2
	v_mov_b32_e32 v10, v2
	v_mov_b32_e32 v11, v2
	v_mov_b32_e32 v12, v2
	v_mov_b32_e32 v13, v2
	v_mov_b32_e32 v14, v2
	v_mov_b32_e32 v15, v2
	v_mov_b32_e32 v16, v2
	v_mov_b32_e32 v17, v2
	v_mov_b32_e32 v18, v2
	v_mov_b32_e32 v19, v2
	v_mov_b32_e32 v20, v2
	v_mov_b32_e32 v21, v2
	v_mov_b32_e32 v26, v2
	v_mov_b32_e32 v27, v2
	v_mov_b32_e32 v28, v2
	v_mov_b32_e32 v29, v2
	v_mov_b32_e32 v38, v2
	v_mov_b32_e32 v39, v2
	v_mov_b32_e32 v40, v2
	v_mov_b32_e32 v41, v2
	v_mov_b32_e32 v54, v2
	v_mov_b32_e32 v55, v2
	v_mov_b32_e32 v56, v2
	v_mov_b32_e32 v57, v2
	v_mov_b32_e32 v22, v2
	v_mov_b32_e32 v23, v2
	v_mov_b32_e32 v24, v2
	v_mov_b32_e32 v25, v2
	v_mov_b32_e32 v30, v2
	v_mov_b32_e32 v31, v2
	v_mov_b32_e32 v32, v2
	v_mov_b32_e32 v33, v2
	v_mov_b32_e32 v34, v2
	v_mov_b32_e32 v35, v2
	v_mov_b32_e32 v36, v2
	v_mov_b32_e32 v37, v2
	v_mov_b32_e32 v42, v2
	v_mov_b32_e32 v43, v2
	v_mov_b32_e32 v44, v2
	v_mov_b32_e32 v45, v2
	v_mov_b32_e32 v46, v2
	v_mov_b32_e32 v47, v2
	v_mov_b32_e32 v48, v2
	v_mov_b32_e32 v49, v2
	v_mov_b32_e32 v58, v2
	v_mov_b32_e32 v59, v2
	v_mov_b32_e32 v60, v2
	v_mov_b32_e32 v61, v2
	v_mov_b32_e32 v70, v2
	v_mov_b32_e32 v71, v2
	v_mov_b32_e32 v72, v2
	v_mov_b32_e32 v73, v2
	v_mov_b32_e32 v86, v2
	v_mov_b32_e32 v87, v2
	v_mov_b32_e32 v88, v2
	v_mov_b32_e32 v89, v2
	v_mov_b32_e32 v50, v2
	v_mov_b32_e32 v51, v2
	v_mov_b32_e32 v52, v2
	v_mov_b32_e32 v53, v2
	v_mov_b32_e32 v62, v2
	v_mov_b32_e32 v63, v2
	v_mov_b32_e32 v64, v2
	v_mov_b32_e32 v65, v2
	v_mov_b32_e32 v66, v2
	v_mov_b32_e32 v67, v2
	v_mov_b32_e32 v68, v2
	v_mov_b32_e32 v69, v2
	v_mov_b32_e32 v74, v2
	v_mov_b32_e32 v75, v2
	v_mov_b32_e32 v76, v2
	v_mov_b32_e32 v77, v2
	v_mov_b32_e32 v78, v2
	v_mov_b32_e32 v79, v2
	v_mov_b32_e32 v80, v2
	v_mov_b32_e32 v81, v2
	v_mov_b32_e32 v90, v2
	v_mov_b32_e32 v91, v2
	v_mov_b32_e32 v92, v2
	v_mov_b32_e32 v93, v2
	v_mov_b32_e32 v102, v2
	v_mov_b32_e32 v103, v2
	v_mov_b32_e32 v104, v2
	v_mov_b32_e32 v105, v2
	v_mov_b32_e32 v114, v2
	v_mov_b32_e32 v115, v2
	v_mov_b32_e32 v116, v2
	v_mov_b32_e32 v117, v2
	v_mov_b32_e32 v82, v2
	v_mov_b32_e32 v83, v2
	v_mov_b32_e32 v84, v2
	v_mov_b32_e32 v85, v2
	v_mov_b32_e32 v94, v2
	v_mov_b32_e32 v95, v2
	v_mov_b32_e32 v96, v2
	v_mov_b32_e32 v97, v2
	v_mov_b32_e32 v98, v2
	v_mov_b32_e32 v99, v2
	v_mov_b32_e32 v100, v2
	v_mov_b32_e32 v101, v2
	v_mov_b32_e32 v106, v2
	v_mov_b32_e32 v107, v2
	v_mov_b32_e32 v108, v2
	v_mov_b32_e32 v109, v2
	v_mov_b32_e32 v110, v2
	v_mov_b32_e32 v111, v2
	v_mov_b32_e32 v112, v2
	v_mov_b32_e32 v113, v2
	v_mov_b32_e32 v118, v2
	v_mov_b32_e32 v119, v2
	v_mov_b32_e32 v120, v2
	v_mov_b32_e32 v121, v2
	v_mov_b32_e32 v122, v2
	v_mov_b32_e32 v123, v2
	v_mov_b32_e32 v124, v2
	v_mov_b32_e32 v125, v2
	v_mov_b32_e32 v126, v2
	v_mov_b32_e32 v127, v2
	v_mov_b32_e32 v128, v2
	v_mov_b32_e32 v129, v2
	v_and_b32_e32 v154, 63, v170
	v_lshrrev_b32_e32 v155, 3, v154
	v_and_b32_e32 v156, 7, v154
	v_xor_b32_e32 v156, v156, v155
	v_lshrrev_b32_e32 v157, 6, v170
	v_lshl_add_u32 v158, v157, 6, v155
	v_add_u32_e32 v158, s4, v158
	v_mul_u32_u24_e32 v224, 0x1580, v158
	v_lshl_add_u32 v224, v156, 4, v224
	v_lshl_add_u32 v158, v157, 5, v155
	v_mul_u32_u24_e32 v225, 0x1580, v158
	v_lshl_add_u32 v225, v156, 4, v225
	v_and_b32_e32 v155, 15, v154
	v_lshrrev_b32_e32 v156, 4, v154
	v_and_b32_e32 v158, 7, v155
	v_xor_b32_e32 v156, v156, v158
	v_lshlrev_b32_e32 v156, 4, v156
	v_lshl_add_u32 v229, v155, 7, v156
	v_lshl_add_u32 v227, v157, 13, v229
	v_xor_b32_e32 v228, 64, v227
	v_add_u32_e32 v229, 0xc000, v229
	v_xor_b32_e32 v230, 64, v229
	s_mov_b32 s18, s38
	s_mov_b32 s19, s39
	s_mul_i32 s32, s5, 0xac000
	s_add_u32 s16, s20, s32
	s_addc_u32 s17, s21, 0
	s_mov_b32 s25, 0
	v_readfirstlane_b32 s32, v145
	s_lshl_b32 m0, s32, 3
	v_mov_b32_e32 v226, v224
	global_load_lds_dwordx4 v226, s[18:19]
	s_add_u32 m0, m0, 0x400
	v_add_u32_e32 v226, 0xac00, v224
	global_load_lds_dwordx4 v226, s[18:19]
	s_add_u32 m0, m0, 0x400
	v_add_u32_e32 v226, 0x15800, v224
	global_load_lds_dwordx4 v226, s[18:19]
	s_add_u32 m0, m0, 0x400
	v_add_u32_e32 v226, 0x20400, v224
	global_load_lds_dwordx4 v226, s[18:19]
	s_add_u32 m0, m0, 0x400
	v_add_u32_e32 v226, 0x2b000, v224
	global_load_lds_dwordx4 v226, s[18:19]
	s_add_u32 m0, m0, 0x400
	v_add_u32_e32 v226, 0x35c00, v224
	global_load_lds_dwordx4 v226, s[18:19]
	s_add_u32 m0, m0, 0x400
	v_add_u32_e32 v226, 0x40800, v224
	global_load_lds_dwordx4 v226, s[18:19]
	s_add_u32 m0, m0, 0x400
	v_add_u32_e32 v226, 0x4b400, v224
	global_load_lds_dwordx4 v226, s[18:19]
	v_readfirstlane_b32 s32, v145
	s_lshl_b32 s32, s32, 2
	s_add_u32 m0, s32, 0xc000
	v_mov_b32_e32 v226, v225
	global_load_lds_dwordx4 v226, s[16:17]
	s_add_u32 m0, m0, 0x400
	v_add_u32_e32 v226, 0xac00, v225
	global_load_lds_dwordx4 v226, s[16:17]
	s_add_u32 m0, m0, 0x400
	v_add_u32_e32 v226, 0x15800, v225
	global_load_lds_dwordx4 v226, s[16:17]
	s_add_u32 m0, m0, 0x400
	v_add_u32_e32 v226, 0x20400, v225
	global_load_lds_dwordx4 v226, s[16:17]
.Lbk64_350:
	s_waitcnt vmcnt(0)
	s_barrier
	ds_read_b128 v[192:195], v227
	ds_read_b128 v[196:199], v228
	ds_read_b128 v[200:203], v227 offset:2048
	ds_read_b128 v[204:207], v228 offset:2048
	ds_read_b128 v[208:211], v227 offset:4096
	ds_read_b128 v[212:215], v228 offset:4096
	ds_read_b128 v[216:219], v227 offset:6144
	ds_read_b128 v[220:223], v228 offset:6144
	s_add_u32 s18, s18, 0x80
	s_addc_u32 s19, s19, 0
	s_add_u32 s16, s16, 0x80
	s_addc_u32 s17, s17, 0
	s_waitcnt lgkmcnt(0)
	s_barrier
	ds_read_b128 v[154:157], v229 offset:0
	ds_read_b128 v[158:161], v230 offset:0
	ds_read_b128 v[162:165], v229 offset:2048
	ds_read_b128 v[166:169], v230 offset:2048
	s_waitcnt lgkmcnt(2)
	v_mfma_f32_16x16x32_bf16 v[126:129], v[192:195], v[154:157], v[126:129]
	v_mfma_f32_16x16x32_bf16 v[114:117], v[200:203], v[154:157], v[114:117]
	v_mfma_f32_16x16x32_bf16 v[86:89], v[208:211], v[154:157], v[86:89]
	v_mfma_f32_16x16x32_bf16 v[54:57], v[216:219], v[154:157], v[54:57]
	v_readfirstlane_b32 s32, v145
	s_lshl_b32 m0, s32, 3
	v_mov_b32_e32 v226, v224
	global_load_lds_dwordx4 v226, s[18:19]
	v_mfma_f32_16x16x32_bf16 v[126:129], v[196:199], v[158:161], v[126:129]
	v_mfma_f32_16x16x32_bf16 v[114:117], v[204:207], v[158:161], v[114:117]
	v_mfma_f32_16x16x32_bf16 v[86:89], v[212:215], v[158:161], v[86:89]
	v_mfma_f32_16x16x32_bf16 v[54:57], v[220:223], v[158:161], v[54:57]
	s_add_u32 m0, m0, 0x400
	v_add_u32_e32 v226, 0xac00, v224
	global_load_lds_dwordx4 v226, s[18:19]
	ds_read_b128 v[154:157], v229 offset:4096
	ds_read_b128 v[158:161], v230 offset:4096
	s_waitcnt lgkmcnt(2)
	v_mfma_f32_16x16x32_bf16 v[122:125], v[192:195], v[162:165], v[122:125]
	v_mfma_f32_16x16x32_bf16 v[102:105], v[200:203], v[162:165], v[102:105]
	v_mfma_f32_16x16x32_bf16 v[70:73], v[208:211], v[162:165], v[70:73]
	v_mfma_f32_16x16x32_bf16 v[38:41], v[216:219], v[162:165], v[38:41]
	s_add_u32 m0, m0, 0x400
	v_add_u32_e32 v226, 0x15800, v224
	global_load_lds_dwordx4 v226, s[18:19]
	v_mfma_f32_16x16x32_bf16 v[122:125], v[196:199], v[166:169], v[122:125]
	v_mfma_f32_16x16x32_bf16 v[102:105], v[204:207], v[166:169], v[102:105]
	v_mfma_f32_16x16x32_bf16 v[70:73], v[212:215], v[166:169], v[70:73]
	v_mfma_f32_16x16x32_bf16 v[38:41], v[220:223], v[166:169], v[38:41]
	s_add_u32 m0, m0, 0x400
	v_add_u32_e32 v226, 0x20400, v224
	global_load_lds_dwordx4 v226, s[18:19]
	ds_read_b128 v[162:165], v229 offset:6144
	ds_read_b128 v[166:169], v230 offset:6144
	s_waitcnt lgkmcnt(2)
	v_mfma_f32_16x16x32_bf16 v[118:121], v[192:195], v[154:157], v[118:121]
	v_mfma_f32_16x16x32_bf16 v[90:93], v[200:203], v[154:157], v[90:93]
	v_mfma_f32_16x16x32_bf16 v[58:61], v[208:211], v[154:157], v[58:61]
	v_mfma_f32_16x16x32_bf16 v[26:29], v[216:219], v[154:157], v[26:29]
	s_add_u32 m0, m0, 0x400
	v_add_u32_e32 v226, 0x2b000, v224
	global_load_lds_dwordx4 v226, s[18:19]
	v_mfma_f32_16x16x32_bf16 v[118:121], v[196:199], v[158:161], v[118:121]
	v_mfma_f32_16x16x32_bf16 v[90:93], v[204:207], v[158:161], v[90:93]
	v_mfma_f32_16x16x32_bf16 v[58:61], v[212:215], v[158:161], v[58:61]
	v_mfma_f32_16x16x32_bf16 v[26:29], v[220:223], v[158:161], v[26:29]
	s_add_u32 m0, m0, 0x400
	v_add_u32_e32 v226, 0x35c00, v224
	global_load_lds_dwordx4 v226, s[18:19]
	ds_read_b128 v[154:157], v229 offset:8192
	ds_read_b128 v[158:161], v230 offset:8192
	s_waitcnt lgkmcnt(2)
	v_mfma_f32_16x16x32_bf16 v[110:113], v[192:195], v[162:165], v[110:113]
	v_mfma_f32_16x16x32_bf16 v[78:81], v[200:203], v[162:165], v[78:81]
	v_mfma_f32_16x16x32_bf16 v[46:49], v[208:211], v[162:165], v[46:49]
	v_mfma_f32_16x16x32_bf16 v[18:21], v[216:219], v[162:165], v[18:21]
	s_add_u32 m0, m0, 0x400
	v_add_u32_e32 v226, 0x40800, v224
	global_load_lds_dwordx4 v226, s[18:19]
	v_mfma_f32_16x16x32_bf16 v[110:113], v[196:199], v[166:169], v[110:113]
	v_mfma_f32_16x16x32_bf16 v[78:81], v[204:207], v[166:169], v[78:81]
	v_mfma_f32_16x16x32_bf16 v[46:49], v[212:215], v[166:169], v[46:49]
	v_mfma_f32_16x16x32_bf16 v[18:21], v[220:223], v[166:169], v[18:21]
	s_add_u32 m0, m0, 0x400
	v_add_u32_e32 v226, 0x4b400, v224
	global_load_lds_dwordx4 v226, s[18:19]
	ds_read_b128 v[162:165], v229 offset:10240
	ds_read_b128 v[166:169], v230 offset:10240
	s_waitcnt lgkmcnt(2)
	v_mfma_f32_16x16x32_bf16 v[106:109], v[192:195], v[154:157], v[106:109]
	v_mfma_f32_16x16x32_bf16 v[74:77], v[200:203], v[154:157], v[74:77]
	v_mfma_f32_16x16x32_bf16 v[42:45], v[208:211], v[154:157], v[42:45]
	v_mfma_f32_16x16x32_bf16 v[14:17], v[216:219], v[154:157], v[14:17]
	s_add_u32 m0, s25, 44
	s_and_b32 m0, m0, 1
	s_lshl_b32 m0, m0, 14
	s_add_u32 m0, m0, 0x8000
	v_readfirstlane_b32 s32, v145
	s_lshl_b32 s32, s32, 2
	s_add_u32 m0, m0, s32
	v_mov_b32_e32 v226, v225
	global_load_lds_dwordx4 v226, s[16:17]
	v_mfma_f32_16x16x32_bf16 v[106:109], v[196:199], v[158:161], v[106:109]
	v_mfma_f32_16x16x32_bf16 v[74:77], v[204:207], v[158:161], v[74:77]
	v_mfma_f32_16x16x32_bf16 v[42:45], v[212:215], v[158:161], v[42:45]
	v_mfma_f32_16x16x32_bf16 v[14:17], v[220:223], v[158:161], v[14:17]
	s_add_u32 m0, m0, 0x400
	v_add_u32_e32 v226, 0xac00, v225
	global_load_lds_dwordx4 v226, s[16:17]
	ds_read_b128 v[154:157], v229 offset:12288
	ds_read_b128 v[158:161], v230 offset:12288
	s_waitcnt lgkmcnt(2)
	v_mfma_f32_16x16x32_bf16 v[98:101], v[192:195], v[162:165], v[98:101]
	v_mfma_f32_16x16x32_bf16 v[66:69], v[200:203], v[162:165], v[66:69]
	v_mfma_f32_16x16x32_bf16 v[34:37], v[208:211], v[162:165], v[34:37]
	v_mfma_f32_16x16x32_bf16 v[10:13], v[216:219], v[162:165], v[10:13]
	s_add_u32 m0, m0, 0x400
	v_add_u32_e32 v226, 0x15800, v225
	global_load_lds_dwordx4 v226, s[16:17]
	v_mfma_f32_16x16x32_bf16 v[98:101], v[196:199], v[166:169], v[98:101]
	v_mfma_f32_16x16x32_bf16 v[66:69], v[204:207], v[166:169], v[66:69]
	v_mfma_f32_16x16x32_bf16 v[34:37], v[212:215], v[166:169], v[34:37]
	v_mfma_f32_16x16x32_bf16 v[10:13], v[220:223], v[166:169], v[10:13]
	s_add_u32 m0, m0, 0x400
	v_add_u32_e32 v226, 0x20400, v225
	global_load_lds_dwordx4 v226, s[16:17]
	ds_read_b128 v[162:165], v229 offset:14336
	ds_read_b128 v[166:169], v230 offset:14336
	s_waitcnt lgkmcnt(2)
	v_mfma_f32_16x16x32_bf16 v[94:97], v[192:195], v[154:157], v[94:97]
	v_mfma_f32_16x16x32_bf16 v[62:65], v[200:203], v[154:157], v[62:65]
	v_mfma_f32_16x16x32_bf16 v[30:33], v[208:211], v[154:157], v[30:33]
	v_mfma_f32_16x16x32_bf16 v[6:9], v[216:219], v[154:157], v[6:9]
	v_mfma_f32_16x16x32_bf16 v[94:97], v[196:199], v[158:161], v[94:97]
	v_mfma_f32_16x16x32_bf16 v[62:65], v[204:207], v[158:161], v[62:65]
	v_mfma_f32_16x16x32_bf16 v[30:33], v[212:215], v[158:161], v[30:33]
	v_mfma_f32_16x16x32_bf16 v[6:9], v[220:223], v[158:161], v[6:9]
	s_waitcnt lgkmcnt(0)
	v_mfma_f32_16x16x32_bf16 v[82:85], v[192:195], v[162:165], v[82:85]
	v_mfma_f32_16x16x32_bf16 v[50:53], v[200:203], v[162:165], v[50:53]
	v_mfma_f32_16x16x32_bf16 v[22:25], v[208:211], v[162:165], v[22:25]
	v_mfma_f32_16x16x32_bf16 v[2:5], v[216:219], v[162:165], v[2:5]
	v_mfma_f32_16x16x32_bf16 v[82:85], v[196:199], v[166:169], v[82:85]
	v_mfma_f32_16x16x32_bf16 v[50:53], v[204:207], v[166:169], v[50:53]
	v_mfma_f32_16x16x32_bf16 v[22:25], v[212:215], v[166:169], v[22:25]
	v_mfma_f32_16x16x32_bf16 v[2:5], v[220:223], v[166:169], v[2:5]
	v_xor_b32_e32 v229, 0x4000, v229
	v_xor_b32_e32 v230, 0x4000, v230
	s_add_i32 s25, s25, 1
	s_cmp_lg_u32 s25, 42
	s_cbranch_scc1 .Lbk64_350
	s_waitcnt vmcnt(0)
	s_barrier
	ds_read_b128 v[192:195], v227
	ds_read_b128 v[196:199], v228
	ds_read_b128 v[200:203], v227 offset:2048
	ds_read_b128 v[204:207], v228 offset:2048
	ds_read_b128 v[208:211], v227 offset:4096
	ds_read_b128 v[212:215], v228 offset:4096
	ds_read_b128 v[216:219], v227 offset:6144
	ds_read_b128 v[220:223], v228 offset:6144
	s_waitcnt lgkmcnt(0)
	s_barrier
	ds_read_b128 v[154:157], v229 offset:0
	ds_read_b128 v[158:161], v230 offset:0
	ds_read_b128 v[162:165], v229 offset:2048
	ds_read_b128 v[166:169], v230 offset:2048
	s_waitcnt lgkmcnt(2)
	v_mfma_f32_16x16x32_bf16 v[126:129], v[192:195], v[154:157], v[126:129]
	v_mfma_f32_16x16x32_bf16 v[114:117], v[200:203], v[154:157], v[114:117]
	v_mfma_f32_16x16x32_bf16 v[86:89], v[208:211], v[154:157], v[86:89]
	v_mfma_f32_16x16x32_bf16 v[54:57], v[216:219], v[154:157], v[54:57]
	v_mfma_f32_16x16x32_bf16 v[126:129], v[196:199], v[158:161], v[126:129]
	v_mfma_f32_16x16x32_bf16 v[114:117], v[204:207], v[158:161], v[114:117]
	v_mfma_f32_16x16x32_bf16 v[86:89], v[212:215], v[158:161], v[86:89]
	v_mfma_f32_16x16x32_bf16 v[54:57], v[220:223], v[158:161], v[54:57]
	ds_read_b128 v[154:157], v229 offset:4096
	ds_read_b128 v[158:161], v230 offset:4096
	s_waitcnt lgkmcnt(2)
	v_mfma_f32_16x16x32_bf16 v[122:125], v[192:195], v[162:165], v[122:125]
	v_mfma_f32_16x16x32_bf16 v[102:105], v[200:203], v[162:165], v[102:105]
	v_mfma_f32_16x16x32_bf16 v[70:73], v[208:211], v[162:165], v[70:73]
	v_mfma_f32_16x16x32_bf16 v[38:41], v[216:219], v[162:165], v[38:41]
	v_mfma_f32_16x16x32_bf16 v[122:125], v[196:199], v[166:169], v[122:125]
	v_mfma_f32_16x16x32_bf16 v[102:105], v[204:207], v[166:169], v[102:105]
	v_mfma_f32_16x16x32_bf16 v[70:73], v[212:215], v[166:169], v[70:73]
	v_mfma_f32_16x16x32_bf16 v[38:41], v[220:223], v[166:169], v[38:41]
	ds_read_b128 v[162:165], v229 offset:6144
	ds_read_b128 v[166:169], v230 offset:6144
	s_waitcnt lgkmcnt(2)
	v_mfma_f32_16x16x32_bf16 v[118:121], v[192:195], v[154:157], v[118:121]
	v_mfma_f32_16x16x32_bf16 v[90:93], v[200:203], v[154:157], v[90:93]
	v_mfma_f32_16x16x32_bf16 v[58:61], v[208:211], v[154:157], v[58:61]
	v_mfma_f32_16x16x32_bf16 v[26:29], v[216:219], v[154:157], v[26:29]
	v_mfma_f32_16x16x32_bf16 v[118:121], v[196:199], v[158:161], v[118:121]
	v_mfma_f32_16x16x32_bf16 v[90:93], v[204:207], v[158:161], v[90:93]
	v_mfma_f32_16x16x32_bf16 v[58:61], v[212:215], v[158:161], v[58:61]
	v_mfma_f32_16x16x32_bf16 v[26:29], v[220:223], v[158:161], v[26:29]
	ds_read_b128 v[154:157], v229 offset:8192
	ds_read_b128 v[158:161], v230 offset:8192
	s_waitcnt lgkmcnt(2)
	v_mfma_f32_16x16x32_bf16 v[110:113], v[192:195], v[162:165], v[110:113]
	v_mfma_f32_16x16x32_bf16 v[78:81], v[200:203], v[162:165], v[78:81]
	v_mfma_f32_16x16x32_bf16 v[46:49], v[208:211], v[162:165], v[46:49]
	v_mfma_f32_16x16x32_bf16 v[18:21], v[216:219], v[162:165], v[18:21]
	v_mfma_f32_16x16x32_bf16 v[110:113], v[196:199], v[166:169], v[110:113]
	v_mfma_f32_16x16x32_bf16 v[78:81], v[204:207], v[166:169], v[78:81]
	v_mfma_f32_16x16x32_bf16 v[46:49], v[212:215], v[166:169], v[46:49]
	v_mfma_f32_16x16x32_bf16 v[18:21], v[220:223], v[166:169], v[18:21]
	ds_read_b128 v[162:165], v229 offset:10240
	ds_read_b128 v[166:169], v230 offset:10240
	s_waitcnt lgkmcnt(2)
	v_mfma_f32_16x16x32_bf16 v[106:109], v[192:195], v[154:157], v[106:109]
	v_mfma_f32_16x16x32_bf16 v[74:77], v[200:203], v[154:157], v[74:77]
	v_mfma_f32_16x16x32_bf16 v[42:45], v[208:211], v[154:157], v[42:45]
	v_mfma_f32_16x16x32_bf16 v[14:17], v[216:219], v[154:157], v[14:17]
	v_mfma_f32_16x16x32_bf16 v[106:109], v[196:199], v[158:161], v[106:109]
	v_mfma_f32_16x16x32_bf16 v[74:77], v[204:207], v[158:161], v[74:77]
	v_mfma_f32_16x16x32_bf16 v[42:45], v[212:215], v[158:161], v[42:45]
	v_mfma_f32_16x16x32_bf16 v[14:17], v[220:223], v[158:161], v[14:17]
	ds_read_b128 v[154:157], v229 offset:12288
	ds_read_b128 v[158:161], v230 offset:12288
	s_waitcnt lgkmcnt(2)
	v_mfma_f32_16x16x32_bf16 v[98:101], v[192:195], v[162:165], v[98:101]
	v_mfma_f32_16x16x32_bf16 v[66:69], v[200:203], v[162:165], v[66:69]
	v_mfma_f32_16x16x32_bf16 v[34:37], v[208:211], v[162:165], v[34:37]
	v_mfma_f32_16x16x32_bf16 v[10:13], v[216:219], v[162:165], v[10:13]
	v_mfma_f32_16x16x32_bf16 v[98:101], v[196:199], v[166:169], v[98:101]
	v_mfma_f32_16x16x32_bf16 v[66:69], v[204:207], v[166:169], v[66:69]
	v_mfma_f32_16x16x32_bf16 v[34:37], v[212:215], v[166:169], v[34:37]
	v_mfma_f32_16x16x32_bf16 v[10:13], v[220:223], v[166:169], v[10:13]
	ds_read_b128 v[162:165], v229 offset:14336
	ds_read_b128 v[166:169], v230 offset:14336
	s_waitcnt lgkmcnt(2)
	v_mfma_f32_16x16x32_bf16 v[94:97], v[192:195], v[154:157], v[94:97]
	v_mfma_f32_16x16x32_bf16 v[62:65], v[200:203], v[154:157], v[62:65]
	v_mfma_f32_16x16x32_bf16 v[30:33], v[208:211], v[154:157], v[30:33]
	v_mfma_f32_16x16x32_bf16 v[6:9], v[216:219], v[154:157], v[6:9]
	v_mfma_f32_16x16x32_bf16 v[94:97], v[196:199], v[158:161], v[94:97]
	v_mfma_f32_16x16x32_bf16 v[62:65], v[204:207], v[158:161], v[62:65]
	v_mfma_f32_16x16x32_bf16 v[30:33], v[212:215], v[158:161], v[30:33]
	v_mfma_f32_16x16x32_bf16 v[6:9], v[220:223], v[158:161], v[6:9]
	s_waitcnt lgkmcnt(0)
	v_mfma_f32_16x16x32_bf16 v[82:85], v[192:195], v[162:165], v[82:85]
	v_mfma_f32_16x16x32_bf16 v[50:53], v[200:203], v[162:165], v[50:53]
	v_mfma_f32_16x16x32_bf16 v[22:25], v[208:211], v[162:165], v[22:25]
	v_mfma_f32_16x16x32_bf16 v[2:5], v[216:219], v[162:165], v[2:5]
	v_mfma_f32_16x16x32_bf16 v[82:85], v[196:199], v[166:169], v[82:85]
	v_mfma_f32_16x16x32_bf16 v[50:53], v[204:207], v[166:169], v[50:53]
	v_mfma_f32_16x16x32_bf16 v[22:25], v[212:215], v[166:169], v[22:25]
	v_mfma_f32_16x16x32_bf16 v[2:5], v[220:223], v[166:169], v[2:5]
	s_nop 7
	s_nop 7
	s_waitcnt vmcnt(6)
	v_add_u32_e32 v145, v149, v147
	s_waitcnt vmcnt(0)
	s_waitcnt lgkmcnt(0)
	s_lshl_b32 s16, s5, 7
	s_ashr_i32 s17, s16, 31
	s_lshl_b64 s[16:17], s[16:17], 1
	v_and_b32_e32 v1, 0xfffffc0, v1
	v_lshl_or_b32 v1, v143, 2, v1
	v_mul_lo_u32 v1, v1, s33
	v_lshl_or_b32 v1, v142, 2, v1
	s_lshl_b32 s18, s5, 1
	s_ashr_i32 s19, s18, 31
	s_lshl_b64 s[18:19], s[18:19], 2
	s_add_i32 s24, s24, 1
	v_mov_b64_e32 v[158:159], v[62:63]
	v_mov_b64_e32 v[160:161], v[64:65]
	v_mov_b64_e32 v[162:163], v[30:31]
	v_mov_b64_e32 v[164:165], v[32:33]
	v_mov_b64_e32 v[130:131], v[22:23]
	v_mov_b64_e32 v[132:133], v[24:25]
	s_waitcnt lgkmcnt(0)
	v_mov_b64_e32 v[224:225], v[38:39]
	v_mov_b64_e32 v[226:227], v[40:41]
	v_mov_b64_e32 v[38:39], v[34:35]
	v_mov_b64_e32 v[40:41], v[36:37]
	v_mov_b64_e32 v[34:35], v[2:3]
	v_mov_b64_e32 v[36:37], v[4:5]
	s_nop 2
	v_mov_b32_e32 v2, v170
	v_mov_b64_e32 v[208:209], v[114:115]
	v_mov_b64_e32 v[210:211], v[116:117]
	v_add_u32_e32 v2, s4, v2
	v_ashrrev_i32_e32 v3, 31, v2
	v_lshlrev_b64 v[2:3], 11, v[2:3]
	v_lshl_add_u64 v[2:3], s[8:9], 0, v[2:3]
	v_lshl_add_u64 v[2:3], v[2:3], 0, s[16:17]
	v_mov_b64_e32 v[212:213], v[54:55]
	v_mov_b64_e32 v[214:215], v[56:57]
	v_mov_b64_e32 v[216:217], v[122:123]
	v_mov_b64_e32 v[218:219], v[124:125]
	v_mov_b64_e32 v[220:221], v[102:103]
	v_mov_b64_e32 v[222:223], v[104:105]
	v_mov_b64_e32 v[228:229], v[118:119]
	v_mov_b64_e32 v[230:231], v[120:121]
	v_mov_b64_e32 v[232:233], v[58:59]
	v_mov_b64_e32 v[234:235], v[60:61]
	v_mov_b64_e32 v[236:237], v[26:27]
	v_mov_b64_e32 v[238:239], v[28:29]
	v_mov_b64_e32 v[240:241], v[110:111]
	v_mov_b64_e32 v[242:243], v[112:113]
	v_mov_b64_e32 v[244:245], v[78:79]
	v_mov_b64_e32 v[246:247], v[80:81]
	v_mov_b64_e32 v[248:249], v[46:47]
	v_mov_b64_e32 v[250:251], v[48:49]
	v_mov_b64_e32 v[62:63], v[106:107]
	v_mov_b64_e32 v[64:65], v[108:109]
	v_mov_b64_e32 v[46:47], v[74:75]
	v_mov_b64_e32 v[48:49], v[76:77]
	v_mov_b64_e32 v[74:75], v[98:99]
	v_mov_b64_e32 v[76:77], v[100:101]
	v_mov_b64_e32 v[54:55], v[66:67]
	v_mov_b64_e32 v[56:57], v[68:69]
	v_mov_b64_e32 v[58:59], v[158:159]
	v_mov_b64_e32 v[60:61], v[160:161]
	v_mov_b64_e32 v[66:67], v[50:51]
	v_mov_b64_e32 v[68:69], v[52:53]
	flat_load_dwordx4 v[138:141], v[2:3]
	flat_load_dwordx4 v[122:125], v[2:3] offset:16
	flat_load_dwordx4 v[118:121], v[2:3] offset:32
	flat_load_dwordx4 v[114:117], v[2:3] offset:48
	flat_load_dwordx4 v[110:113], v[2:3] offset:64
	flat_load_dwordx4 v[106:109], v[2:3] offset:80
	flat_load_dwordx4 v[102:105], v[2:3] offset:96
	flat_load_dwordx4 v[98:101], v[2:3] offset:112
	s_waitcnt vmcnt(0) lgkmcnt(0)
	s_barrier
	s_nop 7
	ds_write2_b32 v1, v126, v216 offset1:16
	ds_write2_b32 v1, v127, v217 offset0:68 offset1:84
	ds_write2_b32 v1, v128, v218 offset0:136 offset1:152
	ds_write2_b32 v1, v129, v219 offset0:204 offset1:220
	ds_write2_b32 v1, v228, v240 offset0:32 offset1:48
	ds_write2_b32 v1, v229, v241 offset0:100 offset1:116
	ds_write2_b32 v1, v230, v242 offset0:168 offset1:184
	ds_write2_b32 v1, v231, v243 offset0:236 offset1:252
	v_mov_b64_e32 v[180:181], v[18:19]
	v_mov_b64_e32 v[182:183], v[20:21]
	v_mov_b64_e32 v[78:79], v[94:95]
	v_mov_b64_e32 v[80:81], v[96:97]
	v_add_u32_e32 v135, 0x3000, v1
	v_add_u32_e32 v134, 0x3400, v1
	v_mov_b32_e32 v136, v170
	v_mov_b64_e32 v[50:51], v[130:131]
	v_mov_b64_e32 v[52:53], v[132:133]
	v_lshlrev_b32_e32 v137, 16, v138
	s_nop 1
	v_add_u32_e32 v130, 0x1000, v1
	v_add_u32_e32 v131, 0x1400, v1
	v_add_u32_e32 v132, 0x2000, v1
	v_add_u32_e32 v133, 0x2400, v1
	ds_write2_b32 v130, v208, v220 offset0:64 offset1:80
	ds_write2_b32 v130, v209, v221 offset0:132 offset1:148
	ds_write2_b32 v130, v210, v222 offset0:200 offset1:216
	ds_write2_b32 v131, v211, v223 offset0:12 offset1:28
	ds_write2_b32 v130, v90, v244 offset0:96 offset1:112
	ds_write2_b32 v130, v91, v245 offset0:164 offset1:180
	ds_write2_b32 v130, v92, v246 offset0:232 offset1:248
	ds_write2_b32 v131, v93, v247 offset0:44 offset1:60
	ds_write2_b32 v132, v86, v70 offset0:128 offset1:144
	ds_write2_b32 v132, v87, v71 offset0:196 offset1:212
	ds_write2_b32 v133, v88, v72 offset0:8 offset1:24
	ds_write2_b32 v133, v89, v73 offset0:76 offset1:92
	ds_write2_b32 v132, v232, v248 offset0:160 offset1:176
	ds_write2_b32 v132, v233, v249 offset0:228 offset1:244
	ds_write2_b32 v133, v234, v250 offset0:40 offset1:56
	ds_write2_b32 v133, v235, v251 offset0:108 offset1:124
	ds_write2_b32 v135, v212, v224 offset0:192 offset1:208
	ds_write2_b32 v134, v213, v225 offset0:4 offset1:20
	ds_write2_b32 v134, v214, v226 offset0:72 offset1:88
	ds_write2_b32 v134, v215, v227 offset0:140 offset1:156
	ds_write2_b32 v135, v236, v180 offset0:224 offset1:240
	ds_write2_b32 v134, v237, v181 offset0:36 offset1:52
	ds_write2_b32 v134, v238, v182 offset0:104 offset1:120
	ds_write2_b32 v134, v239, v183 offset0:172 offset1:188
	s_waitcnt lgkmcnt(0)
	s_barrier
	v_mov_b64_e32 v[30:31], v[42:43]
	v_mov_b64_e32 v[32:33], v[44:45]
	v_add_u32_e32 v126, s4, v136
	v_ashrrev_i32_e32 v127, 31, v126
	v_lshlrev_b64 v[2:3], 11, v[126:127]
	v_lshl_add_u64 v[2:3], s[8:9], 0, v[2:3]
	v_lshl_add_u64 v[128:129], v[2:3], 0, s[16:17]
	v_mul_lo_u32 v136, v136, s33
	v_mov_b64_e32 v[18:19], v[14:15]
	v_mov_b64_e32 v[20:21], v[16:17]
	v_and_b32_e32 v138, 0xffff0000, v138
	v_mov_b64_e32 v[22:23], v[10:11]
	v_mov_b64_e32 v[24:25], v[12:13]
	v_mov_b64_e32 v[42:43], v[162:163]
	v_mov_b64_e32 v[44:45], v[164:165]
	v_mov_b64_e32 v[26:27], v[6:7]
	v_mov_b64_e32 v[28:29], v[8:9]
	flat_load_dwordx4 v[94:97], v[128:129] offset:128
	flat_load_dwordx4 v[90:93], v[128:129] offset:144
	flat_load_dwordx4 v[86:89], v[128:129] offset:160
	flat_load_dwordx4 v[70:73], v[128:129] offset:176
	flat_load_dwordx4 v[14:17], v[128:129] offset:192
	flat_load_dwordx4 v[10:13], v[128:129] offset:208
	flat_load_dwordx4 v[6:9], v[128:129] offset:224
	flat_load_dwordx4 v[2:5], v[128:129] offset:240
	ds_read_b128 v[142:145], v136
	ds_read_b128 v[154:157], v136 offset:16
	s_waitcnt lgkmcnt(0)
	v_add_f32_e32 v137, v142, v137
	v_add_f32_e32 v138, v143, v138
	v_cvt_pk_bf16_f32 v138, v137, v138
	v_lshlrev_b32_e32 v137, 16, v139
	v_and_b32_e32 v139, 0xffff0000, v139
	v_add_f32_e32 v137, v144, v137
	v_add_f32_e32 v139, v145, v139
	v_cvt_pk_bf16_f32 v139, v137, v139
	v_lshlrev_b32_e32 v137, 16, v140
	v_and_b32_e32 v140, 0xffff0000, v140
	v_add_f32_e32 v137, v154, v137
	v_add_f32_e32 v140, v155, v140
	v_cvt_pk_bf16_f32 v140, v137, v140
	v_lshlrev_b32_e32 v137, 16, v141
	v_and_b32_e32 v141, 0xffff0000, v141
	v_add_f32_e32 v137, v156, v137
	v_add_f32_e32 v141, v157, v141
	v_and_b32_e32 v142, 0xffff0000, v138
	v_cvt_pk_bf16_f32 v141, v137, v141
	v_lshlrev_b32_e32 v137, 16, v138
	v_mul_f32_e32 v153, v142, v142
	v_lshlrev_b32_e32 v143, 16, v139
	v_fmac_f32_e32 v153, v137, v137
	v_and_b32_e32 v144, 0xffff0000, v139
	v_fmac_f32_e32 v153, v143, v143
	v_lshlrev_b32_e32 v145, 16, v140
	v_fmac_f32_e32 v153, v144, v144
	flat_store_dwordx4 v[128:129], v[138:141]
	v_and_b32_e32 v147, 0xffff0000, v140
	v_lshlrev_b32_e32 v149, 16, v141
	v_and_b32_e32 v151, 0xffff0000, v141
	v_fmac_f32_e32 v153, v145, v145
	ds_read_b128 v[138:141], v136 offset:32
	ds_read_b128 v[142:145], v136 offset:48
	v_lshlrev_b32_e32 v137, 16, v122
	v_and_b32_e32 v122, 0xffff0000, v122
	v_fmac_f32_e32 v153, v147, v147
	s_waitcnt lgkmcnt(0)
	v_add_f32_e32 v137, v138, v137
	v_add_f32_e32 v122, v139, v122
	v_cvt_pk_bf16_f32 v122, v137, v122
	v_lshlrev_b32_e32 v137, 16, v123
	v_and_b32_e32 v123, 0xffff0000, v123
	v_add_f32_e32 v137, v140, v137
	v_add_f32_e32 v123, v141, v123
	v_cvt_pk_bf16_f32 v123, v137, v123
	v_lshlrev_b32_e32 v137, 16, v124
	v_and_b32_e32 v124, 0xffff0000, v124
	v_add_f32_e32 v137, v142, v137
	v_add_f32_e32 v124, v143, v124
	v_cvt_pk_bf16_f32 v124, v137, v124
	v_lshlrev_b32_e32 v137, 16, v125
	v_and_b32_e32 v125, 0xffff0000, v125
	v_add_f32_e32 v137, v144, v137
	v_add_f32_e32 v125, v145, v125
	v_and_b32_e32 v138, 0xffff0000, v122
	v_cvt_pk_bf16_f32 v125, v137, v125
	v_lshlrev_b32_e32 v137, 16, v122
	v_mul_f32_e32 v138, v138, v138
	v_lshlrev_b32_e32 v139, 16, v123
	v_fmac_f32_e32 v138, v137, v137
	v_and_b32_e32 v140, 0xffff0000, v123
	v_fmac_f32_e32 v138, v139, v139
	v_lshlrev_b32_e32 v141, 16, v124
	v_fmac_f32_e32 v138, v140, v140
	v_and_b32_e32 v142, 0xffff0000, v124
	v_fmac_f32_e32 v138, v141, v141
	v_lshlrev_b32_e32 v143, 16, v125
	v_fmac_f32_e32 v138, v142, v142
	v_fmac_f32_e32 v153, v149, v149
	v_and_b32_e32 v144, 0xffff0000, v125
	v_fmac_f32_e32 v138, v143, v143
	v_fmac_f32_e32 v153, v151, v151
	v_fmac_f32_e32 v138, v144, v144
	flat_store_dwordx4 v[128:129], v[122:125] offset:16
	v_add_f32_e32 v137, v153, v138
	ds_read_b128 v[122:125], v136 offset:64
	ds_read_b128 v[138:141], v136 offset:80
	v_lshlrev_b32_e32 v142, 16, v118
	v_and_b32_e32 v118, 0xffff0000, v118
	s_waitcnt lgkmcnt(0)
	v_add_f32_e32 v122, v122, v142
	v_add_f32_e32 v118, v123, v118
	v_cvt_pk_bf16_f32 v118, v122, v118
	v_lshlrev_b32_e32 v122, 16, v119
	v_and_b32_e32 v119, 0xffff0000, v119
	v_add_f32_e32 v122, v124, v122
	v_add_f32_e32 v119, v125, v119
	v_cvt_pk_bf16_f32 v119, v122, v119
	v_lshlrev_b32_e32 v122, 16, v120
	v_and_b32_e32 v120, 0xffff0000, v120
	v_add_f32_e32 v122, v138, v122
	v_add_f32_e32 v120, v139, v120
	v_cvt_pk_bf16_f32 v120, v122, v120
	v_lshlrev_b32_e32 v122, 16, v121
	v_and_b32_e32 v121, 0xffff0000, v121
	v_add_f32_e32 v122, v140, v122
	v_add_f32_e32 v121, v141, v121
	v_and_b32_e32 v123, 0xffff0000, v118
	v_cvt_pk_bf16_f32 v121, v122, v121
	v_lshlrev_b32_e32 v122, 16, v118
	v_mul_f32_e32 v123, v123, v123
	v_lshlrev_b32_e32 v124, 16, v119
	v_fmac_f32_e32 v123, v122, v122
	v_and_b32_e32 v125, 0xffff0000, v119
	v_fmac_f32_e32 v123, v124, v124
	v_lshlrev_b32_e32 v138, 16, v120
	v_fmac_f32_e32 v123, v125, v125
	v_and_b32_e32 v139, 0xffff0000, v120
	v_fmac_f32_e32 v123, v138, v138
	v_lshlrev_b32_e32 v140, 16, v121
	v_fmac_f32_e32 v123, v139, v139
	v_and_b32_e32 v141, 0xffff0000, v121
	v_fmac_f32_e32 v123, v140, v140
	v_fmac_f32_e32 v123, v141, v141
	flat_store_dwordx4 v[128:129], v[118:121] offset:32
	v_add_f32_e32 v137, v137, v123
	ds_read_b128 v[118:121], v136 offset:96
	ds_read_b128 v[122:125], v136 offset:112
	v_lshlrev_b32_e32 v138, 16, v114
	v_and_b32_e32 v114, 0xffff0000, v114
	s_waitcnt lgkmcnt(0)
	v_add_f32_e32 v118, v118, v138
	v_add_f32_e32 v114, v119, v114
	v_cvt_pk_bf16_f32 v114, v118, v114
	v_lshlrev_b32_e32 v118, 16, v115
	v_and_b32_e32 v115, 0xffff0000, v115
	v_add_f32_e32 v118, v120, v118
	v_add_f32_e32 v115, v121, v115
	v_cvt_pk_bf16_f32 v115, v118, v115
	v_lshlrev_b32_e32 v118, 16, v116
	v_and_b32_e32 v116, 0xffff0000, v116
	v_add_f32_e32 v118, v122, v118
	v_add_f32_e32 v116, v123, v116
	v_cvt_pk_bf16_f32 v116, v118, v116
	v_lshlrev_b32_e32 v118, 16, v117
	v_and_b32_e32 v117, 0xffff0000, v117
	v_add_f32_e32 v118, v124, v118
	v_add_f32_e32 v117, v125, v117
	v_and_b32_e32 v119, 0xffff0000, v114
	v_cvt_pk_bf16_f32 v117, v118, v117
	v_lshlrev_b32_e32 v118, 16, v114
	v_mul_f32_e32 v119, v119, v119
	v_lshlrev_b32_e32 v120, 16, v115
	v_fmac_f32_e32 v119, v118, v118
	v_and_b32_e32 v121, 0xffff0000, v115
	v_fmac_f32_e32 v119, v120, v120
	v_lshlrev_b32_e32 v122, 16, v116
	v_fmac_f32_e32 v119, v121, v121
	v_and_b32_e32 v123, 0xffff0000, v116
	v_fmac_f32_e32 v119, v122, v122
	v_lshlrev_b32_e32 v124, 16, v117
	v_fmac_f32_e32 v119, v123, v123
	v_and_b32_e32 v125, 0xffff0000, v117
	v_fmac_f32_e32 v119, v124, v124
	v_fmac_f32_e32 v119, v125, v125
	flat_store_dwordx4 v[128:129], v[114:117] offset:48
	v_add_f32_e32 v122, v137, v119
	ds_read_b128 v[114:117], v136 offset:128
	ds_read_b128 v[118:121], v136 offset:144
	v_lshlrev_b32_e32 v123, 16, v110
	v_and_b32_e32 v110, 0xffff0000, v110
	s_waitcnt lgkmcnt(0)
	v_add_f32_e32 v114, v114, v123
	v_add_f32_e32 v110, v115, v110
	v_cvt_pk_bf16_f32 v110, v114, v110
	v_lshlrev_b32_e32 v114, 16, v111
	v_and_b32_e32 v111, 0xffff0000, v111
	v_add_f32_e32 v114, v116, v114
	v_add_f32_e32 v111, v117, v111
	v_cvt_pk_bf16_f32 v111, v114, v111
	v_lshlrev_b32_e32 v114, 16, v112
	v_and_b32_e32 v112, 0xffff0000, v112
	v_add_f32_e32 v114, v118, v114
	v_add_f32_e32 v112, v119, v112
	v_cvt_pk_bf16_f32 v112, v114, v112
	v_lshlrev_b32_e32 v114, 16, v113
	v_and_b32_e32 v113, 0xffff0000, v113
	v_add_f32_e32 v114, v120, v114
	v_add_f32_e32 v113, v121, v113
	v_and_b32_e32 v115, 0xffff0000, v110
	v_cvt_pk_bf16_f32 v113, v114, v113
	v_lshlrev_b32_e32 v114, 16, v110
	v_mul_f32_e32 v115, v115, v115
	v_lshlrev_b32_e32 v116, 16, v111
	v_fmac_f32_e32 v115, v114, v114
	v_and_b32_e32 v117, 0xffff0000, v111
	v_fmac_f32_e32 v115, v116, v116
	v_lshlrev_b32_e32 v118, 16, v112
	v_fmac_f32_e32 v115, v117, v117
	v_and_b32_e32 v119, 0xffff0000, v112
	v_fmac_f32_e32 v115, v118, v118
	v_lshlrev_b32_e32 v120, 16, v113
	v_fmac_f32_e32 v115, v119, v119
	v_and_b32_e32 v121, 0xffff0000, v113
	v_fmac_f32_e32 v115, v120, v120
	v_fmac_f32_e32 v115, v121, v121
	flat_store_dwordx4 v[128:129], v[110:113] offset:64
	v_add_f32_e32 v118, v122, v115
	ds_read_b128 v[110:113], v136 offset:160
	ds_read_b128 v[114:117], v136 offset:176
	v_lshlrev_b32_e32 v119, 16, v106
	v_and_b32_e32 v106, 0xffff0000, v106
	s_waitcnt lgkmcnt(0)
	v_add_f32_e32 v110, v110, v119
	v_add_f32_e32 v106, v111, v106
	v_cvt_pk_bf16_f32 v106, v110, v106
	v_lshlrev_b32_e32 v110, 16, v107
	v_and_b32_e32 v107, 0xffff0000, v107
	v_add_f32_e32 v110, v112, v110
	v_add_f32_e32 v107, v113, v107
	v_cvt_pk_bf16_f32 v107, v110, v107
	v_lshlrev_b32_e32 v110, 16, v108
	v_and_b32_e32 v108, 0xffff0000, v108
	v_add_f32_e32 v110, v114, v110
	v_add_f32_e32 v108, v115, v108
	v_cvt_pk_bf16_f32 v108, v110, v108
	v_lshlrev_b32_e32 v110, 16, v109
	v_and_b32_e32 v109, 0xffff0000, v109
	v_add_f32_e32 v110, v116, v110
	v_add_f32_e32 v109, v117, v109
	v_and_b32_e32 v111, 0xffff0000, v106
	v_cvt_pk_bf16_f32 v109, v110, v109
	v_lshlrev_b32_e32 v110, 16, v106
	v_mul_f32_e32 v111, v111, v111
	v_lshlrev_b32_e32 v112, 16, v107
	v_fmac_f32_e32 v111, v110, v110
	v_and_b32_e32 v113, 0xffff0000, v107
	v_fmac_f32_e32 v111, v112, v112
	v_lshlrev_b32_e32 v114, 16, v108
	v_fmac_f32_e32 v111, v113, v113
	v_and_b32_e32 v115, 0xffff0000, v108
	v_fmac_f32_e32 v111, v114, v114
	v_lshlrev_b32_e32 v116, 16, v109
	v_fmac_f32_e32 v111, v115, v115
	v_and_b32_e32 v117, 0xffff0000, v109
	v_fmac_f32_e32 v111, v116, v116
	v_fmac_f32_e32 v111, v117, v117
	flat_store_dwordx4 v[128:129], v[106:109] offset:80
	v_add_f32_e32 v114, v118, v111
	ds_read_b128 v[106:109], v136 offset:192
	ds_read_b128 v[110:113], v136 offset:208
	v_lshlrev_b32_e32 v115, 16, v102
	v_and_b32_e32 v102, 0xffff0000, v102
	s_waitcnt lgkmcnt(0)
	v_add_f32_e32 v106, v106, v115
	v_add_f32_e32 v102, v107, v102
	v_cvt_pk_bf16_f32 v102, v106, v102
	v_lshlrev_b32_e32 v106, 16, v103
	v_and_b32_e32 v103, 0xffff0000, v103
	v_add_f32_e32 v106, v108, v106
	v_add_f32_e32 v103, v109, v103
	v_cvt_pk_bf16_f32 v103, v106, v103
	v_lshlrev_b32_e32 v106, 16, v104
	v_and_b32_e32 v104, 0xffff0000, v104
	v_add_f32_e32 v106, v110, v106
	v_add_f32_e32 v104, v111, v104
	v_cvt_pk_bf16_f32 v104, v106, v104
	v_lshlrev_b32_e32 v106, 16, v105
	v_and_b32_e32 v105, 0xffff0000, v105
	v_add_f32_e32 v106, v112, v106
	v_add_f32_e32 v105, v113, v105
	v_and_b32_e32 v107, 0xffff0000, v102
	v_cvt_pk_bf16_f32 v105, v106, v105
	v_lshlrev_b32_e32 v106, 16, v102
	v_mul_f32_e32 v107, v107, v107
	v_lshlrev_b32_e32 v108, 16, v103
	v_fmac_f32_e32 v107, v106, v106
	v_and_b32_e32 v109, 0xffff0000, v103
	v_fmac_f32_e32 v107, v108, v108
	v_lshlrev_b32_e32 v110, 16, v104
	v_fmac_f32_e32 v107, v109, v109
	v_and_b32_e32 v111, 0xffff0000, v104
	v_fmac_f32_e32 v107, v110, v110
	v_lshlrev_b32_e32 v112, 16, v105
	v_fmac_f32_e32 v107, v111, v111
	v_and_b32_e32 v113, 0xffff0000, v105
	v_fmac_f32_e32 v107, v112, v112
	v_fmac_f32_e32 v107, v113, v113
	flat_store_dwordx4 v[128:129], v[102:105] offset:96
	v_add_f32_e32 v110, v114, v107
	ds_read_b128 v[102:105], v136 offset:224
	ds_read_b128 v[106:109], v136 offset:240
	v_lshlrev_b32_e32 v111, 16, v98
	v_and_b32_e32 v98, 0xffff0000, v98
	s_waitcnt lgkmcnt(0)
	v_add_f32_e32 v102, v102, v111
	v_add_f32_e32 v98, v103, v98
	v_cvt_pk_bf16_f32 v98, v102, v98
	v_lshlrev_b32_e32 v102, 16, v99
	v_and_b32_e32 v99, 0xffff0000, v99
	v_add_f32_e32 v102, v104, v102
	v_add_f32_e32 v99, v105, v99
	v_cvt_pk_bf16_f32 v99, v102, v99
	v_lshlrev_b32_e32 v102, 16, v100
	v_and_b32_e32 v100, 0xffff0000, v100
	v_add_f32_e32 v102, v106, v102
	v_add_f32_e32 v100, v107, v100
	v_cvt_pk_bf16_f32 v100, v102, v100
	v_lshlrev_b32_e32 v102, 16, v101
	v_and_b32_e32 v101, 0xffff0000, v101
	v_add_f32_e32 v102, v108, v102
	v_add_f32_e32 v101, v109, v101
	v_and_b32_e32 v103, 0xffff0000, v98
	v_cvt_pk_bf16_f32 v101, v102, v101
	v_lshlrev_b32_e32 v102, 16, v98
	v_mul_f32_e32 v103, v103, v103
	v_lshlrev_b32_e32 v104, 16, v99
	v_fmac_f32_e32 v103, v102, v102
	v_and_b32_e32 v105, 0xffff0000, v99
	v_fmac_f32_e32 v103, v104, v104
	v_lshlrev_b32_e32 v106, 16, v100
	v_fmac_f32_e32 v103, v105, v105
	v_and_b32_e32 v107, 0xffff0000, v100
	v_fmac_f32_e32 v103, v106, v106
	v_lshlrev_b32_e32 v108, 16, v101
	v_fmac_f32_e32 v103, v107, v107
	v_and_b32_e32 v109, 0xffff0000, v101
	v_fmac_f32_e32 v103, v108, v108
	flat_store_dwordx4 v[128:129], v[98:101] offset:112
	v_fmac_f32_e32 v103, v109, v109
	v_add_f32_e32 v102, v110, v103
	v_lshlrev_b64 v[98:99], 6, v[126:127]
	v_lshl_add_u64 v[98:99], s[6:7], 0, v[98:99]
	v_lshl_add_u64 v[98:99], v[98:99], 0, s[18:19]
	flat_store_dword v[98:99], v102
	s_waitcnt lgkmcnt(0)
	s_barrier
	ds_write2_b32 v1, v62, v74 offset1:16
	ds_write2_b32 v1, v63, v75 offset0:68 offset1:84
	ds_write2_b32 v1, v64, v76 offset0:136 offset1:152
	ds_write2_b32 v1, v65, v77 offset0:204 offset1:220
	ds_write2_b32 v1, v78, v82 offset0:32 offset1:48
	ds_write2_b32 v1, v79, v83 offset0:100 offset1:116
	ds_write2_b32 v1, v80, v84 offset0:168 offset1:184
	ds_write2_b32 v1, v81, v85 offset0:236 offset1:252
	ds_write2_b32 v130, v46, v54 offset0:64 offset1:80
	ds_write2_b32 v130, v47, v55 offset0:132 offset1:148
	ds_write2_b32 v130, v48, v56 offset0:200 offset1:216
	ds_write2_b32 v131, v49, v57 offset0:12 offset1:28
	ds_write2_b32 v130, v58, v66 offset0:96 offset1:112
	ds_write2_b32 v130, v59, v67 offset0:164 offset1:180
	ds_write2_b32 v130, v60, v68 offset0:232 offset1:248
	ds_write2_b32 v131, v61, v69 offset0:44 offset1:60
	ds_write2_b32 v132, v30, v38 offset0:128 offset1:144
	ds_write2_b32 v132, v31, v39 offset0:196 offset1:212
	ds_write2_b32 v133, v32, v40 offset0:8 offset1:24
	ds_write2_b32 v133, v33, v41 offset0:76 offset1:92
	ds_write2_b32 v132, v42, v50 offset0:160 offset1:176
	ds_write2_b32 v132, v43, v51 offset0:228 offset1:244
	ds_write2_b32 v133, v44, v52 offset0:40 offset1:56
	ds_write2_b32 v133, v45, v53 offset0:108 offset1:124
	ds_write2_b32 v135, v18, v22 offset0:192 offset1:208
	ds_write2_b32 v134, v19, v23 offset0:4 offset1:20
	ds_write2_b32 v134, v20, v24 offset0:72 offset1:88
	ds_write2_b32 v134, v21, v25 offset0:140 offset1:156
	ds_write2_b32 v135, v26, v34 offset0:224 offset1:240
	ds_write2_b32 v134, v27, v35 offset0:36 offset1:52
	ds_write2_b32 v134, v28, v36 offset0:104 offset1:120
	ds_write2_b32 v134, v29, v37 offset0:172 offset1:188
	v_mov_b32_e32 v1, v170
	s_waitcnt lgkmcnt(0)
	s_barrier
	s_waitcnt vmcnt(0)
	v_lshlrev_b32_e32 v28, 16, v94
	v_add_u32_e32 v18, s4, v1
	v_ashrrev_i32_e32 v19, 31, v18
	v_lshlrev_b64 v[20:21], 11, v[18:19]
	v_lshl_add_u64 v[20:21], s[38:39], 0, v[20:21]
	v_mul_lo_u32 v1, v1, s33
	v_lshl_add_u64 v[32:33], v[20:21], 0, s[16:17]
	ds_read_b128 v[20:23], v1
	ds_read_b128 v[24:27], v1 offset:16
	s_mov_b64 s[4:5], 0
	s_waitcnt lgkmcnt(1)
	v_add_f32_e32 v20, v20, v28
	v_and_b32_e32 v28, 0xffff0000, v94
	v_add_f32_e32 v21, v21, v28
	v_cvt_pk_bf16_f32 v28, v20, v21
	v_and_b32_e32 v21, 0xffff0000, v95
	v_lshlrev_b32_e32 v20, 16, v95
	v_add_f32_e32 v21, v23, v21
	v_add_f32_e32 v20, v22, v20
	v_cvt_pk_bf16_f32 v29, v20, v21
	v_and_b32_e32 v21, 0xffff0000, v96
	v_lshlrev_b32_e32 v20, 16, v96
	s_waitcnt lgkmcnt(0)
	v_add_f32_e32 v21, v25, v21
	v_add_f32_e32 v20, v24, v20
	v_cvt_pk_bf16_f32 v30, v20, v21
	v_and_b32_e32 v21, 0xffff0000, v97
	v_lshlrev_b32_e32 v20, 16, v97
	v_add_f32_e32 v21, v27, v21
	v_add_f32_e32 v20, v26, v20
	v_cvt_pk_bf16_f32 v31, v20, v21
	v_and_b32_e32 v21, 0xffff0000, v28
	v_lshlrev_b32_e32 v20, 16, v28
	v_mul_f32_e32 v34, v21, v21
	v_lshlrev_b32_e32 v22, 16, v29
	v_fmac_f32_e32 v34, v20, v20
	v_and_b32_e32 v23, 0xffff0000, v29
	v_fmac_f32_e32 v34, v22, v22
	v_lshlrev_b32_e32 v24, 16, v30
	v_fmac_f32_e32 v34, v23, v23
	v_and_b32_e32 v25, 0xffff0000, v30
	v_fmac_f32_e32 v34, v24, v24
	v_add_co_u32_e32 v20, vcc, s90, v32
	v_lshlrev_b32_e32 v26, 16, v31
	v_fmac_f32_e32 v34, v25, v25
	v_addc_co_u32_e32 v21, vcc, 0, v33, vcc
	v_and_b32_e32 v27, 0xffff0000, v31
	v_fmac_f32_e32 v34, v26, v26
	flat_store_dwordx4 v[20:21], v[28:31] offset:128
	v_fmac_f32_e32 v34, v27, v27
	ds_read_b128 v[22:25], v1 offset:32
	ds_read_b128 v[26:29], v1 offset:48
	v_lshlrev_b32_e32 v30, 16, v90
	s_waitcnt lgkmcnt(0)
	v_add_f32_e32 v22, v22, v30
	v_and_b32_e32 v30, 0xffff0000, v90
	v_add_f32_e32 v23, v23, v30
	v_cvt_pk_bf16_f32 v22, v22, v23
	v_lshlrev_b32_e32 v23, 16, v91
	v_add_f32_e32 v23, v24, v23
	v_and_b32_e32 v24, 0xffff0000, v91
	v_add_f32_e32 v24, v25, v24
	v_cvt_pk_bf16_f32 v23, v23, v24
	v_lshlrev_b32_e32 v24, 16, v92
	v_and_b32_e32 v25, 0xffff0000, v92
	v_add_f32_e32 v24, v26, v24
	v_add_f32_e32 v25, v27, v25
	v_cvt_pk_bf16_f32 v24, v24, v25
	v_lshlrev_b32_e32 v25, 16, v93
	v_and_b32_e32 v26, 0xffff0000, v93
	v_add_f32_e32 v25, v28, v25
	v_add_f32_e32 v26, v29, v26
	v_and_b32_e32 v27, 0xffff0000, v22
	v_cvt_pk_bf16_f32 v25, v25, v26
	v_lshlrev_b32_e32 v26, 16, v22
	v_mul_f32_e32 v27, v27, v27
	v_lshlrev_b32_e32 v28, 16, v23
	v_fmac_f32_e32 v27, v26, v26
	v_and_b32_e32 v29, 0xffff0000, v23
	v_fmac_f32_e32 v27, v28, v28
	v_lshlrev_b32_e32 v30, 16, v24
	v_fmac_f32_e32 v27, v29, v29
	v_and_b32_e32 v31, 0xffff0000, v24
	v_fmac_f32_e32 v27, v30, v30
	v_lshlrev_b32_e32 v32, 16, v25
	v_fmac_f32_e32 v27, v31, v31
	v_and_b32_e32 v33, 0xffff0000, v25
	v_fmac_f32_e32 v27, v32, v32
	v_fmac_f32_e32 v27, v33, v33
	flat_store_dwordx4 v[20:21], v[22:25] offset:144
	v_add_f32_e32 v30, v34, v27
	ds_read_b128 v[22:25], v1 offset:64
	ds_read_b128 v[26:29], v1 offset:80
	v_lshlrev_b32_e32 v31, 16, v86
	s_waitcnt lgkmcnt(0)
	v_add_f32_e32 v22, v22, v31
	v_and_b32_e32 v31, 0xffff0000, v86
	v_add_f32_e32 v23, v23, v31
	v_cvt_pk_bf16_f32 v22, v22, v23
	v_lshlrev_b32_e32 v23, 16, v87
	v_add_f32_e32 v23, v24, v23
	v_and_b32_e32 v24, 0xffff0000, v87
	v_add_f32_e32 v24, v25, v24
	v_cvt_pk_bf16_f32 v23, v23, v24
	v_lshlrev_b32_e32 v24, 16, v88
	v_and_b32_e32 v25, 0xffff0000, v88
	v_add_f32_e32 v24, v26, v24
	v_add_f32_e32 v25, v27, v25
	v_cvt_pk_bf16_f32 v24, v24, v25
	v_lshlrev_b32_e32 v25, 16, v89
	v_and_b32_e32 v26, 0xffff0000, v89
	v_add_f32_e32 v25, v28, v25
	v_add_f32_e32 v26, v29, v26
	v_and_b32_e32 v27, 0xffff0000, v22
	v_cvt_pk_bf16_f32 v25, v25, v26
	v_lshlrev_b32_e32 v26, 16, v22
	v_mul_f32_e32 v27, v27, v27
	v_lshlrev_b32_e32 v28, 16, v23
	v_fmac_f32_e32 v27, v26, v26
	v_and_b32_e32 v29, 0xffff0000, v23
	v_fmac_f32_e32 v27, v28, v28
	v_lshlrev_b32_e32 v31, 16, v24
	v_fmac_f32_e32 v27, v29, v29
	v_and_b32_e32 v32, 0xffff0000, v24
	v_fmac_f32_e32 v27, v31, v31
	v_lshlrev_b32_e32 v33, 16, v25
	v_fmac_f32_e32 v27, v32, v32
	v_and_b32_e32 v34, 0xffff0000, v25
	v_fmac_f32_e32 v27, v33, v33
	v_fmac_f32_e32 v27, v34, v34
	flat_store_dwordx4 v[20:21], v[22:25] offset:160
	v_add_f32_e32 v30, v30, v27
	ds_read_b128 v[22:25], v1 offset:96
	ds_read_b128 v[26:29], v1 offset:112
	v_lshlrev_b32_e32 v31, 16, v70
	s_waitcnt lgkmcnt(0)
	v_add_f32_e32 v22, v22, v31
	v_and_b32_e32 v31, 0xffff0000, v70
	v_add_f32_e32 v23, v23, v31
	v_cvt_pk_bf16_f32 v22, v22, v23
	v_lshlrev_b32_e32 v23, 16, v71
	v_add_f32_e32 v23, v24, v23
	v_and_b32_e32 v24, 0xffff0000, v71
	v_add_f32_e32 v24, v25, v24
	v_cvt_pk_bf16_f32 v23, v23, v24
	v_lshlrev_b32_e32 v24, 16, v72
	v_and_b32_e32 v25, 0xffff0000, v72
	v_add_f32_e32 v24, v26, v24
	v_add_f32_e32 v25, v27, v25
	v_cvt_pk_bf16_f32 v24, v24, v25
	v_lshlrev_b32_e32 v25, 16, v73
	v_and_b32_e32 v26, 0xffff0000, v73
	v_add_f32_e32 v25, v28, v25
	v_add_f32_e32 v26, v29, v26
	v_and_b32_e32 v27, 0xffff0000, v22
	v_cvt_pk_bf16_f32 v25, v25, v26
	v_lshlrev_b32_e32 v26, 16, v22
	v_mul_f32_e32 v27, v27, v27
	v_lshlrev_b32_e32 v28, 16, v23
	v_fmac_f32_e32 v27, v26, v26
	v_and_b32_e32 v29, 0xffff0000, v23
	v_fmac_f32_e32 v27, v28, v28
	v_lshlrev_b32_e32 v31, 16, v24
	v_fmac_f32_e32 v27, v29, v29
	v_and_b32_e32 v32, 0xffff0000, v24
	v_fmac_f32_e32 v27, v31, v31
	v_lshlrev_b32_e32 v33, 16, v25
	v_fmac_f32_e32 v27, v32, v32
	v_and_b32_e32 v34, 0xffff0000, v25
	v_fmac_f32_e32 v27, v33, v33
	v_fmac_f32_e32 v27, v34, v34
	flat_store_dwordx4 v[20:21], v[22:25] offset:176
	v_add_f32_e32 v30, v30, v27
	ds_read_b128 v[22:25], v1 offset:128
	ds_read_b128 v[26:29], v1 offset:144
	v_lshlrev_b32_e32 v31, 16, v14
	v_and_b32_e32 v14, 0xffff0000, v14
	s_waitcnt lgkmcnt(0)
	v_add_f32_e32 v22, v22, v31
	v_add_f32_e32 v14, v23, v14
	v_cvt_pk_bf16_f32 v14, v22, v14
	v_lshlrev_b32_e32 v22, 16, v15
	v_and_b32_e32 v15, 0xffff0000, v15
	v_add_f32_e32 v22, v24, v22
	v_add_f32_e32 v15, v25, v15
	v_cvt_pk_bf16_f32 v15, v22, v15
	v_lshlrev_b32_e32 v22, 16, v16
	v_and_b32_e32 v16, 0xffff0000, v16
	v_add_f32_e32 v22, v26, v22
	v_add_f32_e32 v16, v27, v16
	v_cvt_pk_bf16_f32 v16, v22, v16
	v_lshlrev_b32_e32 v22, 16, v17
	v_and_b32_e32 v17, 0xffff0000, v17
	v_add_f32_e32 v22, v28, v22
	v_add_f32_e32 v17, v29, v17
	v_and_b32_e32 v23, 0xffff0000, v14
	v_cvt_pk_bf16_f32 v17, v22, v17
	v_lshlrev_b32_e32 v22, 16, v14
	v_mul_f32_e32 v23, v23, v23
	v_lshlrev_b32_e32 v24, 16, v15
	v_fmac_f32_e32 v23, v22, v22
	v_and_b32_e32 v25, 0xffff0000, v15
	v_fmac_f32_e32 v23, v24, v24
	v_lshlrev_b32_e32 v26, 16, v16
	v_fmac_f32_e32 v23, v25, v25
	v_and_b32_e32 v27, 0xffff0000, v16
	v_fmac_f32_e32 v23, v26, v26
	v_lshlrev_b32_e32 v28, 16, v17
	v_fmac_f32_e32 v23, v27, v27
	v_and_b32_e32 v29, 0xffff0000, v17
	v_fmac_f32_e32 v23, v28, v28
	v_fmac_f32_e32 v23, v29, v29
	flat_store_dwordx4 v[20:21], v[14:17] offset:192
	v_add_f32_e32 v26, v30, v23
	ds_read_b128 v[14:17], v1 offset:160
	ds_read_b128 v[22:25], v1 offset:176
	v_lshlrev_b32_e32 v27, 16, v10
	v_and_b32_e32 v10, 0xffff0000, v10
	s_waitcnt lgkmcnt(0)
	v_add_f32_e32 v14, v14, v27
	v_add_f32_e32 v10, v15, v10
	v_cvt_pk_bf16_f32 v10, v14, v10
	v_lshlrev_b32_e32 v14, 16, v11
	v_and_b32_e32 v11, 0xffff0000, v11
	v_add_f32_e32 v14, v16, v14
	v_add_f32_e32 v11, v17, v11
	v_cvt_pk_bf16_f32 v11, v14, v11
	v_lshlrev_b32_e32 v14, 16, v12
	v_and_b32_e32 v12, 0xffff0000, v12
	v_add_f32_e32 v14, v22, v14
	v_add_f32_e32 v12, v23, v12
	v_cvt_pk_bf16_f32 v12, v14, v12
	v_lshlrev_b32_e32 v14, 16, v13
	v_and_b32_e32 v13, 0xffff0000, v13
	v_add_f32_e32 v14, v24, v14
	v_add_f32_e32 v13, v25, v13
	v_and_b32_e32 v15, 0xffff0000, v10
	v_cvt_pk_bf16_f32 v13, v14, v13
	v_lshlrev_b32_e32 v14, 16, v10
	v_mul_f32_e32 v15, v15, v15
	v_lshlrev_b32_e32 v16, 16, v11
	v_fmac_f32_e32 v15, v14, v14
	v_and_b32_e32 v17, 0xffff0000, v11
	v_fmac_f32_e32 v15, v16, v16
	v_lshlrev_b32_e32 v22, 16, v12
	v_fmac_f32_e32 v15, v17, v17
	v_and_b32_e32 v23, 0xffff0000, v12
	v_fmac_f32_e32 v15, v22, v22
	v_lshlrev_b32_e32 v24, 16, v13
	v_fmac_f32_e32 v15, v23, v23
	v_and_b32_e32 v25, 0xffff0000, v13
	v_fmac_f32_e32 v15, v24, v24
	v_fmac_f32_e32 v15, v25, v25
	flat_store_dwordx4 v[20:21], v[10:13] offset:208
	v_add_f32_e32 v22, v26, v15
	ds_read_b128 v[10:13], v1 offset:192
	ds_read_b128 v[14:17], v1 offset:208
	v_lshlrev_b32_e32 v23, 16, v6
	v_and_b32_e32 v6, 0xffff0000, v6
	s_waitcnt lgkmcnt(0)
	v_add_f32_e32 v10, v10, v23
	v_add_f32_e32 v6, v11, v6
	v_cvt_pk_bf16_f32 v6, v10, v6
	v_lshlrev_b32_e32 v10, 16, v7
	v_and_b32_e32 v7, 0xffff0000, v7
	v_add_f32_e32 v10, v12, v10
	v_add_f32_e32 v7, v13, v7
	v_cvt_pk_bf16_f32 v7, v10, v7
	v_lshlrev_b32_e32 v10, 16, v8
	v_and_b32_e32 v8, 0xffff0000, v8
	v_add_f32_e32 v10, v14, v10
	v_add_f32_e32 v8, v15, v8
	v_cvt_pk_bf16_f32 v8, v10, v8
	v_lshlrev_b32_e32 v10, 16, v9
	v_and_b32_e32 v9, 0xffff0000, v9
	v_add_f32_e32 v10, v16, v10
	v_add_f32_e32 v9, v17, v9
	v_and_b32_e32 v11, 0xffff0000, v6
	v_cvt_pk_bf16_f32 v9, v10, v9
	v_lshlrev_b32_e32 v10, 16, v6
	v_mul_f32_e32 v11, v11, v11
	v_lshlrev_b32_e32 v12, 16, v7
	v_fmac_f32_e32 v11, v10, v10
	v_and_b32_e32 v13, 0xffff0000, v7
	v_fmac_f32_e32 v11, v12, v12
	v_lshlrev_b32_e32 v14, 16, v8
	v_fmac_f32_e32 v11, v13, v13
	v_and_b32_e32 v15, 0xffff0000, v8
	v_fmac_f32_e32 v11, v14, v14
	v_lshlrev_b32_e32 v16, 16, v9
	v_fmac_f32_e32 v11, v15, v15
	v_and_b32_e32 v17, 0xffff0000, v9
	v_fmac_f32_e32 v11, v16, v16
	v_fmac_f32_e32 v11, v17, v17
	flat_store_dwordx4 v[20:21], v[6:9] offset:224
	v_add_f32_e32 v14, v22, v11
	ds_read_b128 v[6:9], v1 offset:224
	ds_read_b128 v[10:13], v1 offset:240
	v_lshlrev_b32_e32 v1, 16, v2
	v_and_b32_e32 v2, 0xffff0000, v2
	s_waitcnt lgkmcnt(0)
	v_add_f32_e32 v1, v6, v1
	v_add_f32_e32 v2, v7, v2
	v_cvt_pk_bf16_f32 v2, v1, v2
	v_lshlrev_b32_e32 v1, 16, v3
	v_and_b32_e32 v3, 0xffff0000, v3
	v_add_f32_e32 v1, v8, v1
	v_add_f32_e32 v3, v9, v3
	v_cvt_pk_bf16_f32 v3, v1, v3
	v_lshlrev_b32_e32 v1, 16, v4
	v_and_b32_e32 v4, 0xffff0000, v4
	v_add_f32_e32 v1, v10, v1
	v_add_f32_e32 v4, v11, v4
	v_cvt_pk_bf16_f32 v4, v1, v4
	v_lshlrev_b32_e32 v1, 16, v5
	v_and_b32_e32 v5, 0xffff0000, v5
	v_add_f32_e32 v1, v12, v1
	v_add_f32_e32 v5, v13, v5
	v_and_b32_e32 v6, 0xffff0000, v2
	v_cvt_pk_bf16_f32 v5, v1, v5
	v_lshlrev_b32_e32 v1, 16, v2
	v_mul_f32_e32 v6, v6, v6
	v_lshlrev_b32_e32 v7, 16, v3
	v_fmac_f32_e32 v6, v1, v1
	v_and_b32_e32 v8, 0xffff0000, v3
	v_fmac_f32_e32 v6, v7, v7
	v_lshlrev_b32_e32 v9, 16, v4
	v_fmac_f32_e32 v6, v8, v8
	v_and_b32_e32 v10, 0xffff0000, v4
	v_fmac_f32_e32 v6, v9, v9
	v_lshlrev_b32_e32 v11, 16, v5
	v_fmac_f32_e32 v6, v10, v10
	v_and_b32_e32 v12, 0xffff0000, v5
	v_fmac_f32_e32 v6, v11, v11
	flat_store_dwordx4 v[20:21], v[2:5] offset:240
	v_fmac_f32_e32 v6, v12, v12
	v_add_f32_e32 v1, v14, v6
	v_lshlrev_b64 v[2:3], 6, v[18:19]
	v_lshl_add_u64 v[2:3], s[6:7], 0, v[2:3]
	v_lshl_add_u64 v[2:3], v[2:3], 0, s[18:19]
	flat_store_dword v[2:3], v1 offset:4
	s_branch .LBB0_342

.LBB0_373:
	v_mov_b32_e32 v1, v170
	s_barrier
	s_lshl_b32 s46, s41, 1
	v_ashrrev_i32_e32 v2, 7, v1
	v_add_u32_e32 v3, s46, v2
	v_cmp_lt_i32_e32 vcc, s91, v3
	s_and_saveexec_b64 s[4:5], vcc
	s_xor_b64 s[22:23], exec, s[4:5]
	v_add_u32_e32 v3, 0xfffffef0, v3
	v_mul_hi_u32 v2, v3, s96
	v_lshrrev_b32_e32 v4, 3, v2
	v_add_u32_e32 v2, 16, v4
	v_lshl_add_u32 v4, v4, 5, v4
	v_sub_u32_e32 v6, v3, v4
	s_andn2_saveexec_b64 s[22:23], s[22:23]
	v_mul_hi_i32 v2, v3, s97
	v_lshrrev_b32_e32 v4, 31, v2
	v_ashrrev_i32_e32 v2, 3, v2
	v_add_u32_e32 v2, v2, v4
	v_lshl_add_u32 v4, v2, 4, v2
	v_sub_u32_e32 v6, v3, v4
	s_or_b64 exec, exec, s[22:23]
	v_cmp_lt_i32_e32 vcc, 15, v2
	s_and_saveexec_b64 s[4:5], vcc
	s_xor_b64 s[4:5], exec, s[4:5]
	v_add_u32_e32 v2, -16, v2
	v_mov_b32_e32 v3, v0
	v_lshlrev_b64 v[2:3], 12, v[2:3]
	v_lshl_add_u64 v[4:5], v[2:3], 0, s[42:43]
	s_andn2_saveexec_b64 s[22:23], s[4:5]
	v_ashrrev_i32_e32 v3, 31, v2
	v_lshlrev_b64 v[4:5], 11, v[2:3]
	s_or_b64 exec, exec, s[22:23]
	v_mad_u64_u32 v[2:3], s[4:5], v6, s54, -1
	v_ashrrev_i32_e32 v3, 31, v2
	v_and_b32_e32 v6, 0x7f, v1
	v_mov_b32_e32 v7, v0
	v_lshl_add_u64 v[2:3], v[2:3], 0, v[6:7]
	v_lshl_add_u64 v[2:3], v[2:3], 0, v[4:5]
	v_cmp_lt_i64_e32 vcc, 0, v[2:3]
	s_nop 1
	v_cndmask_b32_e32 v3, 0, v3, vcc
	v_cndmask_b32_e32 v2, 0, v2, vcc
	v_cmp_gt_i64_e32 vcc, s[44:45], v[2:3]
	v_mov_b32_e32 v3, v0
	s_nop 0
	v_cndmask_b32_e32 v2, v174, v2, vcc
	v_lshlrev_b32_e32 v2, 6, v2
	v_lshl_add_u64 v[14:15], s[8:9], 0, v[2:3]
	flat_load_dwordx4 v[2:5], v[14:15]
	flat_load_dwordx4 v[6:9], v[14:15] offset:16
	flat_load_dwordx4 v[10:13], v[14:15] offset:32
	s_waitcnt vmcnt(0) lgkmcnt(0)
	v_mov_b32_e32 v16, v3
	v_mov_b32_e32 v17, v4
	v_mov_b32_e32 v3, v5
	v_mov_b32_e32 v18, v7
	v_mov_b32_e32 v19, v8
	v_pk_add_f32 v[2:3], v[16:17], v[2:3]
	v_mov_b32_e32 v7, v9
	v_pk_add_f32 v[16:17], v[2:3], v[2:3] op_sel:[0,1] op_sel_hi:[1,0]
	v_pk_add_f32 v[2:3], v[18:19], v[6:7]
	s_nop 0
	v_pk_add_f32 v[6:7], v[2:3], v[2:3] op_sel:[0,1] op_sel_hi:[1,0]
	v_mov_b32_e32 v2, v11
	v_pk_add_f32 v[8:9], v[10:11], v[2:3]
	v_mov_b32_e32 v2, v13
	v_pk_add_f32 v[10:11], v[12:13], v[2:3]
	flat_load_dwordx4 v[2:5], v[14:15] offset:48
	s_waitcnt vmcnt(0) lgkmcnt(0)
	v_mov_b32_e32 v17, v2
	v_mov_b32_e32 v7, v3
	v_mov_b32_e32 v9, v4
	v_mov_b32_e32 v11, v5
	v_pk_add_f32 v[2:3], v[16:17], v[6:7]
	v_pk_add_f32 v[4:5], v[8:9], v[10:11]
	v_ashrrev_i32_e32 v6, 6, v1
	v_pk_add_f32 v[2:3], v[2:3], v[4:5]
	s_nop 0
	v_add_f32_e32 v2, v2, v3
	v_fmamk_f32 v2, v2, 0x3a800000, v172
	v_cmp_gt_f32_e32 vcc, s58, v2
	v_mul_f32_e32 v3, 0x4b800000, v2
	s_nop 0
	v_cndmask_b32_e32 v2, v2, v3, vcc
	v_rsq_f32_e32 v2, v2
	s_nop 0
	v_mul_f32_e32 v3, 0x45800000, v2
	v_cndmask_b32_e32 v2, v2, v3, vcc
	v_lshl_add_u32 v3, v1, 2, v175
	ds_write_b32 v3, v2
	v_and_b32_e32 v3, 63, v1
	v_cmp_lt_i32_e32 vcc, 2, v6
	s_and_saveexec_b64 s[4:5], vcc
	s_xor_b64 s[4:5], exec, s[4:5]
	v_lshl_or_b32 v2, s20, 6, v3
	s_or_saveexec_b64 s[22:23], s[4:5]
	v_mov_b64_e32 v[4:5], s[14:15]
	s_xor_b64 exec, exec, s[22:23]
	s_movk_i32 s4, 0xac0
	v_mul_lo_u32 v2, v6, s4
	v_lshl_add_u32 v2, s20, 6, v2
	v_or_b32_e32 v2, v2, v3
	v_mov_b64_e32 v[4:5], s[12:13]
	s_or_b64 exec, exec, s[22:23]
	v_ashrrev_i32_e32 v3, 31, v2
	v_lshl_add_u64 v[2:3], v[2:3], 2, v[4:5]
	flat_load_dword v2, v[2:3]
	v_lshl_add_u32 v3, v1, 2, v254
	v_mov_b32_e32 v1, v170
	s_waitcnt vmcnt(0) lgkmcnt(0)
	ds_write_b32 v3, v2
	s_nop 0
	v_ashrrev_i32_e32 v2, 9, v1
	v_add_u32_e32 v2, s46, v2
	v_cmp_lt_i32_e32 vcc, s91, v2
	s_and_saveexec_b64 s[4:5], vcc
	s_xor_b64 s[22:23], exec, s[4:5]
	v_add_u32_e32 v2, 0xfffffef0, v2
	v_mul_hi_u32 v3, v2, s96
	v_lshrrev_b32_e32 v3, 3, v3
	v_add_u32_e32 v4, 16, v3
	v_lshl_add_u32 v3, v3, 5, v3
	v_sub_u32_e32 v13, v2, v3
	s_andn2_saveexec_b64 s[22:23], s[22:23]
	v_mul_hi_i32 v3, v2, s97
	v_lshrrev_b32_e32 v4, 31, v3
	v_ashrrev_i32_e32 v3, 3, v3
	v_add_u32_e32 v4, v3, v4
	v_lshl_add_u32 v3, v4, 4, v4
	v_sub_u32_e32 v13, v2, v3
	s_or_b64 exec, exec, s[22:23]
	v_cmp_lt_i32_e32 vcc, 15, v4
	s_and_saveexec_b64 s[4:5], vcc
	s_xor_b64 s[4:5], exec, s[4:5]
	v_add_u32_e32 v2, -16, v4
	v_mov_b32_e32 v3, v0
	v_lshlrev_b64 v[2:3], 12, v[2:3]
	v_lshl_add_u64 v[2:3], v[2:3], 0, s[42:43]
	s_andn2_saveexec_b64 s[22:23], s[4:5]
	v_ashrrev_i32_e32 v5, 31, v4
	v_lshlrev_b64 v[2:3], 11, v[4:5]
	s_or_b64 exec, exec, s[22:23]
	v_lshlrev_b32_e32 v142, 4, v1
	v_add_u32_e32 v12, 0x1000, v142
	v_ashrrev_i32_e32 v4, 13, v12
	v_add_u32_e32 v4, s46, v4
	v_cmp_lt_i32_e32 vcc, s91, v4
	s_and_saveexec_b64 s[4:5], vcc
	s_xor_b64 s[4:5], exec, s[4:5]
	v_add_u32_e32 v4, 0xfffffef0, v4
	v_mul_hi_u32 v5, v4, s96
	v_lshrrev_b32_e32 v5, 3, v5
	v_add_u32_e32 v6, 16, v5
	v_lshl_add_u32 v5, v5, 5, v5
	v_sub_u32_e32 v15, v4, v5
	s_andn2_saveexec_b64 s[22:23], s[4:5]
	v_mul_hi_i32 v5, v4, s97
	v_lshrrev_b32_e32 v6, 31, v5
	v_ashrrev_i32_e32 v5, 3, v5
	v_add_u32_e32 v6, v5, v6
	v_lshl_add_u32 v5, v6, 4, v6
	v_sub_u32_e32 v15, v4, v5
	s_or_b64 exec, exec, s[22:23]
	v_cmp_lt_i32_e32 vcc, 15, v6
	s_and_saveexec_b64 s[4:5], vcc
	s_xor_b64 s[4:5], exec, s[4:5]
	v_add_u32_e32 v4, -16, v6
	v_mov_b32_e32 v5, v0
	v_lshlrev_b64 v[4:5], 12, v[4:5]
	v_lshl_add_u64 v[4:5], v[4:5], 0, s[42:43]
	s_andn2_saveexec_b64 s[4:5], s[4:5]
	v_ashrrev_i32_e32 v7, 31, v6
	v_lshlrev_b64 v[4:5], 11, v[6:7]
	s_or_b64 exec, exec, s[4:5]
	v_add_u32_e32 v14, 0x2000, v142
	v_ashrrev_i32_e32 v6, 13, v14
	v_add_u32_e32 v6, s46, v6
	v_cmp_lt_i32_e32 vcc, s91, v6
	s_and_saveexec_b64 s[4:5], vcc
	s_xor_b64 s[4:5], exec, s[4:5]
	v_add_u32_e32 v6, 0xfffffef0, v6
	v_mul_hi_u32 v7, v6, s96
	v_lshrrev_b32_e32 v7, 3, v7
	v_add_u32_e32 v8, 16, v7
	v_lshl_add_u32 v7, v7, 5, v7
	v_sub_u32_e32 v17, v6, v7
	s_andn2_saveexec_b64 s[22:23], s[4:5]
	v_mul_hi_i32 v7, v6, s97
	v_lshrrev_b32_e32 v8, 31, v7
	v_ashrrev_i32_e32 v7, 3, v7
	v_add_u32_e32 v8, v7, v8
	v_lshl_add_u32 v7, v8, 4, v8
	v_sub_u32_e32 v17, v6, v7
	s_or_b64 exec, exec, s[22:23]
	v_cmp_lt_i32_e32 vcc, 15, v8
	s_and_saveexec_b64 s[4:5], vcc
	s_xor_b64 s[4:5], exec, s[4:5]
	v_add_u32_e32 v6, -16, v8
	v_mov_b32_e32 v7, v0
	v_lshlrev_b64 v[6:7], 12, v[6:7]
	v_lshl_add_u64 v[6:7], v[6:7], 0, s[42:43]
	s_andn2_saveexec_b64 s[4:5], s[4:5]
	v_ashrrev_i32_e32 v9, 31, v8
	v_lshlrev_b64 v[6:7], 11, v[8:9]
	s_or_b64 exec, exec, s[4:5]
	v_add_u32_e32 v16, 0x3000, v142
	v_ashrrev_i32_e32 v8, 13, v16
	v_add_u32_e32 v8, s46, v8
	v_cmp_lt_i32_e32 vcc, s91, v8
	s_and_saveexec_b64 s[4:5], vcc
	s_xor_b64 s[4:5], exec, s[4:5]
	v_add_u32_e32 v8, 0xfffffef0, v8
	v_mul_hi_u32 v9, v8, s96
	v_lshrrev_b32_e32 v9, 3, v9
	v_add_u32_e32 v10, 16, v9
	v_lshl_add_u32 v9, v9, 5, v9
	v_sub_u32_e32 v18, v8, v9
	s_andn2_saveexec_b64 s[22:23], s[4:5]
	v_mul_hi_i32 v9, v8, s97
	v_lshrrev_b32_e32 v10, 31, v9
	v_ashrrev_i32_e32 v9, 3, v9
	v_add_u32_e32 v10, v9, v10
	v_lshl_add_u32 v9, v10, 4, v10
	v_sub_u32_e32 v18, v8, v9
	s_or_b64 exec, exec, s[22:23]
	v_cmp_lt_i32_e32 vcc, 15, v10
	s_and_saveexec_b64 s[4:5], vcc
	s_xor_b64 s[4:5], exec, s[4:5]
	v_add_u32_e32 v8, -16, v10
	v_mov_b32_e32 v9, v0
	v_lshlrev_b64 v[8:9], 12, v[8:9]
	v_lshl_add_u64 v[8:9], v[8:9], 0, s[42:43]
	s_andn2_saveexec_b64 s[4:5], s[4:5]
	v_ashrrev_i32_e32 v11, 31, v10
	v_lshlrev_b64 v[8:9], 11, v[10:11]
	s_or_b64 exec, exec, s[4:5]
	v_mad_u64_u32 v[24:25], s[4:5], v17, s54, -1
	v_bfe_u32 v22, v142, 6, 7
	v_mov_b32_e32 v23, v0
	v_ashrrev_i32_e32 v25, 31, v24
	v_lshl_add_u64 v[24:25], v[24:25], 0, v[22:23]
	v_lshl_add_u64 v[6:7], v[24:25], 0, v[6:7]
	v_cmp_lt_i64_e32 vcc, 0, v[6:7]
	v_and_b32_e32 v44, 32, v1
	v_bitop3_b32 v10, v142, v44, 48 bitop3:0x6c
	v_cndmask_b32_e32 v7, 0, v7, vcc
	v_cndmask_b32_e32 v6, 0, v6, vcc
	v_cmp_gt_i64_e32 vcc, s[44:45], v[6:7]
	v_mov_b32_e32 v11, v0
	v_lshl_add_u64 v[20:21], s[6:7], 0, v[10:11]
	v_cndmask_b32_e32 v6, v174, v6, vcc
	v_lshlrev_b32_e32 v6, 11, v6
	v_mov_b32_e32 v7, v0
	v_bfe_u32 v19, v142, 6, 4
	v_lshl_add_u64 v[24:25], v[20:21], 0, v[6:7]
	v_lshrrev_b32_e32 v7, 6, v16
	v_and_or_b32 v26, v7, s82, v19
	v_lshrrev_b32_e32 v7, 6, v12
	v_mad_u64_u32 v[30:31], s[24:25], v15, s54, -1
	v_and_or_b32 v28, v7, s82, v19
	v_ashrrev_i32_e32 v31, 31, v30
	v_mov_b32_e32 v29, v0
	v_lshl_add_u64 v[28:29], v[30:31], 0, v[28:29]
	v_lshl_add_u64 v[4:5], v[28:29], 0, v[4:5]
	v_mad_u64_u32 v[30:31], s[24:25], v13, s54, -1
	v_cmp_lt_i64_e32 vcc, 0, v[4:5]
	v_ashrrev_i32_e32 v31, 31, v30
	v_lshl_add_u64 v[22:23], v[30:31], 0, v[22:23]
	v_cndmask_b32_e32 v5, 0, v5, vcc
	v_cndmask_b32_e32 v4, 0, v4, vcc
	v_cmp_gt_i64_e32 vcc, s[44:45], v[4:5]
	v_lshl_add_u64 v[2:3], v[22:23], 0, v[2:3]
	v_mad_u64_u32 v[18:19], s[66:67], v18, s54, -1
	v_cndmask_b32_e32 v4, v174, v4, vcc
	v_cmp_lt_i64_e32 vcc, 0, v[2:3]
	v_ashrrev_i32_e32 v19, 31, v18
	v_mov_b32_e32 v27, v0
	v_cndmask_b32_e32 v3, 0, v3, vcc
	v_cndmask_b32_e32 v2, 0, v2, vcc
	v_lshl_add_u64 v[18:19], v[18:19], 0, v[26:27]
	v_cmp_gt_i64_e32 vcc, s[44:45], v[2:3]
	v_lshl_add_u64 v[8:9], v[18:19], 0, v[8:9]
	v_mov_b32_e32 v3, v0
	v_cndmask_b32_e32 v2, v174, v2, vcc
	v_cmp_lt_i64_e32 vcc, 0, v[8:9]
	v_lshlrev_b32_e32 v2, 11, v2
	v_lshl_add_u64 v[22:23], v[20:21], 0, v[2:3]
	v_cndmask_b32_e32 v9, 0, v9, vcc
	v_cndmask_b32_e32 v8, 0, v8, vcc
	v_cmp_gt_i64_e32 vcc, s[44:45], v[8:9]
	s_ashr_i32 s21, s20, 31
	v_readfirstlane_b32 s5, v142
	v_cndmask_b32_e32 v3, v174, v8, vcc
	v_lshrrev_b32_e32 v32, 6, v142
	v_lshlrev_b32_e32 v4, 11, v4
	v_mov_b32_e32 v5, v0
	s_lshl_b64 s[24:25], s[20:21], 18
	v_lshlrev_b32_e32 v8, 11, v3
	v_mov_b32_e32 v9, v0
	v_ashrrev_i32_e32 v3, 2, v1
	s_waitcnt vmcnt(0)
	s_mov_b32 m0, s5
	v_readfirstlane_b32 s5, v12
	v_lshl_add_u64 v[28:29], v[20:21], 0, v[4:5]
	s_add_u32 s64, s26, s24
	v_lshl_add_u64 v[18:19], v[20:21], 0, v[8:9]
	v_bfi_b32 v20, 15, v32, v3
	v_ashrrev_i32_e32 v3, 6, v12
	s_mov_b32 m0, s5
	v_readfirstlane_b32 s5, v14
	s_addc_u32 s65, s27, s25
	v_ashrrev_i32_e32 v21, 31, v20
	v_bfi_b32 v30, -16, v3, v32
	v_add_u32_e32 v15, 0x4000, v142
	s_mov_b32 m0, s5
	v_readfirstlane_b32 s5, v16
	v_lshl_add_u64 v[10:11], s[64:65], 0, v[10:11]
	v_lshlrev_b64 v[20:21], 11, v[20:21]
	v_ashrrev_i32_e32 v31, 31, v30
	v_add_u32_e32 v17, 0x5000, v142
	s_mov_b32 m0, s5
	v_readfirstlane_b32 s5, v15
	v_lshl_add_u64 v[26:27], v[10:11], 0, v[20:21]
	v_lshlrev_b64 v[30:31], 11, v[30:31]
	v_add_u32_e32 v46, 0x6000, v142
	s_mov_b32 m0, s5
	v_readfirstlane_b32 s5, v17
	v_lshl_add_u64 v[10:11], v[10:11], 0, v[30:31]
	v_add_u32_e32 v47, 0x7000, v142
	s_mov_b32 m0, s5
	v_readfirstlane_b32 s5, v46
	v_lshl_add_u64 v[32:33], v[22:23], 0, 64
	v_add_u32_e32 v48, 0x8000, v142
	s_mov_b32 m0, s5
	v_readfirstlane_b32 s5, v47
	v_add_u32_e32 v49, 0x9000, v142
	v_lshl_add_u64 v[34:35], v[28:29], 0, 64
	s_mov_b32 m0, s5
	v_readfirstlane_b32 s5, v48
	v_add_u32_e32 v50, 0xa000, v142
	v_lshl_add_u64 v[36:37], v[24:25], 0, 64
	s_mov_b32 m0, s5
	v_readfirstlane_b32 s5, v49
	v_add_u32_e32 v51, 0xb000, v142
	v_lshl_add_u64 v[38:39], v[18:19], 0, 64
	s_mov_b32 m0, s5
	v_readfirstlane_b32 s5, v50
	v_lshl_add_u64 v[40:41], v[26:27], 0, 64
	s_mov_b32 m0, s5
	v_readfirstlane_b32 s5, v51
	v_lshl_add_u64 v[42:43], v[10:11], 0, 64
	s_mov_b32 m0, s5
	v_and_b32_e32 v45, 48, v142
	v_and_b32_e32 v143, 15, v1
	v_bfe_u32 v144, v1, 4, 2
	v_lshlrev_b32_e32 v5, 6, v1
	v_lshlrev_b32_e32 v13, 2, v1
	v_lshl_add_u64 v[10:11], s[24:25], 0, v[30:31]
	v_lshlrev_b32_e32 v3, 4, v144
	v_and_b32_e32 v7, 0x3c0, v5
	v_lshlrev_b32_e32 v9, 6, v143
	v_and_b32_e32 v13, 32, v13
	v_bitop3_b32 v10, v10, v45, v44 bitop3:0xf6
	v_bitop3_b32 v149, v3, v13, v7 bitop3:0x36
	v_bitop3_b32 v145, v3, v13, v9 bitop3:0x36
	v_lshl_add_u64 v[130:131], s[16:17], 0, v[10:11]
	v_lshl_add_u64 v[10:11], s[24:25], 0, v[20:21]
	v_bitop3_b32 v2, v2, v45, v44 bitop3:0xf6
	v_mov_b32_e32 v3, v0
	v_and_b32_e32 v147, 0xfffff000, v5
	v_bitop3_b32 v10, v10, v45, v44 bitop3:0xf6
	v_bitop3_b32 v8, v8, v45, v44 bitop3:0xf6
	v_mov_b32_e32 v9, v0
	v_bitop3_b32 v6, v6, v45, v44 bitop3:0xf6
	v_mov_b32_e32 v7, v0
	v_bitop3_b32 v4, v4, v45, v44 bitop3:0xf6
	v_mov_b32_e32 v5, v0
	v_lshl_add_u64 v[140:141], s[18:19], 0, v[2:3]
	v_mov_b32_e32 v2, 0
	s_mov_b64 s[22:23], 0
	s_mov_b32 s4, 0
	v_lshl_add_u64 v[132:133], s[16:17], 0, v[10:11]
	v_lshl_add_u64 v[134:135], s[18:19], 0, v[8:9]
	v_lshl_add_u64 v[136:137], s[18:19], 0, v[6:7]
	v_lshl_add_u64 v[138:139], s[18:19], 0, v[4:5]
	v_mov_b32_e32 v3, v2
	v_mov_b32_e32 v4, v2
	v_mov_b32_e32 v5, v2
	v_mov_b32_e32 v6, v2
	v_mov_b32_e32 v7, v2
	v_mov_b32_e32 v8, v2
	v_mov_b32_e32 v9, v2
	v_mov_b32_e32 v10, v2
	v_mov_b32_e32 v11, v2
	v_mov_b32_e32 v12, v2
	v_mov_b32_e32 v13, v2
	v_mov_b32_e32 v18, v2
	v_mov_b32_e32 v19, v2
	v_mov_b32_e32 v20, v2
	v_mov_b32_e32 v21, v2
	v_mov_b32_e32 v26, v2
	v_mov_b32_e32 v27, v2
	v_mov_b32_e32 v28, v2
	v_mov_b32_e32 v29, v2
	v_mov_b32_e32 v38, v2
	v_mov_b32_e32 v39, v2
	v_mov_b32_e32 v40, v2
	v_mov_b32_e32 v41, v2
	v_mov_b32_e32 v46, v2
	v_mov_b32_e32 v47, v2
	v_mov_b32_e32 v48, v2
	v_mov_b32_e32 v49, v2
	v_mov_b32_e32 v62, v2
	v_mov_b32_e32 v63, v2
	v_mov_b32_e32 v64, v2
	v_mov_b32_e32 v65, v2
	v_mov_b32_e32 v14, v2
	v_mov_b32_e32 v15, v2
	v_mov_b32_e32 v16, v2
	v_mov_b32_e32 v17, v2
	v_mov_b32_e32 v22, v2
	v_mov_b32_e32 v23, v2
	v_mov_b32_e32 v24, v2
	v_mov_b32_e32 v25, v2
	v_mov_b32_e32 v30, v2
	v_mov_b32_e32 v31, v2
	v_mov_b32_e32 v32, v2
	v_mov_b32_e32 v33, v2
	v_mov_b32_e32 v42, v2
	v_mov_b32_e32 v43, v2
	v_mov_b32_e32 v44, v2
	v_mov_b32_e32 v45, v2
	v_mov_b32_e32 v54, v2
	v_mov_b32_e32 v55, v2
	v_mov_b32_e32 v56, v2
	v_mov_b32_e32 v57, v2
	v_mov_b32_e32 v70, v2
	v_mov_b32_e32 v71, v2
	v_mov_b32_e32 v72, v2
	v_mov_b32_e32 v73, v2
	v_mov_b32_e32 v78, v2
	v_mov_b32_e32 v79, v2
	v_mov_b32_e32 v80, v2
	v_mov_b32_e32 v81, v2
	v_mov_b32_e32 v94, v2
	v_mov_b32_e32 v95, v2
	v_mov_b32_e32 v96, v2
	v_mov_b32_e32 v97, v2
	v_mov_b32_e32 v34, v2
	v_mov_b32_e32 v35, v2
	v_mov_b32_e32 v36, v2
	v_mov_b32_e32 v37, v2
	v_mov_b32_e32 v50, v2
	v_mov_b32_e32 v51, v2
	v_mov_b32_e32 v52, v2
	v_mov_b32_e32 v53, v2
	v_mov_b32_e32 v58, v2
	v_mov_b32_e32 v59, v2
	v_mov_b32_e32 v60, v2
	v_mov_b32_e32 v61, v2
	v_mov_b32_e32 v74, v2
	v_mov_b32_e32 v75, v2
	v_mov_b32_e32 v76, v2
	v_mov_b32_e32 v77, v2
	v_mov_b32_e32 v86, v2
	v_mov_b32_e32 v87, v2
	v_mov_b32_e32 v88, v2
	v_mov_b32_e32 v89, v2
	v_mov_b32_e32 v98, v2
	v_mov_b32_e32 v99, v2
	v_mov_b32_e32 v100, v2
	v_mov_b32_e32 v101, v2
	v_mov_b32_e32 v106, v2
	v_mov_b32_e32 v107, v2
	v_mov_b32_e32 v108, v2
	v_mov_b32_e32 v109, v2
	v_mov_b32_e32 v114, v2
	v_mov_b32_e32 v115, v2
	v_mov_b32_e32 v116, v2
	v_mov_b32_e32 v117, v2
	v_mov_b32_e32 v66, v2
	v_mov_b32_e32 v67, v2
	v_mov_b32_e32 v68, v2
	v_mov_b32_e32 v69, v2
	v_mov_b32_e32 v82, v2
	v_mov_b32_e32 v83, v2
	v_mov_b32_e32 v84, v2
	v_mov_b32_e32 v85, v2
	v_mov_b32_e32 v90, v2
	v_mov_b32_e32 v91, v2
	v_mov_b32_e32 v92, v2
	v_mov_b32_e32 v93, v2
	v_mov_b32_e32 v102, v2
	v_mov_b32_e32 v103, v2
	v_mov_b32_e32 v104, v2
	v_mov_b32_e32 v105, v2
	v_mov_b32_e32 v110, v2
	v_mov_b32_e32 v111, v2
	v_mov_b32_e32 v112, v2
	v_mov_b32_e32 v113, v2
	v_mov_b32_e32 v118, v2
	v_mov_b32_e32 v119, v2
	v_mov_b32_e32 v120, v2
	v_mov_b32_e32 v121, v2
	v_mov_b32_e32 v122, v2
	v_mov_b32_e32 v123, v2
	v_mov_b32_e32 v124, v2
	v_mov_b32_e32 v125, v2
	v_mov_b32_e32 v126, v2
	v_mov_b32_e32 v127, v2
	v_mov_b32_e32 v128, v2
	v_mov_b32_e32 v129, v2
	v_and_b32_e32 v154, 63, v170
	v_lshrrev_b32_e32 v155, 3, v154
	v_and_b32_e32 v156, 7, v154
	v_xor_b32_e32 v156, v156, v155
	v_lshrrev_b32_e32 v157, 6, v170
	v_lshlrev_b32_e32 v231, 4, v156
	v_lshrrev_b32_e32 v159, 1, v157
	v_add_u32_e32 v159, s46, v159
	v_mul_u32_u24_e32 v160, 0xf10, v159
	v_lshrrev_b32_e32 v160, 16, v160
	v_mul_u32_u24_e32 v161, 17, v160
	v_sub_u32_e32 v161, v159, v161
	v_lshlrev_b32_e32 v160, 11, v160
	v_mul_u32_u24_e32 v161, 0x7e, v161
	v_add_u32_e32 v160, v160, v161
	v_add_u32_e32 v161, 0xfffffef0, v159
	v_mul_u32_u24_e32 v162, 0x7c2, v161
	v_lshrrev_b32_e32 v162, 16, v162
	v_mul_u32_u24_e32 v224, 33, v162
	v_sub_u32_e32 v161, v161, v224
	v_lshlrev_b32_e32 v162, 12, v162
	v_mul_u32_u24_e32 v161, 0x7e, v161
	v_add_u32_e32 v161, v162, v161
	v_add_u32_e32 v161, 0x8000, v161
	v_cmp_lt_u32_e32 vcc, 0x10f, v159
	s_nop 1
	v_cndmask_b32_e32 v160, v160, v161, vcc
	v_and_b32_e32 v161, 1, v157
	v_lshl_add_u32 v161, v161, 6, v155
	v_add3_u32 v224, v160, v161, -1
	v_lshl_add_u32 v158, v157, 5, v155
	v_mul_u32_u24_e32 v225, 0x800, v158
	v_lshl_add_u32 v225, v156, 4, v225
	v_and_b32_e32 v155, 15, v154
	v_lshrrev_b32_e32 v156, 4, v154
	v_and_b32_e32 v158, 7, v155
	v_xor_b32_e32 v156, v156, v158
	v_lshlrev_b32_e32 v156, 4, v156
	v_lshl_add_u32 v229, v155, 7, v156
	v_lshl_add_u32 v227, v157, 13, v229
	v_xor_b32_e32 v228, 64, v227
	v_add_u32_e32 v229, 0x8000, v229
	v_xor_b32_e32 v230, 64, v229
	s_mov_b32 s4, s6
	s_mov_b32 s5, s7
	s_mov_b32 s22, s64
	s_mov_b32 s23, s65
	s_mov_b32 s21, 0
	v_readfirstlane_b32 s32, v142
	s_lshl_b32 m0, s32, 3
	v_add_u32_e32 v226, 0, v224
	v_max_i32_e32 v226, 0, v226
	v_min_i32_e32 v226, 0xffff, v226
	v_lshl_add_u32 v226, v226, 11, v231
	global_load_lds_dwordx4 v226, s[4:5]
	s_add_u32 m0, m0, 0x400
	v_add_u32_e32 v226, 8, v224
	v_max_i32_e32 v226, 0, v226
	v_min_i32_e32 v226, 0xffff, v226
	v_lshl_add_u32 v226, v226, 11, v231
	global_load_lds_dwordx4 v226, s[4:5]
	s_add_u32 m0, m0, 0x400
	v_add_u32_e32 v226, 16, v224
	v_max_i32_e32 v226, 0, v226
	v_min_i32_e32 v226, 0xffff, v226
	v_lshl_add_u32 v226, v226, 11, v231
	global_load_lds_dwordx4 v226, s[4:5]
	s_add_u32 m0, m0, 0x400
	v_add_u32_e32 v226, 24, v224
	v_max_i32_e32 v226, 0, v226
	v_min_i32_e32 v226, 0xffff, v226
	v_lshl_add_u32 v226, v226, 11, v231
	global_load_lds_dwordx4 v226, s[4:5]
	s_add_u32 m0, m0, 0x400
	v_add_u32_e32 v226, 32, v224
	v_max_i32_e32 v226, 0, v226
	v_min_i32_e32 v226, 0xffff, v226
	v_lshl_add_u32 v226, v226, 11, v231
	global_load_lds_dwordx4 v226, s[4:5]
	s_add_u32 m0, m0, 0x400
	v_add_u32_e32 v226, 40, v224
	v_max_i32_e32 v226, 0, v226
	v_min_i32_e32 v226, 0xffff, v226
	v_lshl_add_u32 v226, v226, 11, v231
	global_load_lds_dwordx4 v226, s[4:5]
	s_add_u32 m0, m0, 0x400
	v_add_u32_e32 v226, 48, v224
	v_max_i32_e32 v226, 0, v226
	v_min_i32_e32 v226, 0xffff, v226
	v_lshl_add_u32 v226, v226, 11, v231
	global_load_lds_dwordx4 v226, s[4:5]
	s_add_u32 m0, m0, 0x400
	v_add_u32_e32 v226, 56, v224
	v_max_i32_e32 v226, 0, v226
	v_min_i32_e32 v226, 0xffff, v226
	v_lshl_add_u32 v226, v226, 11, v231
	global_load_lds_dwordx4 v226, s[4:5]
	v_readfirstlane_b32 s32, v142
	s_lshl_b32 s32, s32, 2
	s_add_u32 m0, s32, 0x8000
	v_mov_b32_e32 v226, v225
	global_load_lds_dwordx4 v226, s[22:23]
	s_add_u32 m0, m0, 0x400
	v_add_u32_e32 v226, 0x4000, v225
	global_load_lds_dwordx4 v226, s[22:23]
	s_add_u32 m0, m0, 0x400
	v_add_u32_e32 v226, 0x8000, v225
	global_load_lds_dwordx4 v226, s[22:23]
	s_add_u32 m0, m0, 0x400
	v_add_u32_e32 v226, 0xc000, v225
	global_load_lds_dwordx4 v226, s[22:23]
.Lbk64_418:
	s_waitcnt vmcnt(0)
	s_barrier
	ds_read_b128 v[192:195], v227
	ds_read_b128 v[196:199], v228
	ds_read_b128 v[200:203], v227 offset:2048
	ds_read_b128 v[204:207], v228 offset:2048
	ds_read_b128 v[208:211], v227 offset:4096
	ds_read_b128 v[212:215], v228 offset:4096
	ds_read_b128 v[216:219], v227 offset:6144
	ds_read_b128 v[220:223], v228 offset:6144
	s_add_u32 s4, s4, 0x80
	s_addc_u32 s5, s5, 0
	s_add_u32 s22, s22, 0x80
	s_addc_u32 s23, s23, 0
	s_waitcnt lgkmcnt(0)
	s_barrier
	ds_read_b128 v[154:157], v229 offset:0
	ds_read_b128 v[158:161], v230 offset:0
	ds_read_b128 v[162:165], v229 offset:2048
	ds_read_b128 v[166:169], v230 offset:2048
	s_waitcnt lgkmcnt(2)
	v_mfma_f32_16x16x32_bf16 v[126:129], v[192:195], v[154:157], v[126:129]
	v_mfma_f32_16x16x32_bf16 v[114:117], v[200:203], v[154:157], v[114:117]
	v_mfma_f32_16x16x32_bf16 v[94:97], v[208:211], v[154:157], v[94:97]
	v_mfma_f32_16x16x32_bf16 v[62:65], v[216:219], v[154:157], v[62:65]
	v_readfirstlane_b32 s32, v142
	s_lshl_b32 m0, s32, 3
	v_add_u32_e32 v226, 0, v224
	v_max_i32_e32 v226, 0, v226
	v_min_i32_e32 v226, 0xffff, v226
	v_lshl_add_u32 v226, v226, 11, v231
	global_load_lds_dwordx4 v226, s[4:5]
	v_mfma_f32_16x16x32_bf16 v[126:129], v[196:199], v[158:161], v[126:129]
	v_mfma_f32_16x16x32_bf16 v[114:117], v[204:207], v[158:161], v[114:117]
	v_mfma_f32_16x16x32_bf16 v[94:97], v[212:215], v[158:161], v[94:97]
	v_mfma_f32_16x16x32_bf16 v[62:65], v[220:223], v[158:161], v[62:65]
	s_add_u32 m0, m0, 0x400
	v_add_u32_e32 v226, 8, v224
	v_max_i32_e32 v226, 0, v226
	v_min_i32_e32 v226, 0xffff, v226
	v_lshl_add_u32 v226, v226, 11, v231
	global_load_lds_dwordx4 v226, s[4:5]
	ds_read_b128 v[154:157], v229 offset:4096
	ds_read_b128 v[158:161], v230 offset:4096
	s_waitcnt lgkmcnt(2)
	v_mfma_f32_16x16x32_bf16 v[122:125], v[192:195], v[162:165], v[122:125]
	v_mfma_f32_16x16x32_bf16 v[106:109], v[200:203], v[162:165], v[106:109]
	v_mfma_f32_16x16x32_bf16 v[78:81], v[208:211], v[162:165], v[78:81]
	v_mfma_f32_16x16x32_bf16 v[46:49], v[216:219], v[162:165], v[46:49]
	s_add_u32 m0, m0, 0x400
	v_add_u32_e32 v226, 16, v224
	v_max_i32_e32 v226, 0, v226
	v_min_i32_e32 v226, 0xffff, v226
	v_lshl_add_u32 v226, v226, 11, v231
	global_load_lds_dwordx4 v226, s[4:5]
	v_mfma_f32_16x16x32_bf16 v[122:125], v[196:199], v[166:169], v[122:125]
	v_mfma_f32_16x16x32_bf16 v[106:109], v[204:207], v[166:169], v[106:109]
	v_mfma_f32_16x16x32_bf16 v[78:81], v[212:215], v[166:169], v[78:81]
	v_mfma_f32_16x16x32_bf16 v[46:49], v[220:223], v[166:169], v[46:49]
	s_add_u32 m0, m0, 0x400
	v_add_u32_e32 v226, 24, v224
	v_max_i32_e32 v226, 0, v226
	v_min_i32_e32 v226, 0xffff, v226
	v_lshl_add_u32 v226, v226, 11, v231
	global_load_lds_dwordx4 v226, s[4:5]
	ds_read_b128 v[162:165], v229 offset:6144
	ds_read_b128 v[166:169], v230 offset:6144
	s_waitcnt lgkmcnt(2)
	v_mfma_f32_16x16x32_bf16 v[118:121], v[192:195], v[154:157], v[118:121]
	v_mfma_f32_16x16x32_bf16 v[98:101], v[200:203], v[154:157], v[98:101]
	v_mfma_f32_16x16x32_bf16 v[70:73], v[208:211], v[154:157], v[70:73]
	v_mfma_f32_16x16x32_bf16 v[38:41], v[216:219], v[154:157], v[38:41]
	s_add_u32 m0, m0, 0x400
	v_add_u32_e32 v226, 32, v224
	v_max_i32_e32 v226, 0, v226
	v_min_i32_e32 v226, 0xffff, v226
	v_lshl_add_u32 v226, v226, 11, v231
	global_load_lds_dwordx4 v226, s[4:5]
	v_mfma_f32_16x16x32_bf16 v[118:121], v[196:199], v[158:161], v[118:121]
	v_mfma_f32_16x16x32_bf16 v[98:101], v[204:207], v[158:161], v[98:101]
	v_mfma_f32_16x16x32_bf16 v[70:73], v[212:215], v[158:161], v[70:73]
	v_mfma_f32_16x16x32_bf16 v[38:41], v[220:223], v[158:161], v[38:41]
	s_add_u32 m0, m0, 0x400
	v_add_u32_e32 v226, 40, v224
	v_max_i32_e32 v226, 0, v226
	v_min_i32_e32 v226, 0xffff, v226
	v_lshl_add_u32 v226, v226, 11, v231
	global_load_lds_dwordx4 v226, s[4:5]
	ds_read_b128 v[154:157], v229 offset:8192
	ds_read_b128 v[158:161], v230 offset:8192
	s_waitcnt lgkmcnt(2)
	v_mfma_f32_16x16x32_bf16 v[110:113], v[192:195], v[162:165], v[110:113]
	v_mfma_f32_16x16x32_bf16 v[86:89], v[200:203], v[162:165], v[86:89]
	v_mfma_f32_16x16x32_bf16 v[54:57], v[208:211], v[162:165], v[54:57]
	v_mfma_f32_16x16x32_bf16 v[26:29], v[216:219], v[162:165], v[26:29]
	s_add_u32 m0, m0, 0x400
	v_add_u32_e32 v226, 48, v224
	v_max_i32_e32 v226, 0, v226
	v_min_i32_e32 v226, 0xffff, v226
	v_lshl_add_u32 v226, v226, 11, v231
	global_load_lds_dwordx4 v226, s[4:5]
	v_mfma_f32_16x16x32_bf16 v[110:113], v[196:199], v[166:169], v[110:113]
	v_mfma_f32_16x16x32_bf16 v[86:89], v[204:207], v[166:169], v[86:89]
	v_mfma_f32_16x16x32_bf16 v[54:57], v[212:215], v[166:169], v[54:57]
	v_mfma_f32_16x16x32_bf16 v[26:29], v[220:223], v[166:169], v[26:29]
	s_add_u32 m0, m0, 0x400
	v_add_u32_e32 v226, 56, v224
	v_max_i32_e32 v226, 0, v226
	v_min_i32_e32 v226, 0xffff, v226
	v_lshl_add_u32 v226, v226, 11, v231
	global_load_lds_dwordx4 v226, s[4:5]
	ds_read_b128 v[162:165], v229 offset:10240
	ds_read_b128 v[166:169], v230 offset:10240
	s_waitcnt lgkmcnt(2)
	v_mfma_f32_16x16x32_bf16 v[102:105], v[192:195], v[154:157], v[102:105]
	v_mfma_f32_16x16x32_bf16 v[74:77], v[200:203], v[154:157], v[74:77]
	v_mfma_f32_16x16x32_bf16 v[42:45], v[208:211], v[154:157], v[42:45]
	v_mfma_f32_16x16x32_bf16 v[18:21], v[216:219], v[154:157], v[18:21]
	s_add_u32 m0, s21, 17
	s_and_b32 m0, m0, 1
	s_lshl_b32 m0, m0, 14
	s_add_u32 m0, m0, 0x8000
	v_readfirstlane_b32 s32, v142
	s_lshl_b32 s32, s32, 2
	s_add_u32 m0, m0, s32
	v_mov_b32_e32 v226, v225
	global_load_lds_dwordx4 v226, s[22:23]
	v_mfma_f32_16x16x32_bf16 v[102:105], v[196:199], v[158:161], v[102:105]
	v_mfma_f32_16x16x32_bf16 v[74:77], v[204:207], v[158:161], v[74:77]
	v_mfma_f32_16x16x32_bf16 v[42:45], v[212:215], v[158:161], v[42:45]
	v_mfma_f32_16x16x32_bf16 v[18:21], v[220:223], v[158:161], v[18:21]
	s_add_u32 m0, m0, 0x400
	v_add_u32_e32 v226, 0x4000, v225
	global_load_lds_dwordx4 v226, s[22:23]
	ds_read_b128 v[154:157], v229 offset:12288
	ds_read_b128 v[158:161], v230 offset:12288
	s_waitcnt lgkmcnt(2)
	v_mfma_f32_16x16x32_bf16 v[90:93], v[192:195], v[162:165], v[90:93]
	v_mfma_f32_16x16x32_bf16 v[58:61], v[200:203], v[162:165], v[58:61]
	v_mfma_f32_16x16x32_bf16 v[30:33], v[208:211], v[162:165], v[30:33]
	v_mfma_f32_16x16x32_bf16 v[10:13], v[216:219], v[162:165], v[10:13]
	s_add_u32 m0, m0, 0x400
	v_add_u32_e32 v226, 0x8000, v225
	global_load_lds_dwordx4 v226, s[22:23]
	v_mfma_f32_16x16x32_bf16 v[90:93], v[196:199], v[166:169], v[90:93]
	v_mfma_f32_16x16x32_bf16 v[58:61], v[204:207], v[166:169], v[58:61]
	v_mfma_f32_16x16x32_bf16 v[30:33], v[212:215], v[166:169], v[30:33]
	v_mfma_f32_16x16x32_bf16 v[10:13], v[220:223], v[166:169], v[10:13]
	s_add_u32 m0, m0, 0x400
	v_add_u32_e32 v226, 0xc000, v225
	global_load_lds_dwordx4 v226, s[22:23]
	ds_read_b128 v[162:165], v229 offset:14336
	ds_read_b128 v[166:169], v230 offset:14336
	s_waitcnt lgkmcnt(2)
	v_mfma_f32_16x16x32_bf16 v[82:85], v[192:195], v[154:157], v[82:85]
	v_mfma_f32_16x16x32_bf16 v[50:53], v[200:203], v[154:157], v[50:53]
	v_mfma_f32_16x16x32_bf16 v[22:25], v[208:211], v[154:157], v[22:25]
	v_mfma_f32_16x16x32_bf16 v[6:9], v[216:219], v[154:157], v[6:9]
	v_mfma_f32_16x16x32_bf16 v[82:85], v[196:199], v[158:161], v[82:85]
	v_mfma_f32_16x16x32_bf16 v[50:53], v[204:207], v[158:161], v[50:53]
	v_mfma_f32_16x16x32_bf16 v[22:25], v[212:215], v[158:161], v[22:25]
	v_mfma_f32_16x16x32_bf16 v[6:9], v[220:223], v[158:161], v[6:9]
	s_waitcnt lgkmcnt(0)
	v_mfma_f32_16x16x32_bf16 v[66:69], v[192:195], v[162:165], v[66:69]
	v_mfma_f32_16x16x32_bf16 v[34:37], v[200:203], v[162:165], v[34:37]
	v_mfma_f32_16x16x32_bf16 v[14:17], v[208:211], v[162:165], v[14:17]
	v_mfma_f32_16x16x32_bf16 v[2:5], v[216:219], v[162:165], v[2:5]
	v_mfma_f32_16x16x32_bf16 v[66:69], v[196:199], v[166:169], v[66:69]
	v_mfma_f32_16x16x32_bf16 v[34:37], v[204:207], v[166:169], v[34:37]
	v_mfma_f32_16x16x32_bf16 v[14:17], v[212:215], v[166:169], v[14:17]
	v_mfma_f32_16x16x32_bf16 v[2:5], v[220:223], v[166:169], v[2:5]
	v_xor_b32_e32 v229, 0x4000, v229
	v_xor_b32_e32 v230, 0x4000, v230
	s_add_i32 s21, s21, 1
	s_cmp_lg_u32 s21, 15
	s_cbranch_scc1 .Lbk64_418
	s_waitcnt vmcnt(0)
	s_barrier
	ds_read_b128 v[192:195], v227
	ds_read_b128 v[196:199], v228
	ds_read_b128 v[200:203], v227 offset:2048
	ds_read_b128 v[204:207], v228 offset:2048
	ds_read_b128 v[208:211], v227 offset:4096
	ds_read_b128 v[212:215], v228 offset:4096
	ds_read_b128 v[216:219], v227 offset:6144
	ds_read_b128 v[220:223], v228 offset:6144
	s_waitcnt lgkmcnt(0)
	s_barrier
	ds_read_b128 v[154:157], v229 offset:0
	ds_read_b128 v[158:161], v230 offset:0
	ds_read_b128 v[162:165], v229 offset:2048
	ds_read_b128 v[166:169], v230 offset:2048
	s_waitcnt lgkmcnt(2)
	v_mfma_f32_16x16x32_bf16 v[126:129], v[192:195], v[154:157], v[126:129]
	v_mfma_f32_16x16x32_bf16 v[114:117], v[200:203], v[154:157], v[114:117]
	v_mfma_f32_16x16x32_bf16 v[94:97], v[208:211], v[154:157], v[94:97]
	v_mfma_f32_16x16x32_bf16 v[62:65], v[216:219], v[154:157], v[62:65]
	v_mfma_f32_16x16x32_bf16 v[126:129], v[196:199], v[158:161], v[126:129]
	v_mfma_f32_16x16x32_bf16 v[114:117], v[204:207], v[158:161], v[114:117]
	v_mfma_f32_16x16x32_bf16 v[94:97], v[212:215], v[158:161], v[94:97]
	v_mfma_f32_16x16x32_bf16 v[62:65], v[220:223], v[158:161], v[62:65]
	ds_read_b128 v[154:157], v229 offset:4096
	ds_read_b128 v[158:161], v230 offset:4096
	s_waitcnt lgkmcnt(2)
	v_mfma_f32_16x16x32_bf16 v[122:125], v[192:195], v[162:165], v[122:125]
	v_mfma_f32_16x16x32_bf16 v[106:109], v[200:203], v[162:165], v[106:109]
	v_mfma_f32_16x16x32_bf16 v[78:81], v[208:211], v[162:165], v[78:81]
	v_mfma_f32_16x16x32_bf16 v[46:49], v[216:219], v[162:165], v[46:49]
	v_mfma_f32_16x16x32_bf16 v[122:125], v[196:199], v[166:169], v[122:125]
	v_mfma_f32_16x16x32_bf16 v[106:109], v[204:207], v[166:169], v[106:109]
	v_mfma_f32_16x16x32_bf16 v[78:81], v[212:215], v[166:169], v[78:81]
	v_mfma_f32_16x16x32_bf16 v[46:49], v[220:223], v[166:169], v[46:49]
	ds_read_b128 v[162:165], v229 offset:6144
	ds_read_b128 v[166:169], v230 offset:6144
	s_waitcnt lgkmcnt(2)
	v_mfma_f32_16x16x32_bf16 v[118:121], v[192:195], v[154:157], v[118:121]
	v_mfma_f32_16x16x32_bf16 v[98:101], v[200:203], v[154:157], v[98:101]
	v_mfma_f32_16x16x32_bf16 v[70:73], v[208:211], v[154:157], v[70:73]
	v_mfma_f32_16x16x32_bf16 v[38:41], v[216:219], v[154:157], v[38:41]
	v_mfma_f32_16x16x32_bf16 v[118:121], v[196:199], v[158:161], v[118:121]
	v_mfma_f32_16x16x32_bf16 v[98:101], v[204:207], v[158:161], v[98:101]
	v_mfma_f32_16x16x32_bf16 v[70:73], v[212:215], v[158:161], v[70:73]
	v_mfma_f32_16x16x32_bf16 v[38:41], v[220:223], v[158:161], v[38:41]
	ds_read_b128 v[154:157], v229 offset:8192
	ds_read_b128 v[158:161], v230 offset:8192
	s_waitcnt lgkmcnt(2)
	v_mfma_f32_16x16x32_bf16 v[110:113], v[192:195], v[162:165], v[110:113]
	v_mfma_f32_16x16x32_bf16 v[86:89], v[200:203], v[162:165], v[86:89]
	v_mfma_f32_16x16x32_bf16 v[54:57], v[208:211], v[162:165], v[54:57]
	v_mfma_f32_16x16x32_bf16 v[26:29], v[216:219], v[162:165], v[26:29]
	v_mfma_f32_16x16x32_bf16 v[110:113], v[196:199], v[166:169], v[110:113]
	v_mfma_f32_16x16x32_bf16 v[86:89], v[204:207], v[166:169], v[86:89]
	v_mfma_f32_16x16x32_bf16 v[54:57], v[212:215], v[166:169], v[54:57]
	v_mfma_f32_16x16x32_bf16 v[26:29], v[220:223], v[166:169], v[26:29]
	ds_read_b128 v[162:165], v229 offset:10240
	ds_read_b128 v[166:169], v230 offset:10240
	s_waitcnt lgkmcnt(2)
	v_mfma_f32_16x16x32_bf16 v[102:105], v[192:195], v[154:157], v[102:105]
	v_mfma_f32_16x16x32_bf16 v[74:77], v[200:203], v[154:157], v[74:77]
	v_mfma_f32_16x16x32_bf16 v[42:45], v[208:211], v[154:157], v[42:45]
	v_mfma_f32_16x16x32_bf16 v[18:21], v[216:219], v[154:157], v[18:21]
	v_mfma_f32_16x16x32_bf16 v[102:105], v[196:199], v[158:161], v[102:105]
	v_mfma_f32_16x16x32_bf16 v[74:77], v[204:207], v[158:161], v[74:77]
	v_mfma_f32_16x16x32_bf16 v[42:45], v[212:215], v[158:161], v[42:45]
	v_mfma_f32_16x16x32_bf16 v[18:21], v[220:223], v[158:161], v[18:21]
	ds_read_b128 v[154:157], v229 offset:12288
	ds_read_b128 v[158:161], v230 offset:12288
	s_waitcnt lgkmcnt(2)
	v_mfma_f32_16x16x32_bf16 v[90:93], v[192:195], v[162:165], v[90:93]
	v_mfma_f32_16x16x32_bf16 v[58:61], v[200:203], v[162:165], v[58:61]
	v_mfma_f32_16x16x32_bf16 v[30:33], v[208:211], v[162:165], v[30:33]
	v_mfma_f32_16x16x32_bf16 v[10:13], v[216:219], v[162:165], v[10:13]
	v_mfma_f32_16x16x32_bf16 v[90:93], v[196:199], v[166:169], v[90:93]
	v_mfma_f32_16x16x32_bf16 v[58:61], v[204:207], v[166:169], v[58:61]
	v_mfma_f32_16x16x32_bf16 v[30:33], v[212:215], v[166:169], v[30:33]
	v_mfma_f32_16x16x32_bf16 v[10:13], v[220:223], v[166:169], v[10:13]
	ds_read_b128 v[162:165], v229 offset:14336
	ds_read_b128 v[166:169], v230 offset:14336
	s_waitcnt lgkmcnt(2)
	v_mfma_f32_16x16x32_bf16 v[82:85], v[192:195], v[154:157], v[82:85]
	v_mfma_f32_16x16x32_bf16 v[50:53], v[200:203], v[154:157], v[50:53]
	v_mfma_f32_16x16x32_bf16 v[22:25], v[208:211], v[154:157], v[22:25]
	v_mfma_f32_16x16x32_bf16 v[6:9], v[216:219], v[154:157], v[6:9]
	v_mfma_f32_16x16x32_bf16 v[82:85], v[196:199], v[158:161], v[82:85]
	v_mfma_f32_16x16x32_bf16 v[50:53], v[204:207], v[158:161], v[50:53]
	v_mfma_f32_16x16x32_bf16 v[22:25], v[212:215], v[158:161], v[22:25]
	v_mfma_f32_16x16x32_bf16 v[6:9], v[220:223], v[158:161], v[6:9]
	s_waitcnt lgkmcnt(0)
	v_mfma_f32_16x16x32_bf16 v[66:69], v[192:195], v[162:165], v[66:69]
	v_mfma_f32_16x16x32_bf16 v[34:37], v[200:203], v[162:165], v[34:37]
	v_mfma_f32_16x16x32_bf16 v[14:17], v[208:211], v[162:165], v[14:17]
	v_mfma_f32_16x16x32_bf16 v[2:5], v[216:219], v[162:165], v[2:5]
	v_mfma_f32_16x16x32_bf16 v[66:69], v[196:199], v[166:169], v[66:69]
	v_mfma_f32_16x16x32_bf16 v[34:37], v[204:207], v[166:169], v[34:37]
	v_mfma_f32_16x16x32_bf16 v[14:17], v[212:215], v[166:169], v[14:17]
	v_mfma_f32_16x16x32_bf16 v[2:5], v[220:223], v[166:169], v[2:5]
	s_nop 7
	s_nop 7
	s_waitcnt vmcnt(6)
	v_add_u32_e32 v142, v149, v147
	s_waitcnt lgkmcnt(0)
	v_and_b32_e32 v1, 0xfffffc0, v1
	v_lshl_or_b32 v1, v144, 2, v1
	v_mul_lo_u32 v1, v1, s33
	v_lshl_or_b32 v1, v143, 2, v1
	s_waitcnt lgkmcnt(0)
	s_waitcnt lgkmcnt(0)
	s_waitcnt lgkmcnt(0)
	s_waitcnt lgkmcnt(0)
	s_waitcnt lgkmcnt(0)
	v_mov_b64_e32 v[162:163], v[30:31]
	v_mov_b64_e32 v[164:165], v[32:33]
	v_mov_b64_e32 v[134:135], v[10:11]
	v_mov_b64_e32 v[136:137], v[12:13]
	s_nop 2
	s_waitcnt lgkmcnt(0)
	v_mov_b64_e32 v[180:181], v[6:7]
	v_mov_b64_e32 v[182:183], v[8:9]
	s_nop 2
	s_waitcnt vmcnt(0)
	v_mov_b64_e32 v[166:167], v[22:23]
	v_mov_b64_e32 v[168:169], v[24:25]
	s_waitcnt lgkmcnt(0)
	v_mov_b64_e32 v[130:131], v[34:35]
	v_mov_b64_e32 v[132:133], v[36:37]
	v_mov_b64_e32 v[138:139], v[14:15]
	v_mov_b64_e32 v[140:141], v[16:17]
	v_mov_b64_e32 v[158:159], v[2:3]
	v_mov_b64_e32 v[160:161], v[4:5]
	s_nop 1
	s_waitcnt lgkmcnt(0)
	v_mov_b64_e32 v[22:23], v[126:127]
	v_mov_b64_e32 v[24:25], v[128:129]
	s_nop 2
	v_mov_b64_e32 v[32:33], v[114:115]
	v_mov_b64_e32 v[34:35], v[116:117]
	s_nop 2
	s_waitcnt lgkmcnt(0)
	v_mov_b64_e32 v[2:3], v[122:123]
	v_mov_b64_e32 v[4:5], v[124:125]
	v_mov_b64_e32 v[122:123], v[46:47]
	v_mov_b64_e32 v[124:125], v[48:49]
	s_waitcnt lgkmcnt(0)
	v_mov_b64_e32 v[46:47], v[118:119]
	v_mov_b64_e32 v[48:49], v[120:121]
	v_mov_b64_e32 v[118:119], v[38:39]
	v_mov_b64_e32 v[120:121], v[40:41]
	v_mov_b64_e32 v[36:37], v[110:111]
	v_mov_b64_e32 v[38:39], v[112:113]
	s_nop 2
	s_waitcnt vmcnt(0) lgkmcnt(0)
	s_barrier
	ds_write2_b32 v1, v22, v2 offset1:16
	ds_write2_b32 v1, v23, v3 offset0:68 offset1:84
	ds_write2_b32 v1, v24, v4 offset0:136 offset1:152
	ds_write2_b32 v1, v25, v5 offset0:204 offset1:220
	ds_write2_b32 v1, v46, v36 offset0:32 offset1:48
	ds_write2_b32 v1, v47, v37 offset0:100 offset1:116
	ds_write2_b32 v1, v48, v38 offset0:168 offset1:184
	ds_write2_b32 v1, v49, v39 offset0:236 offset1:252
	v_mov_b64_e32 v[200:201], v[86:87]
	v_mov_b64_e32 v[202:203], v[88:89]
	s_nop 1
	v_add_u32_e32 v88, 0x1000, v1
	ds_write2_b32 v88, v32, v106 offset0:64 offset1:80
	ds_write2_b32 v88, v33, v107 offset0:132 offset1:148
	ds_write2_b32 v88, v34, v108 offset0:200 offset1:216
	v_add_u32_e32 v89, 0x1400, v1
	v_mov_b64_e32 v[212:213], v[26:27]
	v_mov_b64_e32 v[214:215], v[28:29]
	ds_write2_b32 v89, v35, v109 offset0:12 offset1:28
	ds_write2_b32 v88, v98, v200 offset0:96 offset1:112
	ds_write2_b32 v88, v99, v201 offset0:164 offset1:180
	ds_write2_b32 v88, v100, v202 offset0:232 offset1:248
	ds_write2_b32 v89, v101, v203 offset0:44 offset1:60
	v_mov_b64_e32 v[30:31], v[90:91]
	v_mov_b64_e32 v[32:33], v[92:93]
	s_nop 2
	v_add_u32_e32 v90, 0x2000, v1
	v_add_u32_e32 v91, 0x2400, v1
	ds_write2_b32 v90, v94, v78 offset0:128 offset1:144
	ds_write2_b32 v90, v95, v79 offset0:196 offset1:212
	ds_write2_b32 v91, v96, v80 offset0:8 offset1:24
	ds_write2_b32 v91, v97, v81 offset0:76 offset1:92
	ds_write2_b32 v90, v70, v54 offset0:160 offset1:176
	ds_write2_b32 v90, v71, v55 offset0:228 offset1:244
	ds_write2_b32 v91, v72, v56 offset0:40 offset1:56
	v_add_u32_e32 v92, 0x3000, v1
	v_add_u32_e32 v93, 0x3400, v1
	v_mov_b32_e32 v70, v170
	v_mov_b64_e32 v[6:7], v[42:43]
	v_mov_b64_e32 v[8:9], v[44:45]
	ds_write2_b32 v91, v73, v57 offset0:108 offset1:124
	ds_write2_b32 v92, v62, v122 offset0:192 offset1:208
	ds_write2_b32 v93, v63, v123 offset0:4 offset1:20
	ds_write2_b32 v93, v64, v124 offset0:72 offset1:88
	v_mov_b64_e32 v[42:43], v[50:51]
	v_mov_b64_e32 v[44:45], v[52:53]
	ds_write2_b32 v93, v65, v125 offset0:140 offset1:156
	ds_write2_b32 v92, v118, v212 offset0:224 offset1:240
	ds_write2_b32 v93, v119, v213 offset0:36 offset1:52
	ds_write2_b32 v93, v120, v214 offset0:104 offset1:120
	ds_write2_b32 v93, v121, v215 offset0:172 offset1:188
	s_waitcnt lgkmcnt(0)
	s_barrier
	v_mov_b64_e32 v[14:15], v[102:103]
	v_mov_b64_e32 v[16:17], v[104:105]
	v_ashrrev_i32_e32 v50, 7, v70
	v_mov_b64_e32 v[10:11], v[74:75]
	v_mov_b64_e32 v[12:13], v[76:77]
	v_mov_b64_e32 v[2:3], v[18:19]
	v_mov_b64_e32 v[4:5], v[20:21]
	v_mov_b64_e32 v[26:27], v[58:59]
	v_mov_b64_e32 v[28:29], v[60:61]
	v_mov_b64_e32 v[22:23], v[162:163]
	v_mov_b64_e32 v[24:25], v[164:165]
	v_mov_b64_e32 v[18:19], v[134:135]
	v_mov_b64_e32 v[20:21], v[136:137]
	v_mov_b64_e32 v[46:47], v[82:83]
	v_mov_b64_e32 v[48:49], v[84:85]
	v_mov_b64_e32 v[38:39], v[166:167]
	v_mov_b64_e32 v[40:41], v[168:169]
	v_mov_b64_e32 v[34:35], v[180:181]
	v_mov_b64_e32 v[36:37], v[182:183]
	v_mov_b64_e32 v[62:63], v[66:67]
	v_mov_b64_e32 v[64:65], v[68:69]
	v_mov_b64_e32 v[58:59], v[130:131]
	v_mov_b64_e32 v[60:61], v[132:133]
	s_nop 1
	v_add_u32_e32 v66, s46, v50
	v_cmp_lt_i32_e32 vcc, s91, v66
	v_mov_b64_e32 v[54:55], v[138:139]
	v_mov_b64_e32 v[56:57], v[140:141]
	v_mov_b64_e32 v[50:51], v[158:159]
	v_mov_b64_e32 v[52:53], v[160:161]
	s_and_saveexec_b64 s[4:5], vcc
	s_xor_b64 s[22:23], exec, s[4:5]
	v_add_u32_e32 v66, 0xfffffef0, v66
	v_mul_hi_u32 v67, v66, s96
	v_lshrrev_b32_e32 v67, 3, v67
	v_add_u32_e32 v68, 16, v67
	v_lshl_add_u32 v67, v67, 5, v67
	v_sub_u32_e32 v71, v66, v67
	s_or_saveexec_b64 s[22:23], s[22:23]
	v_mov_b32_e32 v72, 0x1000
	s_xor_b64 exec, exec, s[22:23]
	v_mul_hi_i32 v67, v66, s97
	v_lshrrev_b32_e32 v68, 31, v67
	v_ashrrev_i32_e32 v67, 3, v67
	v_add_u32_e32 v68, v67, v68
	v_lshl_add_u32 v67, v68, 4, v68
	v_sub_u32_e32 v71, v66, v67
	v_mov_b32_e32 v72, 0x800
	s_or_b64 exec, exec, s[22:23]
	v_cmp_lt_i32_e32 vcc, 15, v68
	s_and_saveexec_b64 s[4:5], vcc
	s_xor_b64 s[4:5], exec, s[4:5]
	v_add_u32_e32 v66, -16, v68
	v_mov_b32_e32 v67, v0
	v_lshlrev_b64 v[66:67], 12, v[66:67]
	v_lshl_add_u64 v[66:67], v[66:67], 0, s[42:43]
	s_andn2_saveexec_b64 s[22:23], s[4:5]
	v_ashrrev_i32_e32 v69, 31, v68
	v_lshlrev_b64 v[66:67], 11, v[68:69]
	s_or_b64 exec, exec, s[22:23]
	v_and_b32_e32 v69, 0x7f, v70
	v_cmp_gt_i32_e32 vcc, s79, v69
	s_and_saveexec_b64 s[22:23], vcc
	s_cbranch_execz .LBB0_436
	v_cmp_ne_u32_e32 vcc, 0, v69
	s_and_b64 exec, exec, vcc
	s_cbranch_execz .LBB0_436
	v_mul_lo_u32 v71, v71, s54
	v_add3_u32 v68, v69, v71, -1
	v_cmp_lt_i32_e32 vcc, v68, v72
	s_and_b64 exec, exec, vcc
	s_cbranch_execz .LBB0_436
	v_cmp_lt_i32_e32 vcc, 0, v68
	v_mov_b32_e32 v83, 0
	v_mov_b32_e32 v82, 0
	s_and_saveexec_b64 s[4:5], vcc
	v_mov_b32_e32 v73, 0x11ffc
	v_lshl_add_u32 v73, v70, 2, v73
	ds_read_b32 v82, v73
	s_or_b64 exec, exec, s[4:5]
	v_add_u32_e32 v69, v71, v69
	v_cmp_lt_i32_e32 vcc, v69, v72
	v_lshl_add_u32 v69, v70, 2, v175
	ds_read_b32 v84, v69
	s_and_saveexec_b64 s[4:5], vcc
	ds_read_b32 v83, v69 offset:4
	s_or_b64 exec, exec, s[4:5]
	s_lshl_b32 s4, s20, 6
	s_ashr_i32 s5, s4, 31
	s_lshl_b64 s[4:5], s[4:5], 1
	v_ashrrev_i32_e32 v69, 31, v68
	s_add_u32 s4, s38, s4
	v_lshl_add_u64 v[66:67], v[66:67], 0, v[68:69]
	v_mul_lo_u32 v68, v70, s33
	s_addc_u32 s5, s39, s5
	v_add_u32_e32 v94, 0xfffffef0, v68
	v_mov_b64_e32 v[68:69], s[4:5]
	v_mad_u64_u32 v[86:87], s[4:5], v66, s3, v[68:69]
	v_mov_b32_e32 v66, v87
	v_mad_u64_u32 v[66:67], s[4:5], v67, s3, v[66:67]
	v_mov_b32_e32 v87, v66
	s_mov_b32 s4, 0

.LBB0_528:
	s_cmpk_gt_i32 s16, 0xff
	s_mov_b64 s[4:5], -1
	s_cbranch_scc1 .LBB0_522
	s_ashr_i32 s4, s16, 31
	s_lshr_b32 s4, s4, 26
	s_add_i32 s4, s16, s4
	s_andn2_b32 s4, s4, 63
	s_sub_i32 s5, s16, s4
	s_ashr_i32 s16, s5, 3
	s_lshl_b32 s5, s5, 3
	s_and_b32 s5, s5, 56
	s_or_b32 s4, s4, s5
	v_mov_b32_e32 v1, v170
	s_barrier
	s_or_b32 s4, s4, s18
	s_lshl_b32 s4, s4, 8
	v_lshlrev_b32_e32 v145, 4, v1
	v_bfe_u32 v35, v1, 2, 4
	v_ashrrev_i32_e32 v14, 2, v1
	v_add_u32_e32 v37, 0x1000, v145
	v_add_u32_e32 v38, 0x2000, v145
	v_add_u32_e32 v40, 0x3000, v145
	v_or_b32_e32 v12, s4, v35
	v_and_b32_e32 v6, -16, v14
	v_ashrrev_i32_e32 v19, 6, v37
	v_ashrrev_i32_e32 v10, 6, v38
	v_ashrrev_i32_e32 v13, 6, v40
	v_and_b32_e32 v34, 32, v1
	v_add_u32_e32 v6, v12, v6
	v_and_b32_e32 v8, -16, v19
	v_and_b32_e32 v39, -16, v10
	v_and_b32_e32 v41, -16, v13
	v_bitop3_b32 v2, v145, v34, 48 bitop3:0x6c
	v_mov_b32_e32 v3, v0
	v_ashrrev_i32_e32 v7, 31, v6
	v_add_u32_e32 v8, v8, v12
	v_add_u32_e32 v10, v39, v12
	v_add_u32_e32 v12, v41, v12
	s_ashr_i32 s17, s16, 31
	v_lshl_add_u64 v[4:5], s[36:37], 0, v[2:3]
	v_lshlrev_b64 v[6:7], 11, v[6:7]
	v_ashrrev_i32_e32 v9, 31, v8
	v_ashrrev_i32_e32 v11, 31, v10
	v_ashrrev_i32_e32 v13, 31, v12
	v_readfirstlane_b32 s5, v145
	s_lshl_b64 s[18:19], s[16:17], 18
	v_lshrrev_b32_e32 v18, 2, v1
	v_lshl_add_u64 v[6:7], v[4:5], 0, v[6:7]
	v_lshlrev_b64 v[8:9], 11, v[8:9]
	v_lshlrev_b64 v[10:11], 11, v[10:11]
	v_lshlrev_b64 v[12:13], 11, v[12:13]
	s_waitcnt vmcnt(0)
	s_mov_b32 m0, s5
	v_readfirstlane_b32 s5, v37
	s_add_u32 s26, s20, s18
	v_lshl_add_u64 v[8:9], v[4:5], 0, v[8:9]
	v_lshl_add_u64 v[10:11], v[4:5], 0, v[10:11]
	v_lshl_add_u64 v[4:5], v[4:5], 0, v[12:13]
	v_bfi_b32 v12, 15, v18, v14
	s_mov_b32 m0, s5
	v_readfirstlane_b32 s5, v38
	s_addc_u32 s27, s21, s19
	v_ashrrev_i32_e32 v13, 31, v12
	v_bfi_b32 v18, -16, v19, v18
	v_add_u32_e32 v42, 0x4000, v145
	s_mov_b32 m0, s5
	v_readfirstlane_b32 s5, v40
	v_lshl_add_u64 v[2:3], s[26:27], 0, v[2:3]
	v_lshlrev_b64 v[14:15], 11, v[12:13]
	v_ashrrev_i32_e32 v19, 31, v18
	v_add_u32_e32 v43, 0x5000, v145
	s_mov_b32 m0, s5
	v_readfirstlane_b32 s5, v42
	v_lshl_add_u64 v[16:17], v[2:3], 0, v[14:15]
	v_lshlrev_b64 v[20:21], 11, v[18:19]
	v_add_u32_e32 v44, 0x6000, v145
	s_mov_b32 m0, s5
	v_readfirstlane_b32 s5, v43
	v_and_b32_e32 v142, 15, v1
	v_lshl_add_u64 v[2:3], v[2:3], 0, v[20:21]
	v_bfe_u32 v143, v1, 4, 2
	v_lshlrev_b32_e32 v19, 6, v1
	v_lshlrev_b32_e32 v22, 2, v1
	v_add_u32_e32 v45, 0x7000, v145
	s_mov_b32 m0, s5
	v_readfirstlane_b32 s5, v44
	v_lshlrev_b32_e32 v13, 4, v143
	v_and_b32_e32 v24, 0x3c0, v19
	v_lshlrev_b32_e32 v25, 6, v142
	v_and_b32_e32 v26, 32, v22
	v_lshl_add_u64 v[22:23], v[6:7], 0, 64
	v_add_u32_e32 v46, 0x8000, v145
	s_mov_b32 m0, s5
	v_readfirstlane_b32 s5, v45
	v_add_u32_e32 v47, 0x9000, v145
	v_bitop3_b32 v149, v13, v26, v24 bitop3:0x36
	v_bitop3_b32 v144, v13, v26, v25 bitop3:0x36
	v_lshl_add_u64 v[24:25], v[8:9], 0, 64
	s_mov_b32 m0, s5
	v_readfirstlane_b32 s5, v46
	v_add_u32_e32 v48, 0xa000, v145
	v_lshl_add_u64 v[26:27], v[10:11], 0, 64
	s_mov_b32 m0, s5
	v_readfirstlane_b32 s5, v47
	v_add_u32_e32 v49, 0xb000, v145
	v_lshl_add_u64 v[28:29], v[4:5], 0, 64
	s_mov_b32 m0, s5
	v_readfirstlane_b32 s5, v48
	v_lshl_add_u64 v[30:31], v[16:17], 0, 64
	s_mov_b32 m0, s5
	v_readfirstlane_b32 s5, v49
	v_lshl_add_u64 v[32:33], v[2:3], 0, 64
	s_mov_b32 m0, s5
	v_and_b32_e32 v36, 48, v145
	v_lshl_add_u64 v[2:3], s[18:19], 0, v[20:21]
	v_bitop3_b32 v2, v2, v36, v34 bitop3:0xf6
	v_lshl_add_u64 v[130:131], s[12:13], 0, v[2:3]
	v_lshl_add_u64 v[2:3], s[18:19], 0, v[14:15]
	v_bitop3_b32 v2, v2, v36, v34 bitop3:0xf6
	v_lshl_add_u64 v[132:133], s[12:13], 0, v[2:3]
	v_add_u32_e32 v2, s4, v41
	v_or_b32_e32 v2, v2, v35
	v_ashrrev_i32_e32 v3, 31, v2
	v_lshlrev_b64 v[2:3], 11, v[2:3]
	v_bitop3_b32 v2, v2, v36, v34 bitop3:0xf6
	v_lshl_add_u64 v[134:135], s[14:15], 0, v[2:3]
	v_add_u32_e32 v2, s4, v39
	v_or_b32_e32 v2, v2, v35
	v_ashrrev_i32_e32 v3, 31, v2
	v_lshlrev_b64 v[2:3], 11, v[2:3]
	v_bitop3_b32 v2, v2, v36, v34 bitop3:0xf6
	v_lshl_add_u64 v[136:137], s[14:15], 0, v[2:3]
	v_add_u32_e32 v2, s4, v18
	v_ashrrev_i32_e32 v3, 31, v2
	v_lshlrev_b64 v[2:3], 11, v[2:3]
	v_bitop3_b32 v2, v2, v36, v34 bitop3:0xf6
	v_lshl_add_u64 v[138:139], s[14:15], 0, v[2:3]
	v_add_u32_e32 v2, s4, v12
	v_ashrrev_i32_e32 v3, 31, v2
	v_lshlrev_b64 v[2:3], 11, v[2:3]
	v_bitop3_b32 v2, v2, v36, v34 bitop3:0xf6
	v_lshl_add_u64 v[140:141], s[14:15], 0, v[2:3]
	v_mov_b32_e32 v2, 0
	v_and_b32_e32 v147, 0xfffff000, v19
	s_mov_b32 s5, 0
	s_mov_b64 s[18:19], 0
	v_mov_b32_e32 v3, v2
	v_mov_b32_e32 v4, v2
	v_mov_b32_e32 v5, v2
	v_mov_b32_e32 v6, v2
	v_mov_b32_e32 v7, v2
	v_mov_b32_e32 v8, v2
	v_mov_b32_e32 v9, v2
	v_mov_b32_e32 v10, v2
	v_mov_b32_e32 v11, v2
	v_mov_b32_e32 v12, v2
	v_mov_b32_e32 v13, v2
	v_mov_b32_e32 v14, v2
	v_mov_b32_e32 v15, v2
	v_mov_b32_e32 v16, v2
	v_mov_b32_e32 v17, v2
	v_mov_b32_e32 v18, v2
	v_mov_b32_e32 v19, v2
	v_mov_b32_e32 v20, v2
	v_mov_b32_e32 v21, v2
	v_mov_b32_e32 v26, v2
	v_mov_b32_e32 v27, v2
	v_mov_b32_e32 v28, v2
	v_mov_b32_e32 v29, v2
	v_mov_b32_e32 v38, v2
	v_mov_b32_e32 v39, v2
	v_mov_b32_e32 v40, v2
	v_mov_b32_e32 v41, v2
	v_mov_b32_e32 v54, v2
	v_mov_b32_e32 v55, v2
	v_mov_b32_e32 v56, v2
	v_mov_b32_e32 v57, v2
	v_mov_b32_e32 v22, v2
	v_mov_b32_e32 v23, v2
	v_mov_b32_e32 v24, v2
	v_mov_b32_e32 v25, v2
	v_mov_b32_e32 v30, v2
	v_mov_b32_e32 v31, v2
	v_mov_b32_e32 v32, v2
	v_mov_b32_e32 v33, v2
	v_mov_b32_e32 v34, v2
	v_mov_b32_e32 v35, v2
	v_mov_b32_e32 v36, v2
	v_mov_b32_e32 v37, v2
	v_mov_b32_e32 v42, v2
	v_mov_b32_e32 v43, v2
	v_mov_b32_e32 v44, v2
	v_mov_b32_e32 v45, v2
	v_mov_b32_e32 v46, v2
	v_mov_b32_e32 v47, v2
	v_mov_b32_e32 v48, v2
	v_mov_b32_e32 v49, v2
	v_mov_b32_e32 v58, v2
	v_mov_b32_e32 v59, v2
	v_mov_b32_e32 v60, v2
	v_mov_b32_e32 v61, v2
	v_mov_b32_e32 v70, v2
	v_mov_b32_e32 v71, v2
	v_mov_b32_e32 v72, v2
	v_mov_b32_e32 v73, v2
	v_mov_b32_e32 v86, v2
	v_mov_b32_e32 v87, v2
	v_mov_b32_e32 v88, v2
	v_mov_b32_e32 v89, v2
	v_mov_b32_e32 v50, v2
	v_mov_b32_e32 v51, v2
	v_mov_b32_e32 v52, v2
	v_mov_b32_e32 v53, v2
	v_mov_b32_e32 v62, v2
	v_mov_b32_e32 v63, v2
	v_mov_b32_e32 v64, v2
	v_mov_b32_e32 v65, v2
	v_mov_b32_e32 v66, v2
	v_mov_b32_e32 v67, v2
	v_mov_b32_e32 v68, v2
	v_mov_b32_e32 v69, v2
	v_mov_b32_e32 v74, v2
	v_mov_b32_e32 v75, v2
	v_mov_b32_e32 v76, v2
	v_mov_b32_e32 v77, v2
	v_mov_b32_e32 v78, v2
	v_mov_b32_e32 v79, v2
	v_mov_b32_e32 v80, v2
	v_mov_b32_e32 v81, v2
	v_mov_b32_e32 v90, v2
	v_mov_b32_e32 v91, v2
	v_mov_b32_e32 v92, v2
	v_mov_b32_e32 v93, v2
	v_mov_b32_e32 v102, v2
	v_mov_b32_e32 v103, v2
	v_mov_b32_e32 v104, v2
	v_mov_b32_e32 v105, v2
	v_mov_b32_e32 v114, v2
	v_mov_b32_e32 v115, v2
	v_mov_b32_e32 v116, v2
	v_mov_b32_e32 v117, v2
	v_mov_b32_e32 v82, v2
	v_mov_b32_e32 v83, v2
	v_mov_b32_e32 v84, v2
	v_mov_b32_e32 v85, v2
	v_mov_b32_e32 v94, v2
	v_mov_b32_e32 v95, v2
	v_mov_b32_e32 v96, v2
	v_mov_b32_e32 v97, v2
	v_mov_b32_e32 v98, v2
	v_mov_b32_e32 v99, v2
	v_mov_b32_e32 v100, v2
	v_mov_b32_e32 v101, v2
	v_mov_b32_e32 v106, v2
	v_mov_b32_e32 v107, v2
	v_mov_b32_e32 v108, v2
	v_mov_b32_e32 v109, v2
	v_mov_b32_e32 v110, v2
	v_mov_b32_e32 v111, v2
	v_mov_b32_e32 v112, v2
	v_mov_b32_e32 v113, v2
	v_mov_b32_e32 v118, v2
	v_mov_b32_e32 v119, v2
	v_mov_b32_e32 v120, v2
	v_mov_b32_e32 v121, v2
	v_mov_b32_e32 v122, v2
	v_mov_b32_e32 v123, v2
	v_mov_b32_e32 v124, v2
	v_mov_b32_e32 v125, v2
	v_mov_b32_e32 v126, v2
	v_mov_b32_e32 v127, v2
	v_mov_b32_e32 v128, v2
	v_mov_b32_e32 v129, v2
	v_and_b32_e32 v154, 63, v170
	v_lshrrev_b32_e32 v155, 3, v154
	v_and_b32_e32 v156, 7, v154
	v_xor_b32_e32 v156, v156, v155
	v_lshrrev_b32_e32 v157, 6, v170
	v_lshl_add_u32 v158, v157, 6, v155
	v_add_u32_e32 v158, s4, v158
	v_mul_u32_u24_e32 v224, 0x800, v158
	v_lshl_add_u32 v224, v156, 4, v224
	v_lshl_add_u32 v158, v157, 5, v155
	v_mul_u32_u24_e32 v225, 0x800, v158
	v_lshl_add_u32 v225, v156, 4, v225
	v_and_b32_e32 v155, 15, v154
	v_lshrrev_b32_e32 v156, 4, v154
	v_and_b32_e32 v158, 7, v155
	v_xor_b32_e32 v156, v156, v158
	v_lshlrev_b32_e32 v156, 4, v156
	v_lshl_add_u32 v229, v155, 7, v156
	v_lshl_add_u32 v227, v157, 13, v229
	v_xor_b32_e32 v228, 64, v227
	v_add_u32_e32 v229, 0x8000, v229
	v_xor_b32_e32 v230, 64, v229
	s_mov_b32 s18, s36
	s_mov_b32 s19, s37
	s_sub_u32 s32, s26, s36
	v_add_u32_e32 v225, s32, v225
	s_mov_b32 s25, 0
	v_readfirstlane_b32 s32, v145
	s_lshl_b32 m0, s32, 3
	v_mov_b32_e32 v226, v224
	global_load_lds_dwordx4 v226, s[18:19]
	s_add_u32 m0, m0, 0x400
	v_add_u32_e32 v226, 0x4000, v224
	global_load_lds_dwordx4 v226, s[18:19]
	s_add_u32 m0, m0, 0x400
	v_add_u32_e32 v226, 0x8000, v224
	global_load_lds_dwordx4 v226, s[18:19]
	s_add_u32 m0, m0, 0x400
	v_add_u32_e32 v226, 0xc000, v224
	global_load_lds_dwordx4 v226, s[18:19]
	s_add_u32 m0, m0, 0x400
	v_add_u32_e32 v226, 0x10000, v224
	global_load_lds_dwordx4 v226, s[18:19]
	s_add_u32 m0, m0, 0x400
	v_add_u32_e32 v226, 0x14000, v224
	global_load_lds_dwordx4 v226, s[18:19]
	s_add_u32 m0, m0, 0x400
	v_add_u32_e32 v226, 0x18000, v224
	global_load_lds_dwordx4 v226, s[18:19]
	s_add_u32 m0, m0, 0x400
	v_add_u32_e32 v226, 0x1c000, v224
	global_load_lds_dwordx4 v226, s[18:19]
	v_readfirstlane_b32 s32, v145
	s_lshl_b32 s32, s32, 2
	s_add_u32 m0, s32, 0x8000
	v_mov_b32_e32 v226, v225
	global_load_lds_dwordx4 v226, s[18:19]
	s_add_u32 m0, m0, 0x400
	v_add_u32_e32 v226, 0x4000, v225
	global_load_lds_dwordx4 v226, s[18:19]
	s_add_u32 m0, m0, 0x400
	v_add_u32_e32 v226, 0x8000, v225
	global_load_lds_dwordx4 v226, s[18:19]
	s_add_u32 m0, m0, 0x400
	v_add_u32_e32 v226, 0xc000, v225
	global_load_lds_dwordx4 v226, s[18:19]
.Lbk64_530:
	s_waitcnt vmcnt(0)
	s_barrier
	ds_read_b128 v[192:195], v227
	ds_read_b128 v[196:199], v228
	ds_read_b128 v[200:203], v227 offset:2048
	ds_read_b128 v[204:207], v228 offset:2048
	ds_read_b128 v[208:211], v227 offset:4096
	ds_read_b128 v[212:215], v228 offset:4096
	ds_read_b128 v[216:219], v227 offset:6144
	ds_read_b128 v[220:223], v228 offset:6144
	s_add_u32 s18, s18, 0x80
	s_addc_u32 s19, s19, 0
	s_waitcnt lgkmcnt(0)
	s_barrier
	ds_read_b128 v[154:157], v229 offset:0
	ds_read_b128 v[158:161], v230 offset:0
	ds_read_b128 v[162:165], v229 offset:2048
	ds_read_b128 v[166:169], v230 offset:2048
	s_waitcnt lgkmcnt(2)
	v_mfma_f32_16x16x32_bf16 v[126:129], v[192:195], v[154:157], v[126:129]
	v_mfma_f32_16x16x32_bf16 v[114:117], v[200:203], v[154:157], v[114:117]
	v_mfma_f32_16x16x32_bf16 v[86:89], v[208:211], v[154:157], v[86:89]
	v_mfma_f32_16x16x32_bf16 v[54:57], v[216:219], v[154:157], v[54:57]
	v_readfirstlane_b32 s32, v145
	s_lshl_b32 m0, s32, 3
	v_mov_b32_e32 v226, v224
	global_load_lds_dwordx4 v226, s[18:19]
	v_mfma_f32_16x16x32_bf16 v[126:129], v[196:199], v[158:161], v[126:129]
	v_mfma_f32_16x16x32_bf16 v[114:117], v[204:207], v[158:161], v[114:117]
	v_mfma_f32_16x16x32_bf16 v[86:89], v[212:215], v[158:161], v[86:89]
	v_mfma_f32_16x16x32_bf16 v[54:57], v[220:223], v[158:161], v[54:57]
	s_add_u32 m0, m0, 0x400
	v_add_u32_e32 v226, 0x4000, v224
	global_load_lds_dwordx4 v226, s[18:19]
	ds_read_b128 v[154:157], v229 offset:4096
	ds_read_b128 v[158:161], v230 offset:4096
	s_waitcnt lgkmcnt(2)
	v_mfma_f32_16x16x32_bf16 v[122:125], v[192:195], v[162:165], v[122:125]
	v_mfma_f32_16x16x32_bf16 v[102:105], v[200:203], v[162:165], v[102:105]
	v_mfma_f32_16x16x32_bf16 v[70:73], v[208:211], v[162:165], v[70:73]
	v_mfma_f32_16x16x32_bf16 v[38:41], v[216:219], v[162:165], v[38:41]
	s_add_u32 m0, m0, 0x400
	v_add_u32_e32 v226, 0x8000, v224
	global_load_lds_dwordx4 v226, s[18:19]
	v_mfma_f32_16x16x32_bf16 v[122:125], v[196:199], v[166:169], v[122:125]
	v_mfma_f32_16x16x32_bf16 v[102:105], v[204:207], v[166:169], v[102:105]
	v_mfma_f32_16x16x32_bf16 v[70:73], v[212:215], v[166:169], v[70:73]
	v_mfma_f32_16x16x32_bf16 v[38:41], v[220:223], v[166:169], v[38:41]
	s_add_u32 m0, m0, 0x400
	v_add_u32_e32 v226, 0xc000, v224
	global_load_lds_dwordx4 v226, s[18:19]
	ds_read_b128 v[162:165], v229 offset:6144
	ds_read_b128 v[166:169], v230 offset:6144
	s_waitcnt lgkmcnt(2)
	v_mfma_f32_16x16x32_bf16 v[118:121], v[192:195], v[154:157], v[118:121]
	v_mfma_f32_16x16x32_bf16 v[90:93], v[200:203], v[154:157], v[90:93]
	v_mfma_f32_16x16x32_bf16 v[58:61], v[208:211], v[154:157], v[58:61]
	v_mfma_f32_16x16x32_bf16 v[26:29], v[216:219], v[154:157], v[26:29]
	s_add_u32 m0, m0, 0x400
	v_add_u32_e32 v226, 0x10000, v224
	global_load_lds_dwordx4 v226, s[18:19]
	v_mfma_f32_16x16x32_bf16 v[118:121], v[196:199], v[158:161], v[118:121]
	v_mfma_f32_16x16x32_bf16 v[90:93], v[204:207], v[158:161], v[90:93]
	v_mfma_f32_16x16x32_bf16 v[58:61], v[212:215], v[158:161], v[58:61]
	v_mfma_f32_16x16x32_bf16 v[26:29], v[220:223], v[158:161], v[26:29]
	s_add_u32 m0, m0, 0x400
	v_add_u32_e32 v226, 0x14000, v224
	global_load_lds_dwordx4 v226, s[18:19]
	ds_read_b128 v[154:157], v229 offset:8192
	ds_read_b128 v[158:161], v230 offset:8192
	s_waitcnt lgkmcnt(2)
	v_mfma_f32_16x16x32_bf16 v[110:113], v[192:195], v[162:165], v[110:113]
	v_mfma_f32_16x16x32_bf16 v[78:81], v[200:203], v[162:165], v[78:81]
	v_mfma_f32_16x16x32_bf16 v[46:49], v[208:211], v[162:165], v[46:49]
	v_mfma_f32_16x16x32_bf16 v[18:21], v[216:219], v[162:165], v[18:21]
	s_add_u32 m0, m0, 0x400
	v_add_u32_e32 v226, 0x18000, v224
	global_load_lds_dwordx4 v226, s[18:19]
	v_mfma_f32_16x16x32_bf16 v[110:113], v[196:199], v[166:169], v[110:113]
	v_mfma_f32_16x16x32_bf16 v[78:81], v[204:207], v[166:169], v[78:81]
	v_mfma_f32_16x16x32_bf16 v[46:49], v[212:215], v[166:169], v[46:49]
	v_mfma_f32_16x16x32_bf16 v[18:21], v[220:223], v[166:169], v[18:21]
	s_add_u32 m0, m0, 0x400
	v_add_u32_e32 v226, 0x1c000, v224
	global_load_lds_dwordx4 v226, s[18:19]
	ds_read_b128 v[162:165], v229 offset:10240
	ds_read_b128 v[166:169], v230 offset:10240
	s_waitcnt lgkmcnt(2)
	v_mfma_f32_16x16x32_bf16 v[106:109], v[192:195], v[154:157], v[106:109]
	v_mfma_f32_16x16x32_bf16 v[74:77], v[200:203], v[154:157], v[74:77]
	v_mfma_f32_16x16x32_bf16 v[42:45], v[208:211], v[154:157], v[42:45]
	v_mfma_f32_16x16x32_bf16 v[14:17], v[216:219], v[154:157], v[14:17]
	s_add_u32 m0, s25, 17
	s_and_b32 m0, m0, 1
	s_lshl_b32 m0, m0, 14
	s_add_u32 m0, m0, 0x8000
	v_readfirstlane_b32 s32, v145
	s_lshl_b32 s32, s32, 2
	s_add_u32 m0, m0, s32
	v_mov_b32_e32 v226, v225
	global_load_lds_dwordx4 v226, s[18:19]
	v_mfma_f32_16x16x32_bf16 v[106:109], v[196:199], v[158:161], v[106:109]
	v_mfma_f32_16x16x32_bf16 v[74:77], v[204:207], v[158:161], v[74:77]
	v_mfma_f32_16x16x32_bf16 v[42:45], v[212:215], v[158:161], v[42:45]
	v_mfma_f32_16x16x32_bf16 v[14:17], v[220:223], v[158:161], v[14:17]
	s_add_u32 m0, m0, 0x400
	v_add_u32_e32 v226, 0x4000, v225
	global_load_lds_dwordx4 v226, s[18:19]
	ds_read_b128 v[154:157], v229 offset:12288
	ds_read_b128 v[158:161], v230 offset:12288
	s_waitcnt lgkmcnt(2)
	v_mfma_f32_16x16x32_bf16 v[98:101], v[192:195], v[162:165], v[98:101]
	v_mfma_f32_16x16x32_bf16 v[66:69], v[200:203], v[162:165], v[66:69]
	v_mfma_f32_16x16x32_bf16 v[34:37], v[208:211], v[162:165], v[34:37]
	v_mfma_f32_16x16x32_bf16 v[10:13], v[216:219], v[162:165], v[10:13]
	s_add_u32 m0, m0, 0x400
	v_add_u32_e32 v226, 0x8000, v225
	global_load_lds_dwordx4 v226, s[18:19]
	v_mfma_f32_16x16x32_bf16 v[98:101], v[196:199], v[166:169], v[98:101]
	v_mfma_f32_16x16x32_bf16 v[66:69], v[204:207], v[166:169], v[66:69]
	v_mfma_f32_16x16x32_bf16 v[34:37], v[212:215], v[166:169], v[34:37]
	v_mfma_f32_16x16x32_bf16 v[10:13], v[220:223], v[166:169], v[10:13]
	s_add_u32 m0, m0, 0x400
	v_add_u32_e32 v226, 0xc000, v225
	global_load_lds_dwordx4 v226, s[18:19]
	ds_read_b128 v[162:165], v229 offset:14336
	ds_read_b128 v[166:169], v230 offset:14336
	s_waitcnt lgkmcnt(2)
	v_mfma_f32_16x16x32_bf16 v[94:97], v[192:195], v[154:157], v[94:97]
	v_mfma_f32_16x16x32_bf16 v[62:65], v[200:203], v[154:157], v[62:65]
	v_mfma_f32_16x16x32_bf16 v[30:33], v[208:211], v[154:157], v[30:33]
	v_mfma_f32_16x16x32_bf16 v[6:9], v[216:219], v[154:157], v[6:9]
	v_mfma_f32_16x16x32_bf16 v[94:97], v[196:199], v[158:161], v[94:97]
	v_mfma_f32_16x16x32_bf16 v[62:65], v[204:207], v[158:161], v[62:65]
	v_mfma_f32_16x16x32_bf16 v[30:33], v[212:215], v[158:161], v[30:33]
	v_mfma_f32_16x16x32_bf16 v[6:9], v[220:223], v[158:161], v[6:9]
	s_waitcnt lgkmcnt(0)
	v_mfma_f32_16x16x32_bf16 v[82:85], v[192:195], v[162:165], v[82:85]
	v_mfma_f32_16x16x32_bf16 v[50:53], v[200:203], v[162:165], v[50:53]
	v_mfma_f32_16x16x32_bf16 v[22:25], v[208:211], v[162:165], v[22:25]
	v_mfma_f32_16x16x32_bf16 v[2:5], v[216:219], v[162:165], v[2:5]
	v_mfma_f32_16x16x32_bf16 v[82:85], v[196:199], v[166:169], v[82:85]
	v_mfma_f32_16x16x32_bf16 v[50:53], v[204:207], v[166:169], v[50:53]
	v_mfma_f32_16x16x32_bf16 v[22:25], v[212:215], v[166:169], v[22:25]
	v_mfma_f32_16x16x32_bf16 v[2:5], v[220:223], v[166:169], v[2:5]
	v_xor_b32_e32 v229, 0x4000, v229
	v_xor_b32_e32 v230, 0x4000, v230
	s_add_i32 s25, s25, 1
	s_cmp_lg_u32 s25, 15
	s_cbranch_scc1 .Lbk64_530
	s_waitcnt vmcnt(0)
	s_barrier
	ds_read_b128 v[192:195], v227
	ds_read_b128 v[196:199], v228
	ds_read_b128 v[200:203], v227 offset:2048
	ds_read_b128 v[204:207], v228 offset:2048
	ds_read_b128 v[208:211], v227 offset:4096
	ds_read_b128 v[212:215], v228 offset:4096
	ds_read_b128 v[216:219], v227 offset:6144
	ds_read_b128 v[220:223], v228 offset:6144
	s_waitcnt lgkmcnt(0)
	s_barrier
	ds_read_b128 v[154:157], v229 offset:0
	ds_read_b128 v[158:161], v230 offset:0
	ds_read_b128 v[162:165], v229 offset:2048
	ds_read_b128 v[166:169], v230 offset:2048
	s_waitcnt lgkmcnt(2)
	v_mfma_f32_16x16x32_bf16 v[126:129], v[192:195], v[154:157], v[126:129]
	v_mfma_f32_16x16x32_bf16 v[114:117], v[200:203], v[154:157], v[114:117]
	v_mfma_f32_16x16x32_bf16 v[86:89], v[208:211], v[154:157], v[86:89]
	v_mfma_f32_16x16x32_bf16 v[54:57], v[216:219], v[154:157], v[54:57]
	v_mfma_f32_16x16x32_bf16 v[126:129], v[196:199], v[158:161], v[126:129]
	v_mfma_f32_16x16x32_bf16 v[114:117], v[204:207], v[158:161], v[114:117]
	v_mfma_f32_16x16x32_bf16 v[86:89], v[212:215], v[158:161], v[86:89]
	v_mfma_f32_16x16x32_bf16 v[54:57], v[220:223], v[158:161], v[54:57]
	ds_read_b128 v[154:157], v229 offset:4096
	ds_read_b128 v[158:161], v230 offset:4096
	s_waitcnt lgkmcnt(2)
	v_mfma_f32_16x16x32_bf16 v[122:125], v[192:195], v[162:165], v[122:125]
	v_mfma_f32_16x16x32_bf16 v[102:105], v[200:203], v[162:165], v[102:105]
	v_mfma_f32_16x16x32_bf16 v[70:73], v[208:211], v[162:165], v[70:73]
	v_mfma_f32_16x16x32_bf16 v[38:41], v[216:219], v[162:165], v[38:41]
	v_mfma_f32_16x16x32_bf16 v[122:125], v[196:199], v[166:169], v[122:125]
	v_mfma_f32_16x16x32_bf16 v[102:105], v[204:207], v[166:169], v[102:105]
	v_mfma_f32_16x16x32_bf16 v[70:73], v[212:215], v[166:169], v[70:73]
	v_mfma_f32_16x16x32_bf16 v[38:41], v[220:223], v[166:169], v[38:41]
	ds_read_b128 v[162:165], v229 offset:6144
	ds_read_b128 v[166:169], v230 offset:6144
	s_waitcnt lgkmcnt(2)
	v_mfma_f32_16x16x32_bf16 v[118:121], v[192:195], v[154:157], v[118:121]
	v_mfma_f32_16x16x32_bf16 v[90:93], v[200:203], v[154:157], v[90:93]
	v_mfma_f32_16x16x32_bf16 v[58:61], v[208:211], v[154:157], v[58:61]
	v_mfma_f32_16x16x32_bf16 v[26:29], v[216:219], v[154:157], v[26:29]
	v_mfma_f32_16x16x32_bf16 v[118:121], v[196:199], v[158:161], v[118:121]
	v_mfma_f32_16x16x32_bf16 v[90:93], v[204:207], v[158:161], v[90:93]
	v_mfma_f32_16x16x32_bf16 v[58:61], v[212:215], v[158:161], v[58:61]
	v_mfma_f32_16x16x32_bf16 v[26:29], v[220:223], v[158:161], v[26:29]
	ds_read_b128 v[154:157], v229 offset:8192
	ds_read_b128 v[158:161], v230 offset:8192
	s_waitcnt lgkmcnt(2)
	v_mfma_f32_16x16x32_bf16 v[110:113], v[192:195], v[162:165], v[110:113]
	v_mfma_f32_16x16x32_bf16 v[78:81], v[200:203], v[162:165], v[78:81]
	v_mfma_f32_16x16x32_bf16 v[46:49], v[208:211], v[162:165], v[46:49]
	v_mfma_f32_16x16x32_bf16 v[18:21], v[216:219], v[162:165], v[18:21]
	v_mfma_f32_16x16x32_bf16 v[110:113], v[196:199], v[166:169], v[110:113]
	v_mfma_f32_16x16x32_bf16 v[78:81], v[204:207], v[166:169], v[78:81]
	v_mfma_f32_16x16x32_bf16 v[46:49], v[212:215], v[166:169], v[46:49]
	v_mfma_f32_16x16x32_bf16 v[18:21], v[220:223], v[166:169], v[18:21]
	ds_read_b128 v[162:165], v229 offset:10240
	ds_read_b128 v[166:169], v230 offset:10240
	s_waitcnt lgkmcnt(2)
	v_mfma_f32_16x16x32_bf16 v[106:109], v[192:195], v[154:157], v[106:109]
	v_mfma_f32_16x16x32_bf16 v[74:77], v[200:203], v[154:157], v[74:77]
	v_mfma_f32_16x16x32_bf16 v[42:45], v[208:211], v[154:157], v[42:45]
	v_mfma_f32_16x16x32_bf16 v[14:17], v[216:219], v[154:157], v[14:17]
	v_mfma_f32_16x16x32_bf16 v[106:109], v[196:199], v[158:161], v[106:109]
	v_mfma_f32_16x16x32_bf16 v[74:77], v[204:207], v[158:161], v[74:77]
	v_mfma_f32_16x16x32_bf16 v[42:45], v[212:215], v[158:161], v[42:45]
	v_mfma_f32_16x16x32_bf16 v[14:17], v[220:223], v[158:161], v[14:17]
	ds_read_b128 v[154:157], v229 offset:12288
	ds_read_b128 v[158:161], v230 offset:12288
	s_waitcnt lgkmcnt(2)
	v_mfma_f32_16x16x32_bf16 v[98:101], v[192:195], v[162:165], v[98:101]
	v_mfma_f32_16x16x32_bf16 v[66:69], v[200:203], v[162:165], v[66:69]
	v_mfma_f32_16x16x32_bf16 v[34:37], v[208:211], v[162:165], v[34:37]
	v_mfma_f32_16x16x32_bf16 v[10:13], v[216:219], v[162:165], v[10:13]
	v_mfma_f32_16x16x32_bf16 v[98:101], v[196:199], v[166:169], v[98:101]
	v_mfma_f32_16x16x32_bf16 v[66:69], v[204:207], v[166:169], v[66:69]
	v_mfma_f32_16x16x32_bf16 v[34:37], v[212:215], v[166:169], v[34:37]
	v_mfma_f32_16x16x32_bf16 v[10:13], v[220:223], v[166:169], v[10:13]
	ds_read_b128 v[162:165], v229 offset:14336
	ds_read_b128 v[166:169], v230 offset:14336
	s_waitcnt lgkmcnt(2)
	v_mfma_f32_16x16x32_bf16 v[94:97], v[192:195], v[154:157], v[94:97]
	v_mfma_f32_16x16x32_bf16 v[62:65], v[200:203], v[154:157], v[62:65]
	v_mfma_f32_16x16x32_bf16 v[30:33], v[208:211], v[154:157], v[30:33]
	v_mfma_f32_16x16x32_bf16 v[6:9], v[216:219], v[154:157], v[6:9]
	v_mfma_f32_16x16x32_bf16 v[94:97], v[196:199], v[158:161], v[94:97]
	v_mfma_f32_16x16x32_bf16 v[62:65], v[204:207], v[158:161], v[62:65]
	v_mfma_f32_16x16x32_bf16 v[30:33], v[212:215], v[158:161], v[30:33]
	v_mfma_f32_16x16x32_bf16 v[6:9], v[220:223], v[158:161], v[6:9]
	s_waitcnt lgkmcnt(0)
	v_mfma_f32_16x16x32_bf16 v[82:85], v[192:195], v[162:165], v[82:85]
	v_mfma_f32_16x16x32_bf16 v[50:53], v[200:203], v[162:165], v[50:53]
	v_mfma_f32_16x16x32_bf16 v[22:25], v[208:211], v[162:165], v[22:25]
	v_mfma_f32_16x16x32_bf16 v[2:5], v[216:219], v[162:165], v[2:5]
	v_mfma_f32_16x16x32_bf16 v[82:85], v[196:199], v[166:169], v[82:85]
	v_mfma_f32_16x16x32_bf16 v[50:53], v[204:207], v[166:169], v[50:53]
	v_mfma_f32_16x16x32_bf16 v[22:25], v[212:215], v[166:169], v[22:25]
	v_mfma_f32_16x16x32_bf16 v[2:5], v[220:223], v[166:169], v[2:5]
	s_nop 7
	s_nop 7
	s_waitcnt vmcnt(6)
	v_add_u32_e32 v145, v149, v147
	s_waitcnt vmcnt(0)
	s_waitcnt lgkmcnt(0)
	s_lshl_b32 s18, s16, 7
	s_ashr_i32 s19, s18, 31
	s_lshl_b64 s[18:19], s[18:19], 1
	v_and_b32_e32 v1, 0xfffffc0, v1
	v_lshl_or_b32 v1, v143, 2, v1
	v_mul_lo_u32 v1, v1, s33
	v_lshl_or_b32 v1, v142, 2, v1
	s_lshl_b32 s16, s16, 1
	s_ashr_i32 s17, s16, 31
	s_lshl_b64 s[16:17], s[16:17], 2
	s_add_i32 s24, s24, 1
	v_mov_b64_e32 v[162:163], v[62:63]
	v_mov_b64_e32 v[164:165], v[64:65]
	v_mov_b64_e32 v[166:167], v[30:31]
	v_mov_b64_e32 v[168:169], v[32:33]
	v_mov_b64_e32 v[130:131], v[22:23]
	v_mov_b64_e32 v[132:133], v[24:25]
	s_waitcnt lgkmcnt(0)
	v_mov_b64_e32 v[232:233], v[38:39]
	v_mov_b64_e32 v[234:235], v[40:41]
	v_mov_b64_e32 v[38:39], v[34:35]
	v_mov_b64_e32 v[40:41], v[36:37]
	v_mov_b64_e32 v[34:35], v[2:3]
	v_mov_b64_e32 v[36:37], v[4:5]
	s_nop 2
	v_mov_b32_e32 v2, v170
	v_mov_b64_e32 v[216:217], v[114:115]
	v_mov_b64_e32 v[218:219], v[116:117]
	v_add_u32_e32 v2, s4, v2
	v_ashrrev_i32_e32 v3, 31, v2
	v_lshlrev_b64 v[2:3], 11, v[2:3]
	v_lshl_add_u64 v[2:3], s[8:9], 0, v[2:3]
	v_lshl_add_u64 v[2:3], v[2:3], 0, s[18:19]
	v_mov_b64_e32 v[220:221], v[54:55]
	v_mov_b64_e32 v[222:223], v[56:57]
	v_mov_b64_e32 v[224:225], v[122:123]
	v_mov_b64_e32 v[226:227], v[124:125]
	v_mov_b64_e32 v[228:229], v[102:103]
	v_mov_b64_e32 v[230:231], v[104:105]
	v_mov_b64_e32 v[236:237], v[118:119]
	v_mov_b64_e32 v[238:239], v[120:121]
	v_mov_b64_e32 v[240:241], v[58:59]
	v_mov_b64_e32 v[242:243], v[60:61]
	v_mov_b64_e32 v[244:245], v[26:27]
	v_mov_b64_e32 v[246:247], v[28:29]
	v_mov_b64_e32 v[248:249], v[110:111]
	v_mov_b64_e32 v[250:251], v[112:113]
	v_mov_b64_e32 v[180:181], v[78:79]
	v_mov_b64_e32 v[182:183], v[80:81]
	v_mov_b64_e32 v[154:155], v[46:47]
	v_mov_b64_e32 v[156:157], v[48:49]
	v_mov_b64_e32 v[62:63], v[106:107]
	v_mov_b64_e32 v[64:65], v[108:109]
	v_mov_b64_e32 v[46:47], v[74:75]
	v_mov_b64_e32 v[48:49], v[76:77]
	v_mov_b64_e32 v[74:75], v[98:99]
	v_mov_b64_e32 v[76:77], v[100:101]
	v_mov_b64_e32 v[54:55], v[66:67]
	v_mov_b64_e32 v[56:57], v[68:69]
	v_mov_b64_e32 v[58:59], v[162:163]
	v_mov_b64_e32 v[60:61], v[164:165]
	v_mov_b64_e32 v[66:67], v[50:51]
	v_mov_b64_e32 v[68:69], v[52:53]
	flat_load_dwordx4 v[138:141], v[2:3]
	flat_load_dwordx4 v[122:125], v[2:3] offset:16
	flat_load_dwordx4 v[118:121], v[2:3] offset:32
	flat_load_dwordx4 v[114:117], v[2:3] offset:48
	flat_load_dwordx4 v[110:113], v[2:3] offset:64
	flat_load_dwordx4 v[106:109], v[2:3] offset:80
	flat_load_dwordx4 v[102:105], v[2:3] offset:96
	flat_load_dwordx4 v[98:101], v[2:3] offset:112
	s_waitcnt vmcnt(0) lgkmcnt(0)
	s_barrier
	s_nop 7
	ds_write2_b32 v1, v126, v224 offset1:16
	ds_write2_b32 v1, v127, v225 offset0:68 offset1:84
	ds_write2_b32 v1, v128, v226 offset0:136 offset1:152
	ds_write2_b32 v1, v129, v227 offset0:204 offset1:220
	ds_write2_b32 v1, v236, v248 offset0:32 offset1:48
	ds_write2_b32 v1, v237, v249 offset0:100 offset1:116
	ds_write2_b32 v1, v238, v250 offset0:168 offset1:184
	ds_write2_b32 v1, v239, v251 offset0:236 offset1:252
	v_mov_b64_e32 v[196:197], v[18:19]
	v_mov_b64_e32 v[198:199], v[20:21]
	v_mov_b64_e32 v[78:79], v[94:95]
	v_mov_b64_e32 v[80:81], v[96:97]
	v_add_u32_e32 v135, 0x3000, v1
	v_add_u32_e32 v134, 0x3400, v1
	v_mov_b32_e32 v136, v170
	v_mov_b64_e32 v[50:51], v[130:131]
	v_mov_b64_e32 v[52:53], v[132:133]
	v_lshlrev_b32_e32 v137, 16, v138
	s_nop 1
	v_add_u32_e32 v130, 0x1000, v1
	v_add_u32_e32 v131, 0x1400, v1
	v_add_u32_e32 v132, 0x2000, v1
	v_add_u32_e32 v133, 0x2400, v1
	ds_write2_b32 v130, v216, v228 offset0:64 offset1:80
	ds_write2_b32 v130, v217, v229 offset0:132 offset1:148
	ds_write2_b32 v130, v218, v230 offset0:200 offset1:216
	ds_write2_b32 v131, v219, v231 offset0:12 offset1:28
	ds_write2_b32 v130, v90, v180 offset0:96 offset1:112
	ds_write2_b32 v130, v91, v181 offset0:164 offset1:180
	ds_write2_b32 v130, v92, v182 offset0:232 offset1:248
	ds_write2_b32 v131, v93, v183 offset0:44 offset1:60
	ds_write2_b32 v132, v86, v70 offset0:128 offset1:144
	ds_write2_b32 v132, v87, v71 offset0:196 offset1:212
	ds_write2_b32 v133, v88, v72 offset0:8 offset1:24
	ds_write2_b32 v133, v89, v73 offset0:76 offset1:92
	ds_write2_b32 v132, v240, v154 offset0:160 offset1:176
	ds_write2_b32 v132, v241, v155 offset0:228 offset1:244
	ds_write2_b32 v133, v242, v156 offset0:40 offset1:56
	ds_write2_b32 v133, v243, v157 offset0:108 offset1:124
	ds_write2_b32 v135, v220, v232 offset0:192 offset1:208
	ds_write2_b32 v134, v221, v233 offset0:4 offset1:20
	ds_write2_b32 v134, v222, v234 offset0:72 offset1:88
	ds_write2_b32 v134, v223, v235 offset0:140 offset1:156
	ds_write2_b32 v135, v244, v196 offset0:224 offset1:240
	ds_write2_b32 v134, v245, v197 offset0:36 offset1:52
	ds_write2_b32 v134, v246, v198 offset0:104 offset1:120
	ds_write2_b32 v134, v247, v199 offset0:172 offset1:188
	s_waitcnt lgkmcnt(0)
	s_barrier
	v_mov_b64_e32 v[18:19], v[14:15]
	v_mov_b64_e32 v[20:21], v[16:17]
	v_add_u32_e32 v126, s4, v136
	v_ashrrev_i32_e32 v127, 31, v126
	v_lshlrev_b64 v[2:3], 11, v[126:127]
	v_lshl_add_u64 v[2:3], s[8:9], 0, v[2:3]
	v_lshl_add_u64 v[128:129], v[2:3], 0, s[18:19]
	v_mul_lo_u32 v136, v136, s33
	v_mov_b64_e32 v[22:23], v[10:11]
	v_mov_b64_e32 v[24:25], v[12:13]
	v_and_b32_e32 v138, 0xffff0000, v138
	v_mov_b64_e32 v[26:27], v[6:7]
	v_mov_b64_e32 v[28:29], v[8:9]
	flat_load_dwordx4 v[94:97], v[128:129] offset:128
	flat_load_dwordx4 v[90:93], v[128:129] offset:144
	flat_load_dwordx4 v[86:89], v[128:129] offset:160
	flat_load_dwordx4 v[70:73], v[128:129] offset:176
	flat_load_dwordx4 v[14:17], v[128:129] offset:192
	flat_load_dwordx4 v[10:13], v[128:129] offset:208
	flat_load_dwordx4 v[6:9], v[128:129] offset:224
	flat_load_dwordx4 v[2:5], v[128:129] offset:240
	ds_read_b128 v[142:145], v136
	ds_read_b128 v[154:157], v136 offset:16
	s_waitcnt lgkmcnt(0)
	v_add_f32_e32 v137, v142, v137
	v_add_f32_e32 v138, v143, v138
	v_cvt_pk_bf16_f32 v138, v137, v138
	v_lshlrev_b32_e32 v137, 16, v139
	v_and_b32_e32 v139, 0xffff0000, v139
	v_add_f32_e32 v137, v144, v137
	v_add_f32_e32 v139, v145, v139
	v_cvt_pk_bf16_f32 v139, v137, v139
	v_lshlrev_b32_e32 v137, 16, v140
	v_and_b32_e32 v140, 0xffff0000, v140
	v_add_f32_e32 v137, v154, v137
	v_add_f32_e32 v140, v155, v140
	v_cvt_pk_bf16_f32 v140, v137, v140
	v_lshlrev_b32_e32 v137, 16, v141
	v_and_b32_e32 v141, 0xffff0000, v141
	v_add_f32_e32 v137, v156, v137
	v_add_f32_e32 v141, v157, v141
	v_and_b32_e32 v142, 0xffff0000, v138
	v_cvt_pk_bf16_f32 v141, v137, v141
	v_lshlrev_b32_e32 v137, 16, v138
	v_mul_f32_e32 v153, v142, v142
	v_lshlrev_b32_e32 v143, 16, v139
	v_fmac_f32_e32 v153, v137, v137
	v_and_b32_e32 v144, 0xffff0000, v139
	v_fmac_f32_e32 v153, v143, v143
	v_lshlrev_b32_e32 v145, 16, v140
	v_fmac_f32_e32 v153, v144, v144
	flat_store_dwordx4 v[128:129], v[138:141]
	v_and_b32_e32 v147, 0xffff0000, v140
	v_lshlrev_b32_e32 v149, 16, v141
	v_and_b32_e32 v151, 0xffff0000, v141
	v_fmac_f32_e32 v153, v145, v145
	ds_read_b128 v[138:141], v136 offset:32
	ds_read_b128 v[142:145], v136 offset:48
	v_lshlrev_b32_e32 v137, 16, v122
	v_and_b32_e32 v122, 0xffff0000, v122
	v_fmac_f32_e32 v153, v147, v147
	s_waitcnt lgkmcnt(0)
	v_add_f32_e32 v137, v138, v137
	v_add_f32_e32 v122, v139, v122
	v_cvt_pk_bf16_f32 v122, v137, v122
	v_lshlrev_b32_e32 v137, 16, v123
	v_and_b32_e32 v123, 0xffff0000, v123
	v_add_f32_e32 v137, v140, v137
	v_add_f32_e32 v123, v141, v123
	v_cvt_pk_bf16_f32 v123, v137, v123
	v_lshlrev_b32_e32 v137, 16, v124
	v_and_b32_e32 v124, 0xffff0000, v124
	v_add_f32_e32 v137, v142, v137
	v_add_f32_e32 v124, v143, v124
	v_cvt_pk_bf16_f32 v124, v137, v124
	v_lshlrev_b32_e32 v137, 16, v125
	v_and_b32_e32 v125, 0xffff0000, v125
	v_add_f32_e32 v137, v144, v137
	v_add_f32_e32 v125, v145, v125
	v_and_b32_e32 v138, 0xffff0000, v122
	v_cvt_pk_bf16_f32 v125, v137, v125
	v_lshlrev_b32_e32 v137, 16, v122
	v_mul_f32_e32 v138, v138, v138
	v_lshlrev_b32_e32 v139, 16, v123
	v_fmac_f32_e32 v138, v137, v137
	v_and_b32_e32 v140, 0xffff0000, v123
	v_fmac_f32_e32 v138, v139, v139
	v_lshlrev_b32_e32 v141, 16, v124
	v_fmac_f32_e32 v138, v140, v140
	v_and_b32_e32 v142, 0xffff0000, v124
	v_fmac_f32_e32 v138, v141, v141
	v_lshlrev_b32_e32 v143, 16, v125
	v_fmac_f32_e32 v138, v142, v142
	v_fmac_f32_e32 v153, v149, v149
	v_and_b32_e32 v144, 0xffff0000, v125
	v_fmac_f32_e32 v138, v143, v143
	v_fmac_f32_e32 v153, v151, v151
	v_fmac_f32_e32 v138, v144, v144
	flat_store_dwordx4 v[128:129], v[122:125] offset:16
	v_add_f32_e32 v137, v153, v138
	ds_read_b128 v[122:125], v136 offset:64
	ds_read_b128 v[138:141], v136 offset:80
	v_lshlrev_b32_e32 v142, 16, v118
	v_and_b32_e32 v118, 0xffff0000, v118
	v_mov_b64_e32 v[30:31], v[42:43]
	v_mov_b64_e32 v[32:33], v[44:45]
	s_waitcnt lgkmcnt(0)
	v_add_f32_e32 v122, v122, v142
	v_add_f32_e32 v118, v123, v118
	v_cvt_pk_bf16_f32 v118, v122, v118
	v_lshlrev_b32_e32 v122, 16, v119
	v_and_b32_e32 v119, 0xffff0000, v119
	v_add_f32_e32 v122, v124, v122
	v_add_f32_e32 v119, v125, v119
	v_cvt_pk_bf16_f32 v119, v122, v119
	v_lshlrev_b32_e32 v122, 16, v120
	v_and_b32_e32 v120, 0xffff0000, v120
	v_add_f32_e32 v122, v138, v122
	v_add_f32_e32 v120, v139, v120
	v_cvt_pk_bf16_f32 v120, v122, v120
	v_lshlrev_b32_e32 v122, 16, v121
	v_and_b32_e32 v121, 0xffff0000, v121
	v_add_f32_e32 v122, v140, v122
	v_add_f32_e32 v121, v141, v121
	v_and_b32_e32 v123, 0xffff0000, v118
	v_cvt_pk_bf16_f32 v121, v122, v121
	v_lshlrev_b32_e32 v122, 16, v118
	v_mul_f32_e32 v123, v123, v123
	v_lshlrev_b32_e32 v124, 16, v119
	v_fmac_f32_e32 v123, v122, v122
	v_and_b32_e32 v125, 0xffff0000, v119
	v_fmac_f32_e32 v123, v124, v124
	v_lshlrev_b32_e32 v138, 16, v120
	v_fmac_f32_e32 v123, v125, v125
	v_and_b32_e32 v139, 0xffff0000, v120
	v_fmac_f32_e32 v123, v138, v138
	v_lshlrev_b32_e32 v140, 16, v121
	v_fmac_f32_e32 v123, v139, v139
	v_and_b32_e32 v141, 0xffff0000, v121
	v_fmac_f32_e32 v123, v140, v140
	v_fmac_f32_e32 v123, v141, v141
	flat_store_dwordx4 v[128:129], v[118:121] offset:32
	v_add_f32_e32 v137, v137, v123
	ds_read_b128 v[118:121], v136 offset:96
	ds_read_b128 v[122:125], v136 offset:112
	v_lshlrev_b32_e32 v138, 16, v114
	v_and_b32_e32 v114, 0xffff0000, v114
	v_mov_b64_e32 v[42:43], v[166:167]
	v_mov_b64_e32 v[44:45], v[168:169]
	s_waitcnt lgkmcnt(0)
	v_add_f32_e32 v118, v118, v138
	v_add_f32_e32 v114, v119, v114
	v_cvt_pk_bf16_f32 v114, v118, v114
	v_lshlrev_b32_e32 v118, 16, v115
	v_and_b32_e32 v115, 0xffff0000, v115
	v_add_f32_e32 v118, v120, v118
	v_add_f32_e32 v115, v121, v115
	v_cvt_pk_bf16_f32 v115, v118, v115
	v_lshlrev_b32_e32 v118, 16, v116
	v_and_b32_e32 v116, 0xffff0000, v116
	v_add_f32_e32 v118, v122, v118
	v_add_f32_e32 v116, v123, v116
	v_cvt_pk_bf16_f32 v116, v118, v116
	v_lshlrev_b32_e32 v118, 16, v117
	v_and_b32_e32 v117, 0xffff0000, v117
	v_add_f32_e32 v118, v124, v118
	v_add_f32_e32 v117, v125, v117
	v_and_b32_e32 v119, 0xffff0000, v114
	v_cvt_pk_bf16_f32 v117, v118, v117
	v_lshlrev_b32_e32 v118, 16, v114
	v_mul_f32_e32 v119, v119, v119
	v_lshlrev_b32_e32 v120, 16, v115
	v_fmac_f32_e32 v119, v118, v118
	v_and_b32_e32 v121, 0xffff0000, v115
	v_fmac_f32_e32 v119, v120, v120
	v_lshlrev_b32_e32 v122, 16, v116
	v_fmac_f32_e32 v119, v121, v121
	v_and_b32_e32 v123, 0xffff0000, v116
	v_fmac_f32_e32 v119, v122, v122
	v_lshlrev_b32_e32 v124, 16, v117
	v_fmac_f32_e32 v119, v123, v123
	v_and_b32_e32 v125, 0xffff0000, v117
	v_fmac_f32_e32 v119, v124, v124
	v_fmac_f32_e32 v119, v125, v125
	flat_store_dwordx4 v[128:129], v[114:117] offset:48
	v_add_f32_e32 v122, v137, v119
	ds_read_b128 v[114:117], v136 offset:128
	ds_read_b128 v[118:121], v136 offset:144
	v_lshlrev_b32_e32 v123, 16, v110
	v_and_b32_e32 v110, 0xffff0000, v110
	s_waitcnt lgkmcnt(0)
	v_add_f32_e32 v114, v114, v123
	v_add_f32_e32 v110, v115, v110
	v_cvt_pk_bf16_f32 v110, v114, v110
	v_lshlrev_b32_e32 v114, 16, v111
	v_and_b32_e32 v111, 0xffff0000, v111
	v_add_f32_e32 v114, v116, v114
	v_add_f32_e32 v111, v117, v111
	v_cvt_pk_bf16_f32 v111, v114, v111
	v_lshlrev_b32_e32 v114, 16, v112
	v_and_b32_e32 v112, 0xffff0000, v112
	v_add_f32_e32 v114, v118, v114
	v_add_f32_e32 v112, v119, v112
	v_cvt_pk_bf16_f32 v112, v114, v112
	v_lshlrev_b32_e32 v114, 16, v113
	v_and_b32_e32 v113, 0xffff0000, v113
	v_add_f32_e32 v114, v120, v114
	v_add_f32_e32 v113, v121, v113
	v_and_b32_e32 v115, 0xffff0000, v110
	v_cvt_pk_bf16_f32 v113, v114, v113
	v_lshlrev_b32_e32 v114, 16, v110
	v_mul_f32_e32 v115, v115, v115
	v_lshlrev_b32_e32 v116, 16, v111
	v_fmac_f32_e32 v115, v114, v114
	v_and_b32_e32 v117, 0xffff0000, v111
	v_fmac_f32_e32 v115, v116, v116
	v_lshlrev_b32_e32 v118, 16, v112
	v_fmac_f32_e32 v115, v117, v117
	v_and_b32_e32 v119, 0xffff0000, v112
	v_fmac_f32_e32 v115, v118, v118
	v_lshlrev_b32_e32 v120, 16, v113
	v_fmac_f32_e32 v115, v119, v119
	v_and_b32_e32 v121, 0xffff0000, v113
	v_fmac_f32_e32 v115, v120, v120
	v_fmac_f32_e32 v115, v121, v121
	flat_store_dwordx4 v[128:129], v[110:113] offset:64
	v_add_f32_e32 v118, v122, v115
	ds_read_b128 v[110:113], v136 offset:160
	ds_read_b128 v[114:117], v136 offset:176
	v_lshlrev_b32_e32 v119, 16, v106
	v_and_b32_e32 v106, 0xffff0000, v106
	s_waitcnt lgkmcnt(0)
	v_add_f32_e32 v110, v110, v119
	v_add_f32_e32 v106, v111, v106
	v_cvt_pk_bf16_f32 v106, v110, v106
	v_lshlrev_b32_e32 v110, 16, v107
	v_and_b32_e32 v107, 0xffff0000, v107
	v_add_f32_e32 v110, v112, v110
	v_add_f32_e32 v107, v113, v107
	v_cvt_pk_bf16_f32 v107, v110, v107
	v_lshlrev_b32_e32 v110, 16, v108
	v_and_b32_e32 v108, 0xffff0000, v108
	v_add_f32_e32 v110, v114, v110
	v_add_f32_e32 v108, v115, v108
	v_cvt_pk_bf16_f32 v108, v110, v108
	v_lshlrev_b32_e32 v110, 16, v109
	v_and_b32_e32 v109, 0xffff0000, v109
	v_add_f32_e32 v110, v116, v110
	v_add_f32_e32 v109, v117, v109
	v_and_b32_e32 v111, 0xffff0000, v106
	v_cvt_pk_bf16_f32 v109, v110, v109
	v_lshlrev_b32_e32 v110, 16, v106
	v_mul_f32_e32 v111, v111, v111
	v_lshlrev_b32_e32 v112, 16, v107
	v_fmac_f32_e32 v111, v110, v110
	v_and_b32_e32 v113, 0xffff0000, v107
	v_fmac_f32_e32 v111, v112, v112
	v_lshlrev_b32_e32 v114, 16, v108
	v_fmac_f32_e32 v111, v113, v113
	v_and_b32_e32 v115, 0xffff0000, v108
	v_fmac_f32_e32 v111, v114, v114
	v_lshlrev_b32_e32 v116, 16, v109
	v_fmac_f32_e32 v111, v115, v115
	v_and_b32_e32 v117, 0xffff0000, v109
	v_fmac_f32_e32 v111, v116, v116
	v_fmac_f32_e32 v111, v117, v117
	flat_store_dwordx4 v[128:129], v[106:109] offset:80
	v_add_f32_e32 v114, v118, v111
	ds_read_b128 v[106:109], v136 offset:192
	ds_read_b128 v[110:113], v136 offset:208
	v_lshlrev_b32_e32 v115, 16, v102
	v_and_b32_e32 v102, 0xffff0000, v102
	s_waitcnt lgkmcnt(0)
	v_add_f32_e32 v106, v106, v115
	v_add_f32_e32 v102, v107, v102
	v_cvt_pk_bf16_f32 v102, v106, v102
	v_lshlrev_b32_e32 v106, 16, v103
	v_and_b32_e32 v103, 0xffff0000, v103
	v_add_f32_e32 v106, v108, v106
	v_add_f32_e32 v103, v109, v103
	v_cvt_pk_bf16_f32 v103, v106, v103
	v_lshlrev_b32_e32 v106, 16, v104
	v_and_b32_e32 v104, 0xffff0000, v104
	v_add_f32_e32 v106, v110, v106
	v_add_f32_e32 v104, v111, v104
	v_cvt_pk_bf16_f32 v104, v106, v104
	v_lshlrev_b32_e32 v106, 16, v105
	v_and_b32_e32 v105, 0xffff0000, v105
	v_add_f32_e32 v106, v112, v106
	v_add_f32_e32 v105, v113, v105
	v_and_b32_e32 v107, 0xffff0000, v102
	v_cvt_pk_bf16_f32 v105, v106, v105
	v_lshlrev_b32_e32 v106, 16, v102
	v_mul_f32_e32 v107, v107, v107
	v_lshlrev_b32_e32 v108, 16, v103
	v_fmac_f32_e32 v107, v106, v106
	v_and_b32_e32 v109, 0xffff0000, v103
	v_fmac_f32_e32 v107, v108, v108
	v_lshlrev_b32_e32 v110, 16, v104
	v_fmac_f32_e32 v107, v109, v109
	v_and_b32_e32 v111, 0xffff0000, v104
	v_fmac_f32_e32 v107, v110, v110
	v_lshlrev_b32_e32 v112, 16, v105
	v_fmac_f32_e32 v107, v111, v111
	v_and_b32_e32 v113, 0xffff0000, v105
	v_fmac_f32_e32 v107, v112, v112
	v_fmac_f32_e32 v107, v113, v113
	flat_store_dwordx4 v[128:129], v[102:105] offset:96
	v_add_f32_e32 v110, v114, v107
	ds_read_b128 v[102:105], v136 offset:224
	ds_read_b128 v[106:109], v136 offset:240
	v_lshlrev_b32_e32 v111, 16, v98
	v_and_b32_e32 v98, 0xffff0000, v98
	s_waitcnt lgkmcnt(0)
	v_add_f32_e32 v102, v102, v111
	v_add_f32_e32 v98, v103, v98
	v_cvt_pk_bf16_f32 v98, v102, v98
	v_lshlrev_b32_e32 v102, 16, v99
	v_and_b32_e32 v99, 0xffff0000, v99
	v_add_f32_e32 v102, v104, v102
	v_add_f32_e32 v99, v105, v99
	v_cvt_pk_bf16_f32 v99, v102, v99
	v_lshlrev_b32_e32 v102, 16, v100
	v_and_b32_e32 v100, 0xffff0000, v100
	v_add_f32_e32 v102, v106, v102
	v_add_f32_e32 v100, v107, v100
	v_cvt_pk_bf16_f32 v100, v102, v100
	v_lshlrev_b32_e32 v102, 16, v101
	v_and_b32_e32 v101, 0xffff0000, v101
	v_add_f32_e32 v102, v108, v102
	v_add_f32_e32 v101, v109, v101
	v_and_b32_e32 v103, 0xffff0000, v98
	v_cvt_pk_bf16_f32 v101, v102, v101
	v_lshlrev_b32_e32 v102, 16, v98
	v_mul_f32_e32 v103, v103, v103
	v_lshlrev_b32_e32 v104, 16, v99
	v_fmac_f32_e32 v103, v102, v102
	v_and_b32_e32 v105, 0xffff0000, v99
	v_fmac_f32_e32 v103, v104, v104
	v_lshlrev_b32_e32 v106, 16, v100
	v_fmac_f32_e32 v103, v105, v105
	v_and_b32_e32 v107, 0xffff0000, v100
	v_fmac_f32_e32 v103, v106, v106
	v_lshlrev_b32_e32 v108, 16, v101
	v_fmac_f32_e32 v103, v107, v107
	v_and_b32_e32 v109, 0xffff0000, v101
	v_fmac_f32_e32 v103, v108, v108
	flat_store_dwordx4 v[128:129], v[98:101] offset:112
	v_fmac_f32_e32 v103, v109, v109
	v_add_f32_e32 v102, v110, v103
	v_lshlrev_b64 v[98:99], 6, v[126:127]
	v_lshl_add_u64 v[98:99], s[6:7], 0, v[98:99]
	v_lshl_add_u64 v[98:99], v[98:99], 0, s[16:17]
	flat_store_dword v[98:99], v102
	s_waitcnt lgkmcnt(0)
	s_barrier
	ds_write2_b32 v1, v62, v74 offset1:16
	ds_write2_b32 v1, v63, v75 offset0:68 offset1:84
	ds_write2_b32 v1, v64, v76 offset0:136 offset1:152
	ds_write2_b32 v1, v65, v77 offset0:204 offset1:220
	ds_write2_b32 v1, v78, v82 offset0:32 offset1:48
	ds_write2_b32 v1, v79, v83 offset0:100 offset1:116
	ds_write2_b32 v1, v80, v84 offset0:168 offset1:184
	ds_write2_b32 v1, v81, v85 offset0:236 offset1:252
	ds_write2_b32 v130, v46, v54 offset0:64 offset1:80
	ds_write2_b32 v130, v47, v55 offset0:132 offset1:148
	ds_write2_b32 v130, v48, v56 offset0:200 offset1:216
	ds_write2_b32 v131, v49, v57 offset0:12 offset1:28
	ds_write2_b32 v130, v58, v66 offset0:96 offset1:112
	ds_write2_b32 v130, v59, v67 offset0:164 offset1:180
	ds_write2_b32 v130, v60, v68 offset0:232 offset1:248
	ds_write2_b32 v131, v61, v69 offset0:44 offset1:60
	ds_write2_b32 v132, v30, v38 offset0:128 offset1:144
	ds_write2_b32 v132, v31, v39 offset0:196 offset1:212
	ds_write2_b32 v133, v32, v40 offset0:8 offset1:24
	ds_write2_b32 v133, v33, v41 offset0:76 offset1:92
	ds_write2_b32 v132, v42, v50 offset0:160 offset1:176
	ds_write2_b32 v132, v43, v51 offset0:228 offset1:244
	ds_write2_b32 v133, v44, v52 offset0:40 offset1:56
	ds_write2_b32 v133, v45, v53 offset0:108 offset1:124
	ds_write2_b32 v135, v18, v22 offset0:192 offset1:208
	ds_write2_b32 v134, v19, v23 offset0:4 offset1:20
	ds_write2_b32 v134, v20, v24 offset0:72 offset1:88
	ds_write2_b32 v134, v21, v25 offset0:140 offset1:156
	ds_write2_b32 v135, v26, v34 offset0:224 offset1:240
	ds_write2_b32 v134, v27, v35 offset0:36 offset1:52
	ds_write2_b32 v134, v28, v36 offset0:104 offset1:120
	ds_write2_b32 v134, v29, v37 offset0:172 offset1:188
	v_mov_b32_e32 v1, v170
	s_waitcnt lgkmcnt(0)
	s_barrier
	s_waitcnt vmcnt(0)
	v_lshlrev_b32_e32 v28, 16, v94
	v_add_u32_e32 v18, s4, v1
	v_ashrrev_i32_e32 v19, 31, v18
	v_lshlrev_b64 v[20:21], 11, v[18:19]
	v_lshl_add_u64 v[20:21], s[38:39], 0, v[20:21]
	v_mul_lo_u32 v1, v1, s33
	v_lshl_add_u64 v[32:33], v[20:21], 0, s[18:19]
	ds_read_b128 v[20:23], v1
	ds_read_b128 v[24:27], v1 offset:16
	s_mov_b64 s[4:5], 0
	s_waitcnt lgkmcnt(1)
	v_add_f32_e32 v20, v20, v28
	v_and_b32_e32 v28, 0xffff0000, v94
	v_add_f32_e32 v21, v21, v28
	v_cvt_pk_bf16_f32 v28, v20, v21
	v_and_b32_e32 v21, 0xffff0000, v95
	v_lshlrev_b32_e32 v20, 16, v95
	v_add_f32_e32 v21, v23, v21
	v_add_f32_e32 v20, v22, v20
	v_cvt_pk_bf16_f32 v29, v20, v21
	v_and_b32_e32 v21, 0xffff0000, v96
	v_lshlrev_b32_e32 v20, 16, v96
	s_waitcnt lgkmcnt(0)
	v_add_f32_e32 v21, v25, v21
	v_add_f32_e32 v20, v24, v20
	v_cvt_pk_bf16_f32 v30, v20, v21
	v_and_b32_e32 v21, 0xffff0000, v97
	v_lshlrev_b32_e32 v20, 16, v97
	v_add_f32_e32 v21, v27, v21
	v_add_f32_e32 v20, v26, v20
	v_cvt_pk_bf16_f32 v31, v20, v21
	v_and_b32_e32 v21, 0xffff0000, v28
	v_lshlrev_b32_e32 v20, 16, v28
	v_mul_f32_e32 v34, v21, v21
	v_lshlrev_b32_e32 v22, 16, v29
	v_fmac_f32_e32 v34, v20, v20
	v_and_b32_e32 v23, 0xffff0000, v29
	v_fmac_f32_e32 v34, v22, v22
	v_lshlrev_b32_e32 v24, 16, v30
	v_fmac_f32_e32 v34, v23, v23
	v_and_b32_e32 v25, 0xffff0000, v30
	v_fmac_f32_e32 v34, v24, v24
	v_add_co_u32_e32 v20, vcc, s90, v32
	v_lshlrev_b32_e32 v26, 16, v31
	v_fmac_f32_e32 v34, v25, v25
	v_addc_co_u32_e32 v21, vcc, 0, v33, vcc
	v_and_b32_e32 v27, 0xffff0000, v31
	v_fmac_f32_e32 v34, v26, v26
	flat_store_dwordx4 v[20:21], v[28:31] offset:128
	v_fmac_f32_e32 v34, v27, v27
	ds_read_b128 v[22:25], v1 offset:32
	ds_read_b128 v[26:29], v1 offset:48
	v_lshlrev_b32_e32 v30, 16, v90
	s_waitcnt lgkmcnt(0)
	v_add_f32_e32 v22, v22, v30
	v_and_b32_e32 v30, 0xffff0000, v90
	v_add_f32_e32 v23, v23, v30
	v_cvt_pk_bf16_f32 v22, v22, v23
	v_lshlrev_b32_e32 v23, 16, v91
	v_add_f32_e32 v23, v24, v23
	v_and_b32_e32 v24, 0xffff0000, v91
	v_add_f32_e32 v24, v25, v24
	v_cvt_pk_bf16_f32 v23, v23, v24
	v_lshlrev_b32_e32 v24, 16, v92
	v_and_b32_e32 v25, 0xffff0000, v92
	v_add_f32_e32 v24, v26, v24
	v_add_f32_e32 v25, v27, v25
	v_cvt_pk_bf16_f32 v24, v24, v25
	v_lshlrev_b32_e32 v25, 16, v93
	v_and_b32_e32 v26, 0xffff0000, v93
	v_add_f32_e32 v25, v28, v25
	v_add_f32_e32 v26, v29, v26
	v_and_b32_e32 v27, 0xffff0000, v22
	v_cvt_pk_bf16_f32 v25, v25, v26
	v_lshlrev_b32_e32 v26, 16, v22
	v_mul_f32_e32 v27, v27, v27
	v_lshlrev_b32_e32 v28, 16, v23
	v_fmac_f32_e32 v27, v26, v26
	v_and_b32_e32 v29, 0xffff0000, v23
	v_fmac_f32_e32 v27, v28, v28
	v_lshlrev_b32_e32 v30, 16, v24
	v_fmac_f32_e32 v27, v29, v29
	v_and_b32_e32 v31, 0xffff0000, v24
	v_fmac_f32_e32 v27, v30, v30
	v_lshlrev_b32_e32 v32, 16, v25
	v_fmac_f32_e32 v27, v31, v31
	v_and_b32_e32 v33, 0xffff0000, v25
	v_fmac_f32_e32 v27, v32, v32
	v_fmac_f32_e32 v27, v33, v33
	flat_store_dwordx4 v[20:21], v[22:25] offset:144
	v_add_f32_e32 v30, v34, v27
	ds_read_b128 v[22:25], v1 offset:64
	ds_read_b128 v[26:29], v1 offset:80
	v_lshlrev_b32_e32 v31, 16, v86
	s_waitcnt lgkmcnt(0)
	v_add_f32_e32 v22, v22, v31
	v_and_b32_e32 v31, 0xffff0000, v86
	v_add_f32_e32 v23, v23, v31
	v_cvt_pk_bf16_f32 v22, v22, v23
	v_lshlrev_b32_e32 v23, 16, v87
	v_add_f32_e32 v23, v24, v23
	v_and_b32_e32 v24, 0xffff0000, v87
	v_add_f32_e32 v24, v25, v24
	v_cvt_pk_bf16_f32 v23, v23, v24
	v_lshlrev_b32_e32 v24, 16, v88
	v_and_b32_e32 v25, 0xffff0000, v88
	v_add_f32_e32 v24, v26, v24
	v_add_f32_e32 v25, v27, v25
	v_cvt_pk_bf16_f32 v24, v24, v25
	v_lshlrev_b32_e32 v25, 16, v89
	v_and_b32_e32 v26, 0xffff0000, v89
	v_add_f32_e32 v25, v28, v25
	v_add_f32_e32 v26, v29, v26
	v_and_b32_e32 v27, 0xffff0000, v22
	v_cvt_pk_bf16_f32 v25, v25, v26
	v_lshlrev_b32_e32 v26, 16, v22
	v_mul_f32_e32 v27, v27, v27
	v_lshlrev_b32_e32 v28, 16, v23
	v_fmac_f32_e32 v27, v26, v26
	v_and_b32_e32 v29, 0xffff0000, v23
	v_fmac_f32_e32 v27, v28, v28
	v_lshlrev_b32_e32 v31, 16, v24
	v_fmac_f32_e32 v27, v29, v29
	v_and_b32_e32 v32, 0xffff0000, v24
	v_fmac_f32_e32 v27, v31, v31
	v_lshlrev_b32_e32 v33, 16, v25
	v_fmac_f32_e32 v27, v32, v32
	v_and_b32_e32 v34, 0xffff0000, v25
	v_fmac_f32_e32 v27, v33, v33
	v_fmac_f32_e32 v27, v34, v34
	flat_store_dwordx4 v[20:21], v[22:25] offset:160
	v_add_f32_e32 v30, v30, v27
	ds_read_b128 v[22:25], v1 offset:96
	ds_read_b128 v[26:29], v1 offset:112
	v_lshlrev_b32_e32 v31, 16, v70
	s_waitcnt lgkmcnt(0)
	v_add_f32_e32 v22, v22, v31
	v_and_b32_e32 v31, 0xffff0000, v70
	v_add_f32_e32 v23, v23, v31
	v_cvt_pk_bf16_f32 v22, v22, v23
	v_lshlrev_b32_e32 v23, 16, v71
	v_add_f32_e32 v23, v24, v23
	v_and_b32_e32 v24, 0xffff0000, v71
	v_add_f32_e32 v24, v25, v24
	v_cvt_pk_bf16_f32 v23, v23, v24
	v_lshlrev_b32_e32 v24, 16, v72
	v_and_b32_e32 v25, 0xffff0000, v72
	v_add_f32_e32 v24, v26, v24
	v_add_f32_e32 v25, v27, v25
	v_cvt_pk_bf16_f32 v24, v24, v25
	v_lshlrev_b32_e32 v25, 16, v73
	v_and_b32_e32 v26, 0xffff0000, v73
	v_add_f32_e32 v25, v28, v25
	v_add_f32_e32 v26, v29, v26
	v_and_b32_e32 v27, 0xffff0000, v22
	v_cvt_pk_bf16_f32 v25, v25, v26
	v_lshlrev_b32_e32 v26, 16, v22
	v_mul_f32_e32 v27, v27, v27
	v_lshlrev_b32_e32 v28, 16, v23
	v_fmac_f32_e32 v27, v26, v26
	v_and_b32_e32 v29, 0xffff0000, v23
	v_fmac_f32_e32 v27, v28, v28
	v_lshlrev_b32_e32 v31, 16, v24
	v_fmac_f32_e32 v27, v29, v29
	v_and_b32_e32 v32, 0xffff0000, v24
	v_fmac_f32_e32 v27, v31, v31
	v_lshlrev_b32_e32 v33, 16, v25
	v_fmac_f32_e32 v27, v32, v32
	v_and_b32_e32 v34, 0xffff0000, v25
	v_fmac_f32_e32 v27, v33, v33
	v_fmac_f32_e32 v27, v34, v34
	flat_store_dwordx4 v[20:21], v[22:25] offset:176
	v_add_f32_e32 v30, v30, v27
	ds_read_b128 v[22:25], v1 offset:128
	ds_read_b128 v[26:29], v1 offset:144
	v_lshlrev_b32_e32 v31, 16, v14
	v_and_b32_e32 v14, 0xffff0000, v14
	s_waitcnt lgkmcnt(0)
	v_add_f32_e32 v22, v22, v31
	v_add_f32_e32 v14, v23, v14
	v_cvt_pk_bf16_f32 v14, v22, v14
	v_lshlrev_b32_e32 v22, 16, v15
	v_and_b32_e32 v15, 0xffff0000, v15
	v_add_f32_e32 v22, v24, v22
	v_add_f32_e32 v15, v25, v15
	v_cvt_pk_bf16_f32 v15, v22, v15
	v_lshlrev_b32_e32 v22, 16, v16
	v_and_b32_e32 v16, 0xffff0000, v16
	v_add_f32_e32 v22, v26, v22
	v_add_f32_e32 v16, v27, v16
	v_cvt_pk_bf16_f32 v16, v22, v16
	v_lshlrev_b32_e32 v22, 16, v17
	v_and_b32_e32 v17, 0xffff0000, v17
	v_add_f32_e32 v22, v28, v22
	v_add_f32_e32 v17, v29, v17
	v_and_b32_e32 v23, 0xffff0000, v14
	v_cvt_pk_bf16_f32 v17, v22, v17
	v_lshlrev_b32_e32 v22, 16, v14
	v_mul_f32_e32 v23, v23, v23
	v_lshlrev_b32_e32 v24, 16, v15
	v_fmac_f32_e32 v23, v22, v22
	v_and_b32_e32 v25, 0xffff0000, v15
	v_fmac_f32_e32 v23, v24, v24
	v_lshlrev_b32_e32 v26, 16, v16
	v_fmac_f32_e32 v23, v25, v25
	v_and_b32_e32 v27, 0xffff0000, v16
	v_fmac_f32_e32 v23, v26, v26
	v_lshlrev_b32_e32 v28, 16, v17
	v_fmac_f32_e32 v23, v27, v27
	v_and_b32_e32 v29, 0xffff0000, v17
	v_fmac_f32_e32 v23, v28, v28
	v_fmac_f32_e32 v23, v29, v29
	flat_store_dwordx4 v[20:21], v[14:17] offset:192
	v_add_f32_e32 v26, v30, v23
	ds_read_b128 v[14:17], v1 offset:160
	ds_read_b128 v[22:25], v1 offset:176
	v_lshlrev_b32_e32 v27, 16, v10
	v_and_b32_e32 v10, 0xffff0000, v10
	s_waitcnt lgkmcnt(0)
	v_add_f32_e32 v14, v14, v27
	v_add_f32_e32 v10, v15, v10
	v_cvt_pk_bf16_f32 v10, v14, v10
	v_lshlrev_b32_e32 v14, 16, v11
	v_and_b32_e32 v11, 0xffff0000, v11
	v_add_f32_e32 v14, v16, v14
	v_add_f32_e32 v11, v17, v11
	v_cvt_pk_bf16_f32 v11, v14, v11
	v_lshlrev_b32_e32 v14, 16, v12
	v_and_b32_e32 v12, 0xffff0000, v12
	v_add_f32_e32 v14, v22, v14
	v_add_f32_e32 v12, v23, v12
	v_cvt_pk_bf16_f32 v12, v14, v12
	v_lshlrev_b32_e32 v14, 16, v13
	v_and_b32_e32 v13, 0xffff0000, v13
	v_add_f32_e32 v14, v24, v14
	v_add_f32_e32 v13, v25, v13
	v_and_b32_e32 v15, 0xffff0000, v10
	v_cvt_pk_bf16_f32 v13, v14, v13
	v_lshlrev_b32_e32 v14, 16, v10
	v_mul_f32_e32 v15, v15, v15
	v_lshlrev_b32_e32 v16, 16, v11
	v_fmac_f32_e32 v15, v14, v14
	v_and_b32_e32 v17, 0xffff0000, v11
	v_fmac_f32_e32 v15, v16, v16
	v_lshlrev_b32_e32 v22, 16, v12
	v_fmac_f32_e32 v15, v17, v17
	v_and_b32_e32 v23, 0xffff0000, v12
	v_fmac_f32_e32 v15, v22, v22
	v_lshlrev_b32_e32 v24, 16, v13
	v_fmac_f32_e32 v15, v23, v23
	v_and_b32_e32 v25, 0xffff0000, v13
	v_fmac_f32_e32 v15, v24, v24
	v_fmac_f32_e32 v15, v25, v25
	flat_store_dwordx4 v[20:21], v[10:13] offset:208
	v_add_f32_e32 v22, v26, v15
	ds_read_b128 v[10:13], v1 offset:192
	ds_read_b128 v[14:17], v1 offset:208
	v_lshlrev_b32_e32 v23, 16, v6
	v_and_b32_e32 v6, 0xffff0000, v6
	s_waitcnt lgkmcnt(0)
	v_add_f32_e32 v10, v10, v23
	v_add_f32_e32 v6, v11, v6
	v_cvt_pk_bf16_f32 v6, v10, v6
	v_lshlrev_b32_e32 v10, 16, v7
	v_and_b32_e32 v7, 0xffff0000, v7
	v_add_f32_e32 v10, v12, v10
	v_add_f32_e32 v7, v13, v7
	v_cvt_pk_bf16_f32 v7, v10, v7
	v_lshlrev_b32_e32 v10, 16, v8
	v_and_b32_e32 v8, 0xffff0000, v8
	v_add_f32_e32 v10, v14, v10
	v_add_f32_e32 v8, v15, v8
	v_cvt_pk_bf16_f32 v8, v10, v8
	v_lshlrev_b32_e32 v10, 16, v9
	v_and_b32_e32 v9, 0xffff0000, v9
	v_add_f32_e32 v10, v16, v10
	v_add_f32_e32 v9, v17, v9
	v_and_b32_e32 v11, 0xffff0000, v6
	v_cvt_pk_bf16_f32 v9, v10, v9
	v_lshlrev_b32_e32 v10, 16, v6
	v_mul_f32_e32 v11, v11, v11
	v_lshlrev_b32_e32 v12, 16, v7
	v_fmac_f32_e32 v11, v10, v10
	v_and_b32_e32 v13, 0xffff0000, v7
	v_fmac_f32_e32 v11, v12, v12
	v_lshlrev_b32_e32 v14, 16, v8
	v_fmac_f32_e32 v11, v13, v13
	v_and_b32_e32 v15, 0xffff0000, v8
	v_fmac_f32_e32 v11, v14, v14
	v_lshlrev_b32_e32 v16, 16, v9
	v_fmac_f32_e32 v11, v15, v15
	v_and_b32_e32 v17, 0xffff0000, v9
	v_fmac_f32_e32 v11, v16, v16
	v_fmac_f32_e32 v11, v17, v17
	flat_store_dwordx4 v[20:21], v[6:9] offset:224
	v_add_f32_e32 v14, v22, v11
	ds_read_b128 v[6:9], v1 offset:224
	ds_read_b128 v[10:13], v1 offset:240
	v_lshlrev_b32_e32 v1, 16, v2
	v_and_b32_e32 v2, 0xffff0000, v2
	s_waitcnt lgkmcnt(0)
	v_add_f32_e32 v1, v6, v1
	v_add_f32_e32 v2, v7, v2
	v_cvt_pk_bf16_f32 v2, v1, v2
	v_lshlrev_b32_e32 v1, 16, v3
	v_and_b32_e32 v3, 0xffff0000, v3
	v_add_f32_e32 v1, v8, v1
	v_add_f32_e32 v3, v9, v3
	v_cvt_pk_bf16_f32 v3, v1, v3
	v_lshlrev_b32_e32 v1, 16, v4
	v_and_b32_e32 v4, 0xffff0000, v4
	v_add_f32_e32 v1, v10, v1
	v_add_f32_e32 v4, v11, v4
	v_cvt_pk_bf16_f32 v4, v1, v4
	v_lshlrev_b32_e32 v1, 16, v5
	v_and_b32_e32 v5, 0xffff0000, v5
	v_add_f32_e32 v1, v12, v1
	v_add_f32_e32 v5, v13, v5
	v_and_b32_e32 v6, 0xffff0000, v2
	v_cvt_pk_bf16_f32 v5, v1, v5
	v_lshlrev_b32_e32 v1, 16, v2
	v_mul_f32_e32 v6, v6, v6
	v_lshlrev_b32_e32 v7, 16, v3
	v_fmac_f32_e32 v6, v1, v1
	v_and_b32_e32 v8, 0xffff0000, v3
	v_fmac_f32_e32 v6, v7, v7
	v_lshlrev_b32_e32 v9, 16, v4
	v_fmac_f32_e32 v6, v8, v8
	v_and_b32_e32 v10, 0xffff0000, v4
	v_fmac_f32_e32 v6, v9, v9
	v_lshlrev_b32_e32 v11, 16, v5
	v_fmac_f32_e32 v6, v10, v10
	v_and_b32_e32 v12, 0xffff0000, v5
	v_fmac_f32_e32 v6, v11, v11
	flat_store_dwordx4 v[20:21], v[2:5] offset:240
	v_fmac_f32_e32 v6, v12, v12
	v_add_f32_e32 v1, v14, v6
	v_lshlrev_b64 v[2:3], 6, v[18:19]
	v_lshl_add_u64 v[2:3], s[6:7], 0, v[2:3]
	v_lshl_add_u64 v[2:3], v[2:3], 0, s[16:17]
	flat_store_dword v[2:3], v1 offset:4
	s_branch .LBB0_522

.LBB0_555:
	s_and_b64 vcc, exec, s[4:5]
	s_cbranch_vccz .LBB0_537
	v_mov_b32_e32 v1, v170
	s_ashr_i32 s31, s30, 31
	v_add_u32_e32 v2, s71, v1
	v_ashrrev_i32_e32 v3, 31, v2
	v_lshlrev_b64 v[2:3], 6, v[2:3]
	v_lshl_add_u64 v[2:3], s[14:15], 0, v[2:3]
	v_mov_b32_e32 v1, v170
	flat_load_dwordx4 v[14:17], v[2:3]
	flat_load_dwordx4 v[10:13], v[2:3] offset:16
	flat_load_dwordx4 v[6:9], v[2:3] offset:32
	s_nop 0
	flat_load_dwordx4 v[2:5], v[2:3] offset:48
	s_lshl_b64 s[6:7], s[30:31], 18
	v_lshlrev_b32_e32 v153, 4, v1
	v_bfe_u32 v51, v1, 2, 4
	v_ashrrev_i32_e32 v30, 2, v1
	v_add_u32_e32 v53, 0x1000, v153
	v_add_u32_e32 v54, 0x2000, v153
	v_add_u32_e32 v56, 0x3000, v153
	v_or_b32_e32 v28, s71, v51
	v_and_b32_e32 v22, -16, v30
	v_ashrrev_i32_e32 v35, 6, v53
	v_ashrrev_i32_e32 v26, 6, v54
	v_ashrrev_i32_e32 v29, 6, v56
	s_add_u32 s4, s57, s6
	v_and_b32_e32 v50, 32, v1
	v_add_u32_e32 v22, v28, v22
	v_and_b32_e32 v24, -16, v35
	v_and_b32_e32 v55, -16, v26
	v_and_b32_e32 v57, -16, v29
	s_addc_u32 s5, s62, s7
	v_bitop3_b32 v18, v153, v50, 48 bitop3:0x6c
	v_mov_b32_e32 v19, v0
	v_ashrrev_i32_e32 v23, 31, v22
	v_add_u32_e32 v24, v24, v28
	v_add_u32_e32 v26, v55, v28
	v_add_u32_e32 v28, v57, v28
	v_lshl_add_u64 v[20:21], s[8:9], 0, v[18:19]
	v_lshlrev_b64 v[22:23], 11, v[22:23]
	v_ashrrev_i32_e32 v25, 31, v24
	v_ashrrev_i32_e32 v27, 31, v26
	v_ashrrev_i32_e32 v29, 31, v28
	v_lshl_add_u64 v[18:19], s[4:5], 0, v[18:19]
	v_readfirstlane_b32 s4, v153
	v_lshrrev_b32_e32 v34, 2, v1
	v_lshl_add_u64 v[22:23], v[20:21], 0, v[22:23]
	v_lshlrev_b64 v[24:25], 11, v[24:25]
	v_lshlrev_b64 v[26:27], 11, v[26:27]
	v_lshlrev_b64 v[28:29], 11, v[28:29]
	s_waitcnt vmcnt(0)
	s_mov_b32 m0, s4
	v_readfirstlane_b32 s4, v53
	v_lshl_add_u64 v[24:25], v[20:21], 0, v[24:25]
	v_lshl_add_u64 v[26:27], v[20:21], 0, v[26:27]
	v_lshl_add_u64 v[20:21], v[20:21], 0, v[28:29]
	v_bfi_b32 v28, 15, v34, v30
	s_mov_b32 m0, s4
	v_readfirstlane_b32 s4, v54
	v_ashrrev_i32_e32 v29, 31, v28
	v_bfi_b32 v34, -16, v35, v34
	v_add_u32_e32 v58, 0x4000, v153
	s_mov_b32 m0, s4
	v_readfirstlane_b32 s4, v56
	v_lshlrev_b64 v[30:31], 11, v[28:29]
	v_ashrrev_i32_e32 v35, 31, v34
	v_add_u32_e32 v59, 0x5000, v153
	s_mov_b32 m0, s4
	v_readfirstlane_b32 s4, v58
	v_lshl_add_u64 v[32:33], v[18:19], 0, v[30:31]
	v_lshlrev_b64 v[36:37], 11, v[34:35]
	v_add_u32_e32 v60, 0x6000, v153
	s_mov_b32 m0, s4
	v_readfirstlane_b32 s4, v59
	v_and_b32_e32 v147, 15, v1
	v_lshl_add_u64 v[18:19], v[18:19], 0, v[36:37]
	v_bfe_u32 v149, v1, 4, 2
	v_lshlrev_b32_e32 v35, 6, v1
	v_lshlrev_b32_e32 v38, 2, v1
	v_add_u32_e32 v61, 0x7000, v153
	s_mov_b32 m0, s4
	v_readfirstlane_b32 s4, v60
	v_lshlrev_b32_e32 v29, 4, v149
	v_and_b32_e32 v40, 0x3c0, v35
	v_lshlrev_b32_e32 v41, 6, v147
	v_and_b32_e32 v42, 32, v38
	v_lshl_add_u64 v[38:39], v[22:23], 0, 64
	v_add_u32_e32 v62, 0x8000, v153
	s_mov_b32 m0, s4
	v_readfirstlane_b32 s4, v61
	v_add_u32_e32 v63, 0x9000, v153
	v_bitop3_b32 v157, v29, v42, v40 bitop3:0x36
	v_bitop3_b32 v151, v29, v42, v41 bitop3:0x36
	v_lshl_add_u64 v[40:41], v[24:25], 0, 64
	s_mov_b32 m0, s4
	v_readfirstlane_b32 s4, v62
	v_add_u32_e32 v64, 0xa000, v153
	v_lshl_add_u64 v[42:43], v[26:27], 0, 64
	s_mov_b32 m0, s4
	v_readfirstlane_b32 s4, v63
	v_add_u32_e32 v65, 0xb000, v153
	v_lshl_add_u64 v[44:45], v[20:21], 0, 64
	s_mov_b32 m0, s4
	v_readfirstlane_b32 s4, v64
	v_lshl_add_u64 v[46:47], v[32:33], 0, 64
	s_mov_b32 m0, s4
	v_readfirstlane_b32 s4, v65
	v_lshl_add_u64 v[48:49], v[18:19], 0, 64
	s_mov_b32 m0, s4
	v_and_b32_e32 v52, 48, v153
	v_lshl_add_u64 v[18:19], s[6:7], 0, v[36:37]
	v_bitop3_b32 v18, v18, v52, v50 bitop3:0xf6
	v_lshl_add_u64 v[158:159], s[26:27], 0, v[18:19]
	v_lshl_add_u64 v[18:19], s[6:7], 0, v[30:31]
	v_bitop3_b32 v18, v18, v52, v50 bitop3:0xf6
	v_lshl_add_u64 v[160:161], s[26:27], 0, v[18:19]
	v_add3_u32 v18, s71, v57, v51
	v_ashrrev_i32_e32 v19, 31, v18
	v_lshlrev_b64 v[18:19], 11, v[18:19]
	v_bitop3_b32 v18, v18, v52, v50 bitop3:0xf6
	v_lshl_add_u64 v[162:163], s[28:29], 0, v[18:19]
	v_add3_u32 v18, s71, v55, v51
	v_ashrrev_i32_e32 v19, 31, v18
	v_lshlrev_b64 v[18:19], 11, v[18:19]
	v_bitop3_b32 v18, v18, v52, v50 bitop3:0xf6
	v_lshl_add_u64 v[164:165], s[28:29], 0, v[18:19]
	v_add_u32_e32 v18, s71, v34
	v_ashrrev_i32_e32 v19, 31, v18
	v_lshlrev_b64 v[18:19], 11, v[18:19]
	v_bitop3_b32 v18, v18, v52, v50 bitop3:0xf6
	v_lshl_add_u64 v[166:167], s[28:29], 0, v[18:19]
	v_add_u32_e32 v18, s71, v28
	v_ashrrev_i32_e32 v19, 31, v18
	v_lshlrev_b64 v[18:19], 11, v[18:19]
	v_bitop3_b32 v18, v18, v52, v50 bitop3:0xf6
	v_lshl_add_u64 v[168:169], s[28:29], 0, v[18:19]
	v_mov_b32_e32 v18, 0
	v_and_b32_e32 v155, 0xfffff000, v35
	s_mov_b32 s4, 0
	s_mov_b64 s[6:7], 0
	v_mov_b32_e32 v19, v18
	v_mov_b32_e32 v20, v18
	v_mov_b32_e32 v21, v18
	v_mov_b32_e32 v22, v18
	v_mov_b32_e32 v23, v18
	v_mov_b32_e32 v24, v18
	v_mov_b32_e32 v25, v18
	v_mov_b32_e32 v26, v18
	v_mov_b32_e32 v27, v18
	v_mov_b32_e32 v28, v18
	v_mov_b32_e32 v29, v18
	v_mov_b32_e32 v34, v18
	v_mov_b32_e32 v35, v18
	v_mov_b32_e32 v36, v18
	v_mov_b32_e32 v37, v18
	v_mov_b32_e32 v42, v18
	v_mov_b32_e32 v43, v18
	v_mov_b32_e32 v44, v18
	v_mov_b32_e32 v45, v18
	v_mov_b32_e32 v54, v18
	v_mov_b32_e32 v55, v18
	v_mov_b32_e32 v56, v18
	v_mov_b32_e32 v57, v18
	v_mov_b32_e32 v62, v18
	v_mov_b32_e32 v63, v18
	v_mov_b32_e32 v64, v18
	v_mov_b32_e32 v65, v18
	v_mov_b32_e32 v78, v18
	v_mov_b32_e32 v79, v18
	v_mov_b32_e32 v80, v18
	v_mov_b32_e32 v81, v18
	v_mov_b32_e32 v30, v18
	v_mov_b32_e32 v31, v18
	v_mov_b32_e32 v32, v18
	v_mov_b32_e32 v33, v18
	v_mov_b32_e32 v38, v18
	v_mov_b32_e32 v39, v18
	v_mov_b32_e32 v40, v18
	v_mov_b32_e32 v41, v18
	v_mov_b32_e32 v46, v18
	v_mov_b32_e32 v47, v18
	v_mov_b32_e32 v48, v18
	v_mov_b32_e32 v49, v18
	v_mov_b32_e32 v58, v18
	v_mov_b32_e32 v59, v18
	v_mov_b32_e32 v60, v18
	v_mov_b32_e32 v61, v18
	v_mov_b32_e32 v70, v18
	v_mov_b32_e32 v71, v18
	v_mov_b32_e32 v72, v18
	v_mov_b32_e32 v73, v18
	v_mov_b32_e32 v86, v18
	v_mov_b32_e32 v87, v18
	v_mov_b32_e32 v88, v18
	v_mov_b32_e32 v89, v18
	v_mov_b32_e32 v94, v18
	v_mov_b32_e32 v95, v18
	v_mov_b32_e32 v96, v18
	v_mov_b32_e32 v97, v18
	v_mov_b32_e32 v110, v18
	v_mov_b32_e32 v111, v18
	v_mov_b32_e32 v112, v18
	v_mov_b32_e32 v113, v18
	v_mov_b32_e32 v50, v18
	v_mov_b32_e32 v51, v18
	v_mov_b32_e32 v52, v18
	v_mov_b32_e32 v53, v18
	v_mov_b32_e32 v66, v18
	v_mov_b32_e32 v67, v18
	v_mov_b32_e32 v68, v18
	v_mov_b32_e32 v69, v18
	v_mov_b32_e32 v74, v18
	v_mov_b32_e32 v75, v18
	v_mov_b32_e32 v76, v18
	v_mov_b32_e32 v77, v18
	v_mov_b32_e32 v90, v18
	v_mov_b32_e32 v91, v18
	v_mov_b32_e32 v92, v18
	v_mov_b32_e32 v93, v18
	v_mov_b32_e32 v102, v18
	v_mov_b32_e32 v103, v18
	v_mov_b32_e32 v104, v18
	v_mov_b32_e32 v105, v18
	v_mov_b32_e32 v114, v18
	v_mov_b32_e32 v115, v18
	v_mov_b32_e32 v116, v18
	v_mov_b32_e32 v117, v18
	v_mov_b32_e32 v122, v18
	v_mov_b32_e32 v123, v18
	v_mov_b32_e32 v124, v18
	v_mov_b32_e32 v125, v18
	v_mov_b32_e32 v130, v18
	v_mov_b32_e32 v131, v18
	v_mov_b32_e32 v132, v18
	v_mov_b32_e32 v133, v18
	v_mov_b32_e32 v82, v18
	v_mov_b32_e32 v83, v18
	v_mov_b32_e32 v84, v18
	v_mov_b32_e32 v85, v18
	v_mov_b32_e32 v98, v18
	v_mov_b32_e32 v99, v18
	v_mov_b32_e32 v100, v18
	v_mov_b32_e32 v101, v18
	v_mov_b32_e32 v106, v18
	v_mov_b32_e32 v107, v18
	v_mov_b32_e32 v108, v18
	v_mov_b32_e32 v109, v18
	v_mov_b32_e32 v118, v18
	v_mov_b32_e32 v119, v18
	v_mov_b32_e32 v120, v18
	v_mov_b32_e32 v121, v18
	v_mov_b32_e32 v126, v18
	v_mov_b32_e32 v127, v18
	v_mov_b32_e32 v128, v18
	v_mov_b32_e32 v129, v18
	v_mov_b32_e32 v134, v18
	v_mov_b32_e32 v135, v18
	v_mov_b32_e32 v136, v18
	v_mov_b32_e32 v137, v18
	v_mov_b32_e32 v138, v18
	v_mov_b32_e32 v139, v18
	v_mov_b32_e32 v140, v18
	v_mov_b32_e32 v141, v18
	v_mov_b32_e32 v142, v18
	v_mov_b32_e32 v143, v18
	v_mov_b32_e32 v144, v18
	v_mov_b32_e32 v145, v18
	v_and_b32_e32 v224, 63, v170
	v_lshrrev_b32_e32 v225, 3, v224
	v_and_b32_e32 v226, 7, v224
	v_xor_b32_e32 v226, v226, v225
	v_lshrrev_b32_e32 v227, 6, v170
	v_lshl_add_u32 v228, v227, 6, v225
	v_add_u32_e32 v228, s71, v228
	v_mul_u32_u24_e32 v240, 0x800, v228
	v_lshl_add_u32 v240, v226, 4, v240
	v_lshl_add_u32 v228, v227, 5, v225
	v_mul_u32_u24_e32 v241, 0x800, v228
	v_lshl_add_u32 v241, v226, 4, v241
	v_and_b32_e32 v225, 15, v224
	v_lshrrev_b32_e32 v226, 4, v224
	v_and_b32_e32 v228, 7, v225
	v_xor_b32_e32 v226, v226, v228
	v_lshlrev_b32_e32 v226, 4, v226
	v_lshl_add_u32 v245, v225, 7, v226
	v_lshl_add_u32 v243, v227, 13, v245
	v_xor_b32_e32 v244, 64, v243
	v_add_u32_e32 v245, 0x8000, v245
	v_xor_b32_e32 v246, 64, v245
	s_mov_b32 s4, s8
	s_mov_b32 s5, s9
	s_lshl_b32 s32, s30, 18
	s_add_u32 s6, s57, s32
	s_addc_u32 s7, s62, 0
	s_mov_b32 s31, 0
	v_readfirstlane_b32 s32, v153
	s_lshl_b32 m0, s32, 3
	v_mov_b32_e32 v242, v240
	global_load_lds_dwordx4 v242, s[4:5]
	s_add_u32 m0, m0, 0x400
	v_add_u32_e32 v242, 0x4000, v240
	global_load_lds_dwordx4 v242, s[4:5]
	s_add_u32 m0, m0, 0x400
	v_add_u32_e32 v242, 0x8000, v240
	global_load_lds_dwordx4 v242, s[4:5]
	s_add_u32 m0, m0, 0x400
	v_add_u32_e32 v242, 0xc000, v240
	global_load_lds_dwordx4 v242, s[4:5]
	s_add_u32 m0, m0, 0x400
	v_add_u32_e32 v242, 0x10000, v240
	global_load_lds_dwordx4 v242, s[4:5]
	s_add_u32 m0, m0, 0x400
	v_add_u32_e32 v242, 0x14000, v240
	global_load_lds_dwordx4 v242, s[4:5]
	s_add_u32 m0, m0, 0x400
	v_add_u32_e32 v242, 0x18000, v240
	global_load_lds_dwordx4 v242, s[4:5]
	s_add_u32 m0, m0, 0x400
	v_add_u32_e32 v242, 0x1c000, v240
	global_load_lds_dwordx4 v242, s[4:5]
	v_readfirstlane_b32 s32, v153
	s_lshl_b32 s32, s32, 2
	s_add_u32 m0, s32, 0x8000
	v_mov_b32_e32 v242, v241
	global_load_lds_dwordx4 v242, s[6:7]
	s_add_u32 m0, m0, 0x400
	v_add_u32_e32 v242, 0x4000, v241
	global_load_lds_dwordx4 v242, s[6:7]
	s_add_u32 m0, m0, 0x400
	v_add_u32_e32 v242, 0x8000, v241
	global_load_lds_dwordx4 v242, s[6:7]
	s_add_u32 m0, m0, 0x400
	v_add_u32_e32 v242, 0xc000, v241
	global_load_lds_dwordx4 v242, s[6:7]
.Lbk64_557:
	s_waitcnt vmcnt(0)
	s_barrier
	ds_read_b128 v[192:195], v243
	ds_read_b128 v[196:199], v244
	ds_read_b128 v[200:203], v243 offset:2048
	ds_read_b128 v[204:207], v244 offset:2048
	ds_read_b128 v[208:211], v243 offset:4096
	ds_read_b128 v[212:215], v244 offset:4096
	ds_read_b128 v[216:219], v243 offset:6144
	ds_read_b128 v[220:223], v244 offset:6144
	s_add_u32 s4, s4, 0x80
	s_addc_u32 s5, s5, 0
	s_add_u32 s6, s6, 0x80
	s_addc_u32 s7, s7, 0
	s_waitcnt lgkmcnt(0)
	s_barrier
	ds_read_b128 v[224:227], v245 offset:0
	ds_read_b128 v[228:231], v246 offset:0
	ds_read_b128 v[232:235], v245 offset:2048
	ds_read_b128 v[236:239], v246 offset:2048
	s_waitcnt lgkmcnt(2)
	v_mfma_f32_16x16x32_bf16 v[142:145], v[192:195], v[224:227], v[142:145]
	v_mfma_f32_16x16x32_bf16 v[130:133], v[200:203], v[224:227], v[130:133]
	v_mfma_f32_16x16x32_bf16 v[110:113], v[208:211], v[224:227], v[110:113]
	v_mfma_f32_16x16x32_bf16 v[78:81], v[216:219], v[224:227], v[78:81]
	v_readfirstlane_b32 s32, v153
	s_lshl_b32 m0, s32, 3
	v_mov_b32_e32 v242, v240
	global_load_lds_dwordx4 v242, s[4:5]
	v_mfma_f32_16x16x32_bf16 v[142:145], v[196:199], v[228:231], v[142:145]
	v_mfma_f32_16x16x32_bf16 v[130:133], v[204:207], v[228:231], v[130:133]
	v_mfma_f32_16x16x32_bf16 v[110:113], v[212:215], v[228:231], v[110:113]
	v_mfma_f32_16x16x32_bf16 v[78:81], v[220:223], v[228:231], v[78:81]
	s_add_u32 m0, m0, 0x400
	v_add_u32_e32 v242, 0x4000, v240
	global_load_lds_dwordx4 v242, s[4:5]
	ds_read_b128 v[224:227], v245 offset:4096
	ds_read_b128 v[228:231], v246 offset:4096
	s_waitcnt lgkmcnt(2)
	v_mfma_f32_16x16x32_bf16 v[138:141], v[192:195], v[232:235], v[138:141]
	v_mfma_f32_16x16x32_bf16 v[122:125], v[200:203], v[232:235], v[122:125]
	v_mfma_f32_16x16x32_bf16 v[94:97], v[208:211], v[232:235], v[94:97]
	v_mfma_f32_16x16x32_bf16 v[62:65], v[216:219], v[232:235], v[62:65]
	s_add_u32 m0, m0, 0x400
	v_add_u32_e32 v242, 0x8000, v240
	global_load_lds_dwordx4 v242, s[4:5]
	v_mfma_f32_16x16x32_bf16 v[138:141], v[196:199], v[236:239], v[138:141]
	v_mfma_f32_16x16x32_bf16 v[122:125], v[204:207], v[236:239], v[122:125]
	v_mfma_f32_16x16x32_bf16 v[94:97], v[212:215], v[236:239], v[94:97]
	v_mfma_f32_16x16x32_bf16 v[62:65], v[220:223], v[236:239], v[62:65]
	s_add_u32 m0, m0, 0x400
	v_add_u32_e32 v242, 0xc000, v240
	global_load_lds_dwordx4 v242, s[4:5]
	ds_read_b128 v[232:235], v245 offset:6144
	ds_read_b128 v[236:239], v246 offset:6144
	s_waitcnt lgkmcnt(2)
	v_mfma_f32_16x16x32_bf16 v[134:137], v[192:195], v[224:227], v[134:137]
	v_mfma_f32_16x16x32_bf16 v[114:117], v[200:203], v[224:227], v[114:117]
	v_mfma_f32_16x16x32_bf16 v[86:89], v[208:211], v[224:227], v[86:89]
	v_mfma_f32_16x16x32_bf16 v[54:57], v[216:219], v[224:227], v[54:57]
	s_add_u32 m0, m0, 0x400
	v_add_u32_e32 v242, 0x10000, v240
	global_load_lds_dwordx4 v242, s[4:5]
	v_mfma_f32_16x16x32_bf16 v[134:137], v[196:199], v[228:231], v[134:137]
	v_mfma_f32_16x16x32_bf16 v[114:117], v[204:207], v[228:231], v[114:117]
	v_mfma_f32_16x16x32_bf16 v[86:89], v[212:215], v[228:231], v[86:89]
	v_mfma_f32_16x16x32_bf16 v[54:57], v[220:223], v[228:231], v[54:57]
	s_add_u32 m0, m0, 0x400
	v_add_u32_e32 v242, 0x14000, v240
	global_load_lds_dwordx4 v242, s[4:5]
	ds_read_b128 v[224:227], v245 offset:8192
	ds_read_b128 v[228:231], v246 offset:8192
	s_waitcnt lgkmcnt(2)
	v_mfma_f32_16x16x32_bf16 v[126:129], v[192:195], v[232:235], v[126:129]
	v_mfma_f32_16x16x32_bf16 v[102:105], v[200:203], v[232:235], v[102:105]
	v_mfma_f32_16x16x32_bf16 v[70:73], v[208:211], v[232:235], v[70:73]
	v_mfma_f32_16x16x32_bf16 v[42:45], v[216:219], v[232:235], v[42:45]
	s_add_u32 m0, m0, 0x400
	v_add_u32_e32 v242, 0x18000, v240
	global_load_lds_dwordx4 v242, s[4:5]
	v_mfma_f32_16x16x32_bf16 v[126:129], v[196:199], v[236:239], v[126:129]
	v_mfma_f32_16x16x32_bf16 v[102:105], v[204:207], v[236:239], v[102:105]
	v_mfma_f32_16x16x32_bf16 v[70:73], v[212:215], v[236:239], v[70:73]
	v_mfma_f32_16x16x32_bf16 v[42:45], v[220:223], v[236:239], v[42:45]
	s_add_u32 m0, m0, 0x400
	v_add_u32_e32 v242, 0x1c000, v240
	global_load_lds_dwordx4 v242, s[4:5]
	ds_read_b128 v[232:235], v245 offset:10240
	ds_read_b128 v[236:239], v246 offset:10240
	s_waitcnt lgkmcnt(2)
	v_mfma_f32_16x16x32_bf16 v[118:121], v[192:195], v[224:227], v[118:121]
	v_mfma_f32_16x16x32_bf16 v[90:93], v[200:203], v[224:227], v[90:93]
	v_mfma_f32_16x16x32_bf16 v[58:61], v[208:211], v[224:227], v[58:61]
	v_mfma_f32_16x16x32_bf16 v[34:37], v[216:219], v[224:227], v[34:37]
	s_add_u32 m0, s31, 17
	s_and_b32 m0, m0, 1
	s_lshl_b32 m0, m0, 14
	s_add_u32 m0, m0, 0x8000
	v_readfirstlane_b32 s32, v153
	s_lshl_b32 s32, s32, 2
	s_add_u32 m0, m0, s32
	v_mov_b32_e32 v242, v241
	global_load_lds_dwordx4 v242, s[6:7]
	v_mfma_f32_16x16x32_bf16 v[118:121], v[196:199], v[228:231], v[118:121]
	v_mfma_f32_16x16x32_bf16 v[90:93], v[204:207], v[228:231], v[90:93]
	v_mfma_f32_16x16x32_bf16 v[58:61], v[212:215], v[228:231], v[58:61]
	v_mfma_f32_16x16x32_bf16 v[34:37], v[220:223], v[228:231], v[34:37]
	s_add_u32 m0, m0, 0x400
	v_add_u32_e32 v242, 0x4000, v241
	global_load_lds_dwordx4 v242, s[6:7]
	ds_read_b128 v[224:227], v245 offset:12288
	ds_read_b128 v[228:231], v246 offset:12288
	s_waitcnt lgkmcnt(2)
	v_mfma_f32_16x16x32_bf16 v[106:109], v[192:195], v[232:235], v[106:109]
	v_mfma_f32_16x16x32_bf16 v[74:77], v[200:203], v[232:235], v[74:77]
	v_mfma_f32_16x16x32_bf16 v[46:49], v[208:211], v[232:235], v[46:49]
	v_mfma_f32_16x16x32_bf16 v[26:29], v[216:219], v[232:235], v[26:29]
	s_add_u32 m0, m0, 0x400
	v_add_u32_e32 v242, 0x8000, v241
	global_load_lds_dwordx4 v242, s[6:7]
	v_mfma_f32_16x16x32_bf16 v[106:109], v[196:199], v[236:239], v[106:109]
	v_mfma_f32_16x16x32_bf16 v[74:77], v[204:207], v[236:239], v[74:77]
	v_mfma_f32_16x16x32_bf16 v[46:49], v[212:215], v[236:239], v[46:49]
	v_mfma_f32_16x16x32_bf16 v[26:29], v[220:223], v[236:239], v[26:29]
	s_add_u32 m0, m0, 0x400
	v_add_u32_e32 v242, 0xc000, v241
	global_load_lds_dwordx4 v242, s[6:7]
	ds_read_b128 v[232:235], v245 offset:14336
	ds_read_b128 v[236:239], v246 offset:14336
	s_waitcnt lgkmcnt(2)
	v_mfma_f32_16x16x32_bf16 v[98:101], v[192:195], v[224:227], v[98:101]
	v_mfma_f32_16x16x32_bf16 v[66:69], v[200:203], v[224:227], v[66:69]
	v_mfma_f32_16x16x32_bf16 v[38:41], v[208:211], v[224:227], v[38:41]
	v_mfma_f32_16x16x32_bf16 v[22:25], v[216:219], v[224:227], v[22:25]
	v_mfma_f32_16x16x32_bf16 v[98:101], v[196:199], v[228:231], v[98:101]
	v_mfma_f32_16x16x32_bf16 v[66:69], v[204:207], v[228:231], v[66:69]
	v_mfma_f32_16x16x32_bf16 v[38:41], v[212:215], v[228:231], v[38:41]
	v_mfma_f32_16x16x32_bf16 v[22:25], v[220:223], v[228:231], v[22:25]
	s_waitcnt lgkmcnt(0)
	v_mfma_f32_16x16x32_bf16 v[82:85], v[192:195], v[232:235], v[82:85]
	v_mfma_f32_16x16x32_bf16 v[50:53], v[200:203], v[232:235], v[50:53]
	v_mfma_f32_16x16x32_bf16 v[30:33], v[208:211], v[232:235], v[30:33]
	v_mfma_f32_16x16x32_bf16 v[18:21], v[216:219], v[232:235], v[18:21]
	v_mfma_f32_16x16x32_bf16 v[82:85], v[196:199], v[236:239], v[82:85]
	v_mfma_f32_16x16x32_bf16 v[50:53], v[204:207], v[236:239], v[50:53]
	v_mfma_f32_16x16x32_bf16 v[30:33], v[212:215], v[236:239], v[30:33]
	v_mfma_f32_16x16x32_bf16 v[18:21], v[220:223], v[236:239], v[18:21]
	v_xor_b32_e32 v245, 0x4000, v245
	v_xor_b32_e32 v246, 0x4000, v246
	s_add_i32 s31, s31, 1
	s_cmp_lg_u32 s31, 15
	s_cbranch_scc1 .Lbk64_557
	s_waitcnt vmcnt(0)
	s_barrier
	ds_read_b128 v[192:195], v243
	ds_read_b128 v[196:199], v244
	ds_read_b128 v[200:203], v243 offset:2048
	ds_read_b128 v[204:207], v244 offset:2048
	ds_read_b128 v[208:211], v243 offset:4096
	ds_read_b128 v[212:215], v244 offset:4096
	ds_read_b128 v[216:219], v243 offset:6144
	ds_read_b128 v[220:223], v244 offset:6144
	s_waitcnt lgkmcnt(0)
	s_barrier
	ds_read_b128 v[224:227], v245 offset:0
	ds_read_b128 v[228:231], v246 offset:0
	ds_read_b128 v[232:235], v245 offset:2048
	ds_read_b128 v[236:239], v246 offset:2048
	s_waitcnt lgkmcnt(2)
	v_mfma_f32_16x16x32_bf16 v[142:145], v[192:195], v[224:227], v[142:145]
	v_mfma_f32_16x16x32_bf16 v[130:133], v[200:203], v[224:227], v[130:133]
	v_mfma_f32_16x16x32_bf16 v[110:113], v[208:211], v[224:227], v[110:113]
	v_mfma_f32_16x16x32_bf16 v[78:81], v[216:219], v[224:227], v[78:81]
	v_mfma_f32_16x16x32_bf16 v[142:145], v[196:199], v[228:231], v[142:145]
	v_mfma_f32_16x16x32_bf16 v[130:133], v[204:207], v[228:231], v[130:133]
	v_mfma_f32_16x16x32_bf16 v[110:113], v[212:215], v[228:231], v[110:113]
	v_mfma_f32_16x16x32_bf16 v[78:81], v[220:223], v[228:231], v[78:81]
	ds_read_b128 v[224:227], v245 offset:4096
	ds_read_b128 v[228:231], v246 offset:4096
	s_waitcnt lgkmcnt(2)
	v_mfma_f32_16x16x32_bf16 v[138:141], v[192:195], v[232:235], v[138:141]
	v_mfma_f32_16x16x32_bf16 v[122:125], v[200:203], v[232:235], v[122:125]
	v_mfma_f32_16x16x32_bf16 v[94:97], v[208:211], v[232:235], v[94:97]
	v_mfma_f32_16x16x32_bf16 v[62:65], v[216:219], v[232:235], v[62:65]
	v_mfma_f32_16x16x32_bf16 v[138:141], v[196:199], v[236:239], v[138:141]
	v_mfma_f32_16x16x32_bf16 v[122:125], v[204:207], v[236:239], v[122:125]
	v_mfma_f32_16x16x32_bf16 v[94:97], v[212:215], v[236:239], v[94:97]
	v_mfma_f32_16x16x32_bf16 v[62:65], v[220:223], v[236:239], v[62:65]
	ds_read_b128 v[232:235], v245 offset:6144
	ds_read_b128 v[236:239], v246 offset:6144
	s_waitcnt lgkmcnt(2)
	v_mfma_f32_16x16x32_bf16 v[134:137], v[192:195], v[224:227], v[134:137]
	v_mfma_f32_16x16x32_bf16 v[114:117], v[200:203], v[224:227], v[114:117]
	v_mfma_f32_16x16x32_bf16 v[86:89], v[208:211], v[224:227], v[86:89]
	v_mfma_f32_16x16x32_bf16 v[54:57], v[216:219], v[224:227], v[54:57]
	v_mfma_f32_16x16x32_bf16 v[134:137], v[196:199], v[228:231], v[134:137]
	v_mfma_f32_16x16x32_bf16 v[114:117], v[204:207], v[228:231], v[114:117]
	v_mfma_f32_16x16x32_bf16 v[86:89], v[212:215], v[228:231], v[86:89]
	v_mfma_f32_16x16x32_bf16 v[54:57], v[220:223], v[228:231], v[54:57]
	ds_read_b128 v[224:227], v245 offset:8192
	ds_read_b128 v[228:231], v246 offset:8192
	s_waitcnt lgkmcnt(2)
	v_mfma_f32_16x16x32_bf16 v[126:129], v[192:195], v[232:235], v[126:129]
	v_mfma_f32_16x16x32_bf16 v[102:105], v[200:203], v[232:235], v[102:105]
	v_mfma_f32_16x16x32_bf16 v[70:73], v[208:211], v[232:235], v[70:73]
	v_mfma_f32_16x16x32_bf16 v[42:45], v[216:219], v[232:235], v[42:45]
	v_mfma_f32_16x16x32_bf16 v[126:129], v[196:199], v[236:239], v[126:129]
	v_mfma_f32_16x16x32_bf16 v[102:105], v[204:207], v[236:239], v[102:105]
	v_mfma_f32_16x16x32_bf16 v[70:73], v[212:215], v[236:239], v[70:73]
	v_mfma_f32_16x16x32_bf16 v[42:45], v[220:223], v[236:239], v[42:45]
	ds_read_b128 v[232:235], v245 offset:10240
	ds_read_b128 v[236:239], v246 offset:10240
	s_waitcnt lgkmcnt(2)
	v_mfma_f32_16x16x32_bf16 v[118:121], v[192:195], v[224:227], v[118:121]
	v_mfma_f32_16x16x32_bf16 v[90:93], v[200:203], v[224:227], v[90:93]
	v_mfma_f32_16x16x32_bf16 v[58:61], v[208:211], v[224:227], v[58:61]
	v_mfma_f32_16x16x32_bf16 v[34:37], v[216:219], v[224:227], v[34:37]
	v_mfma_f32_16x16x32_bf16 v[118:121], v[196:199], v[228:231], v[118:121]
	v_mfma_f32_16x16x32_bf16 v[90:93], v[204:207], v[228:231], v[90:93]
	v_mfma_f32_16x16x32_bf16 v[58:61], v[212:215], v[228:231], v[58:61]
	v_mfma_f32_16x16x32_bf16 v[34:37], v[220:223], v[228:231], v[34:37]
	ds_read_b128 v[224:227], v245 offset:12288
	ds_read_b128 v[228:231], v246 offset:12288
	s_waitcnt lgkmcnt(2)
	v_mfma_f32_16x16x32_bf16 v[106:109], v[192:195], v[232:235], v[106:109]
	v_mfma_f32_16x16x32_bf16 v[74:77], v[200:203], v[232:235], v[74:77]
	v_mfma_f32_16x16x32_bf16 v[46:49], v[208:211], v[232:235], v[46:49]
	v_mfma_f32_16x16x32_bf16 v[26:29], v[216:219], v[232:235], v[26:29]
	v_mfma_f32_16x16x32_bf16 v[106:109], v[196:199], v[236:239], v[106:109]
	v_mfma_f32_16x16x32_bf16 v[74:77], v[204:207], v[236:239], v[74:77]
	v_mfma_f32_16x16x32_bf16 v[46:49], v[212:215], v[236:239], v[46:49]
	v_mfma_f32_16x16x32_bf16 v[26:29], v[220:223], v[236:239], v[26:29]
	ds_read_b128 v[232:235], v245 offset:14336
	ds_read_b128 v[236:239], v246 offset:14336
	s_waitcnt lgkmcnt(2)
	v_mfma_f32_16x16x32_bf16 v[98:101], v[192:195], v[224:227], v[98:101]
	v_mfma_f32_16x16x32_bf16 v[66:69], v[200:203], v[224:227], v[66:69]
	v_mfma_f32_16x16x32_bf16 v[38:41], v[208:211], v[224:227], v[38:41]
	v_mfma_f32_16x16x32_bf16 v[22:25], v[216:219], v[224:227], v[22:25]
	v_mfma_f32_16x16x32_bf16 v[98:101], v[196:199], v[228:231], v[98:101]
	v_mfma_f32_16x16x32_bf16 v[66:69], v[204:207], v[228:231], v[66:69]
	v_mfma_f32_16x16x32_bf16 v[38:41], v[212:215], v[228:231], v[38:41]
	v_mfma_f32_16x16x32_bf16 v[22:25], v[220:223], v[228:231], v[22:25]
	s_waitcnt lgkmcnt(0)
	v_mfma_f32_16x16x32_bf16 v[82:85], v[192:195], v[232:235], v[82:85]
	v_mfma_f32_16x16x32_bf16 v[50:53], v[200:203], v[232:235], v[50:53]
	v_mfma_f32_16x16x32_bf16 v[30:33], v[208:211], v[232:235], v[30:33]
	v_mfma_f32_16x16x32_bf16 v[18:21], v[216:219], v[232:235], v[18:21]
	v_mfma_f32_16x16x32_bf16 v[82:85], v[196:199], v[236:239], v[82:85]
	v_mfma_f32_16x16x32_bf16 v[50:53], v[204:207], v[236:239], v[50:53]
	v_mfma_f32_16x16x32_bf16 v[30:33], v[212:215], v[236:239], v[30:33]
	v_mfma_f32_16x16x32_bf16 v[18:21], v[220:223], v[236:239], v[18:21]
	s_nop 7
	s_nop 7
	s_waitcnt vmcnt(6)
	v_add_u32_e32 v153, v157, v155
	s_waitcnt lgkmcnt(0)
	v_and_b32_e32 v1, 0xfffffc0, v1
	v_lshl_or_b32 v1, v149, 2, v1
	v_mul_lo_u32 v1, v1, s33
	v_lshl_or_b32 v1, v147, 2, v1
	s_lshl_b32 s31, s30, 1
	s_mov_b64 s[4:5], -1
	s_cmp_lg_u32 s30, 20
	s_waitcnt lgkmcnt(0)
	s_waitcnt lgkmcnt(0)
	s_waitcnt lgkmcnt(0)
	s_waitcnt lgkmcnt(0)
	s_waitcnt lgkmcnt(0)
	v_mov_b64_e32 v[162:163], v[26:27]
	v_mov_b64_e32 v[164:165], v[28:29]
	s_nop 2
	s_waitcnt lgkmcnt(0)
	v_mov_b64_e32 v[204:205], v[22:23]
	v_mov_b64_e32 v[206:207], v[24:25]
	s_nop 2
	s_waitcnt vmcnt(0)
	v_mov_b64_e32 v[200:201], v[66:67]
	v_mov_b64_e32 v[202:203], v[68:69]
	s_waitcnt vmcnt(0)
	s_nop 0
	v_mov_b32_e32 v66, v15
	v_mov_b32_e32 v67, v16
	v_mov_b32_e32 v68, v11
	s_waitcnt lgkmcnt(0)
	v_mov_b32_e32 v69, v12
	v_mov_b32_e32 v15, v17
	v_mov_b32_e32 v11, v13
	v_pk_add_f32 v[14:15], v[66:67], v[14:15]
	v_pk_add_f32 v[10:11], v[68:69], v[10:11]
	v_mov_b64_e32 v[158:159], v[30:31]
	v_mov_b64_e32 v[160:161], v[32:33]
	v_pk_add_f32 v[14:15], v[14:15], v[14:15] op_sel:[0,1] op_sel_hi:[1,0]
	v_pk_add_f32 v[16:17], v[10:11], v[10:11] op_sel:[0,1] op_sel_hi:[1,0]
	v_mov_b32_e32 v15, v2
	v_mov_b64_e32 v[192:193], v[18:19]
	v_mov_b64_e32 v[194:195], v[20:21]
	s_nop 1
	v_mov_b32_e32 v17, v3
	s_waitcnt lgkmcnt(3)
	v_mov_b64_e32 v[22:23], v[142:143]
	v_mov_b64_e32 v[24:25], v[144:145]
	v_add_f32_e64 v14, v14, v16
	v_add_f32_e64 v15, v15, v17
	s_nop 0
	s_waitcnt lgkmcnt(3)
	v_mov_b64_e32 v[30:31], v[130:131]
	v_mov_b64_e32 v[32:33], v[132:133]
	s_waitcnt lgkmcnt(0)
	v_mov_b32_e32 v26, v7
	v_pk_add_f32 v[66:67], v[6:7], v[26:27]
	v_mov_b32_e32 v6, v9
	v_pk_add_f32 v[68:69], v[8:9], v[6:7]
	v_mov_b32_e32 v67, v4
	v_mov_b32_e32 v69, v5
	v_pk_add_f32 v[16:17], v[66:67], v[68:69]
	v_pk_add_f32 v[14:15], v[14:15], v[16:17]
	v_mov_b64_e32 v[26:27], v[122:123]
	v_mov_b64_e32 v[28:29], v[124:125]
	v_add_f32_e32 v14, v14, v15
	v_fmamk_f32 v14, v14, 0x3a800000, v172
	v_mul_f32_e32 v15, 0x4b800000, v14
	v_cmp_gt_f32_e32 vcc, s58, v14
	v_mov_b64_e32 v[122:123], v[94:95]
	v_mov_b64_e32 v[124:125], v[96:97]
	s_nop 2
	v_cndmask_b32_e32 v14, v14, v15, vcc
	v_rsq_f32_e32 v14, v14
	v_mov_b64_e32 v[10:11], v[138:139]
	v_mov_b64_e32 v[12:13], v[140:141]
	v_add_u32_e32 v67, 0x1000, v1
	v_mul_f32_e32 v15, 0x45800000, v14
	v_cndmask_b32_e32 v66, v14, v15, vcc
	s_waitcnt lgkmcnt(3)
	v_mov_b64_e32 v[18:19], v[134:135]
	v_mov_b64_e32 v[20:21], v[136:137]
	s_waitcnt lgkmcnt(2)
	v_mov_b64_e32 v[6:7], v[126:127]
	v_mov_b64_e32 v[8:9], v[128:129]
	s_nop 2
	s_waitcnt lgkmcnt(0)
	s_barrier
	ds_write2_b32 v1, v22, v10 offset1:16
	ds_write2_b32 v1, v23, v11 offset0:68 offset1:84
	ds_write2_b32 v1, v24, v12 offset0:136 offset1:152
	ds_write2_b32 v1, v25, v13 offset0:204 offset1:220
	ds_write2_b32 v1, v18, v6 offset0:32 offset1:48
	ds_write2_b32 v1, v19, v7 offset0:100 offset1:116
	v_mov_b32_e32 v68, v70
	v_mov_b32_e32 v69, v71
	v_mov_b32_e32 v70, v72
	v_mov_b32_e32 v71, v73
	ds_write2_b32 v1, v20, v8 offset0:168 offset1:184
	ds_write2_b32 v1, v21, v9 offset0:236 offset1:252
	ds_write2_b32 v67, v30, v26 offset0:64 offset1:80
	ds_write2_b32 v67, v31, v27 offset0:132 offset1:148
	ds_write2_b32 v67, v32, v28 offset0:200 offset1:216
	v_mov_b64_e32 v[138:139], v[42:43]
	v_mov_b64_e32 v[140:141], v[44:45]
	v_mov_b64_e32 v[14:15], v[118:119]
	v_mov_b64_e32 v[16:17], v[120:121]
	v_mov_b64_e32 v[10:11], v[90:91]
	v_mov_b64_e32 v[12:13], v[92:93]
	v_mov_b64_e32 v[6:7], v[58:59]
	v_mov_b64_e32 v[8:9], v[60:61]
	v_mov_b64_e32 v[2:3], v[34:35]
	v_mov_b64_e32 v[4:5], v[36:37]
	v_add_u32_e32 v94, 0x1400, v1
	v_add_u32_e32 v95, 0x2000, v1
	v_add_u32_e32 v96, 0x2400, v1
	v_mov_b64_e32 v[22:23], v[46:47]
	v_mov_b64_e32 v[24:25], v[48:49]
	v_add_u32_e32 v97, 0x3000, v1
	ds_write2_b32 v94, v33, v29 offset0:12 offset1:28
	ds_write2_b32 v67, v114, v102 offset0:96 offset1:112
	ds_write2_b32 v67, v115, v103 offset0:164 offset1:180
	ds_write2_b32 v67, v116, v104 offset0:232 offset1:248
	ds_write2_b32 v94, v117, v105 offset0:44 offset1:60
	v_mov_b64_e32 v[46:47], v[98:99]
	v_mov_b64_e32 v[48:49], v[100:101]
	ds_write2_b32 v95, v110, v122 offset0:128 offset1:144
	ds_write2_b32 v95, v111, v123 offset0:196 offset1:212
	ds_write2_b32 v96, v112, v124 offset0:8 offset1:24
	ds_write2_b32 v96, v113, v125 offset0:76 offset1:92
	v_add_u32_e32 v98, 0x3400, v1
	v_mov_b64_e32 v[30:31], v[106:107]
	v_mov_b64_e32 v[32:33], v[108:109]
	ds_write2_b32 v95, v86, v68 offset0:160 offset1:176
	ds_write2_b32 v95, v87, v69 offset0:228 offset1:244
	ds_write2_b32 v96, v88, v70 offset0:40 offset1:56
	ds_write2_b32 v96, v89, v71 offset0:108 offset1:124
	ds_write2_b32 v97, v78, v62 offset0:192 offset1:208
	v_mov_b64_e32 v[26:27], v[74:75]
	v_mov_b64_e32 v[28:29], v[76:77]
	ds_write2_b32 v98, v79, v63 offset0:4 offset1:20
	ds_write2_b32 v98, v80, v64 offset0:72 offset1:88
	ds_write2_b32 v98, v81, v65 offset0:140 offset1:156
	ds_write2_b32 v97, v54, v138 offset0:224 offset1:240
	ds_write2_b32 v98, v55, v139 offset0:36 offset1:52
	ds_write2_b32 v98, v56, v140 offset0:104 offset1:120
	ds_write2_b32 v98, v57, v141 offset0:172 offset1:188
	v_mov_b64_e32 v[18:19], v[162:163]
	v_mov_b64_e32 v[20:21], v[164:165]
	v_mov_b32_e32 v100, v170
	s_waitcnt lgkmcnt(0)
	s_barrier
	v_mov_b64_e32 v[42:43], v[200:201]
	v_mov_b64_e32 v[44:45], v[202:203]
	v_add_u32_e32 v68, s71, v100
	v_ashrrev_i32_e32 v69, 31, v68
	v_mul_lo_u32 v99, v100, s33
	v_mov_b64_e32 v[34:35], v[204:205]
	v_mov_b64_e32 v[36:37], v[206:207]
	v_mov_b64_e32 v[62:63], v[82:83]
	v_mov_b64_e32 v[64:65], v[84:85]
	v_mov_b64_e32 v[58:59], v[50:51]
	v_mov_b64_e32 v[60:61], v[52:53]
	v_mov_b64_e32 v[54:55], v[158:159]
	v_mov_b64_e32 v[56:57], v[160:161]
	v_mov_b64_e32 v[50:51], v[192:193]
	v_mov_b64_e32 v[52:53], v[194:195]
	s_cbranch_scc0 .LBB0_570
	v_cmp_gt_i32_e32 vcc, s78, v68
	s_nop 1
	v_cndmask_b32_e32 v70, v179, v173, vcc
	v_and_b32_e32 v101, v70, v68
	v_mov_b64_e32 v[70:71], s[38:39]
	v_mad_i64_i32 v[70:71], s[4:5], v68, s59, v[70:71]
	s_lshl_b32 s4, s30, 7
	s_ashr_i32 s5, s4, 31
	v_lshl_add_u64 v[70:71], s[4:5], 1, v[70:71]
	s_sub_i32 s4, s31, 28
	s_cmp_gt_u32 s4, 9
	s_mov_b64 s[4:5], -1
	s_cbranch_scc0 .LBB0_566
	s_cmp_lt_i32 s30, 2
	v_mul_f32_e32 v72, 0x3e38aa3b, v66
	s_cselect_b64 vcc, -1, 0
	s_cmp_lt_i32 s30, 4
	v_cndmask_b32_e32 v72, v66, v72, vcc
	s_cselect_b64 s[6:7], -1, 0
	v_lshlrev_b32_e32 v74, 6, v101
	v_mov_b32_e32 v75, v0
	v_lshl_add_u64 v[74:75], s[16:17], 0, v[74:75]
	v_mov_b32_e32 v73, v72
	s_mov_b32 s4, 0
	s_xor_b64 s[6:7], s[6:7], -1
	v_mov_b64_e32 v[76:77], v[70:71]
	s_branch .LBB0_562
